# block attention (DSA+MoBA): software-pipelined tile loop, 16-slot K/V LDS ring, grouped mask DMA; pipelined residual epilogues
# speedup vs baseline: 1.0270x; 1.0270x over previous
.LBB0_645:
	s_add_u32 s44, s46, 0x100
	s_addc_u32 s45, s47, 0
	s_add_i32 s87, 0, 0x10000
	v_add_u32_e32 v118, s87, v191
	ds_read_b128 v[102:105], v118
	ds_read_b128 v[106:109], v118 offset:1024
	ds_read_b128 v[114:117], v118 offset:2048
	ds_read_b128 v[118:121], v118 offset:3072
	s_cmp_eq_u32 s86, 40
	s_cselect_b32 s53, s17, s45
	s_cselect_b32 s52, s16, s44
	s_cselect_b32 s49, s43, s85
	s_cselect_b32 s48, s42, s84
	v_lshl_add_u64 v[184:185], s[46:47], 0, v[178:179]
	s_add_i32 m0, s67, 0xc000
	ds_read_b128 v[122:125], v193
	ds_read_b128 v[126:129], v193 offset:1024
	ds_read_b128 v[134:137], v193 offset:2048
	ds_read_b128 v[138:141], v193 offset:3072
	ds_read_b128 v[162:165], v193 offset:4096
	ds_read_b128 v[166:169], v193 offset:5120
	ds_read_b128 v[170:173], v193 offset:6144
	ds_read_b128 v[180:183], v193 offset:7168
	global_load_lds_dwordx4 v[184:185], off
	v_lshl_add_u64 v[184:185], s[46:47], 0, v[176:177]
	s_add_i32 m0, s67, 0xe000
	s_nop 0
	global_load_lds_dwordx4 v[184:185], off
	s_waitcnt lgkmcnt(8)
	s_barrier
	s_waitcnt lgkmcnt(0)
	s_setprio 1
	s_waitcnt lgkmcnt(0)
	v_mfma_f32_16x16x32_bf16 v[158:161], v[102:105], v[122:125], v[158:161]
	v_mfma_f32_16x16x32_bf16 v[154:157], v[114:117], v[122:125], v[154:157]
	v_mfma_f32_16x16x32_bf16 v[142:145], v[102:105], v[134:137], v[142:145]
	v_mfma_f32_16x16x32_bf16 v[130:133], v[114:117], v[134:137], v[130:133]
	v_mfma_f32_16x16x32_bf16 v[94:97], v[102:105], v[162:165], v[94:97]
	v_mfma_f32_16x16x32_bf16 v[90:93], v[114:117], v[162:165], v[90:93]
	v_mfma_f32_16x16x32_bf16 v[82:85], v[102:105], v[170:173], v[82:85]
	v_mfma_f32_16x16x32_bf16 v[74:77], v[114:117], v[170:173], v[74:77]
	v_mfma_f32_16x16x32_bf16 v[158:161], v[106:109], v[126:129], v[158:161]
	v_mfma_f32_16x16x32_bf16 v[154:157], v[118:121], v[126:129], v[154:157]
	v_mfma_f32_16x16x32_bf16 v[142:145], v[106:109], v[138:141], v[142:145]
	v_mfma_f32_16x16x32_bf16 v[130:133], v[118:121], v[138:141], v[130:133]
	v_mfma_f32_16x16x32_bf16 v[94:97], v[106:109], v[166:169], v[94:97]
	v_mfma_f32_16x16x32_bf16 v[90:93], v[118:121], v[166:169], v[90:93]
	v_mfma_f32_16x16x32_bf16 v[82:85], v[106:109], v[180:183], v[82:85]
	v_mfma_f32_16x16x32_bf16 v[74:77], v[118:121], v[180:183], v[74:77]
	s_setprio 0
	s_barrier
	s_add_i32 s88, 0, 0x14000
	v_add_u32_e32 v188, s88, v191
	s_add_i32 s46, s87, s66
	ds_read_b128 v[184:187], v188
	ds_read_b128 v[196:199], v188 offset:1024
	ds_read_b128 v[204:207], v188 offset:2048
	ds_read_b128 v[208:211], v188 offset:3072
	v_lshl_add_u64 v[188:189], s[48:49], 0, v[0:1]
	s_mov_b32 m0, s46
	v_lshl_add_u64 v[200:201], s[48:49], 0, v[174:175]
	global_load_lds_dwordx4 v[188:189], off
	s_add_i32 m0, s46, 0x2000
	s_nop 0
	global_load_lds_dwordx4 v[200:201], off
	s_barrier
	s_waitcnt lgkmcnt(0)
	s_setprio 1
	s_waitcnt lgkmcnt(0)
	v_mfma_f32_16x16x32_bf16 v[150:153], v[184:187], v[122:125], v[150:153]
	v_mfma_f32_16x16x32_bf16 v[110:113], v[184:187], v[134:137], v[110:113]
	v_mfma_f32_16x16x32_bf16 v[98:101], v[204:207], v[134:137], v[98:101]
	v_mfma_f32_16x16x32_bf16 v[86:89], v[184:187], v[162:165], v[86:89]
	v_mfma_f32_16x16x32_bf16 v[78:81], v[204:207], v[162:165], v[78:81]
	v_mfma_f32_16x16x32_bf16 v[70:73], v[184:187], v[170:173], v[70:73]
	v_mfma_f32_16x16x32_bf16 v[66:69], v[204:207], v[170:173], v[66:69]
	v_mfma_f32_16x16x32_bf16 v[150:153], v[196:199], v[126:129], v[150:153]
	v_mfma_f32_16x16x32_bf16 v[122:125], v[204:207], v[122:125], v[146:149]
	v_mfma_f32_16x16x32_bf16 v[110:113], v[196:199], v[138:141], v[110:113]
	v_mfma_f32_16x16x32_bf16 v[98:101], v[208:211], v[138:141], v[98:101]
	v_mfma_f32_16x16x32_bf16 v[86:89], v[196:199], v[166:169], v[86:89]
	v_mfma_f32_16x16x32_bf16 v[78:81], v[208:211], v[166:169], v[78:81]
	v_mfma_f32_16x16x32_bf16 v[70:73], v[196:199], v[180:183], v[70:73]
	v_mfma_f32_16x16x32_bf16 v[66:69], v[208:211], v[180:183], v[66:69]
	v_mfma_f32_16x16x32_bf16 v[122:125], v[208:211], v[126:129], v[122:125]
	s_setprio 0
	s_mov_b32 m0, s67
	v_lshl_add_u64 v[202:203], s[52:53], 0, v[0:1]
	s_barrier
	ds_read_b128 v[126:129], v193 offset:16384
	ds_read_b128 v[134:137], v193 offset:17408
	ds_read_b128 v[138:141], v193 offset:18432
	ds_read_b128 v[146:149], v193 offset:19456
	ds_read_b128 v[162:165], v193 offset:20480
	ds_read_b128 v[166:169], v193 offset:21504
	ds_read_b128 v[170:173], v193 offset:22528
	ds_read_b128 v[180:183], v193 offset:23552
	global_load_lds_dwordx4 v[202:203], off
	v_lshl_add_u64 v[216:217], s[52:53], 0, v[174:175]
	s_mov_b32 m0, s68
	s_nop 0
	global_load_lds_dwordx4 v[216:217], off
	s_barrier
	s_waitcnt lgkmcnt(0)
	s_setprio 1
	s_waitcnt lgkmcnt(0)
	v_mfma_f32_16x16x32_bf16 v[62:65], v[102:105], v[126:129], v[62:65]
	v_mfma_f32_16x16x32_bf16 v[58:61], v[114:117], v[126:129], v[58:61]
	v_mfma_f32_16x16x32_bf16 v[50:53], v[102:105], v[138:141], v[50:53]
	v_mfma_f32_16x16x32_bf16 v[42:45], v[114:117], v[138:141], v[42:45]
	v_mfma_f32_16x16x32_bf16 v[30:33], v[102:105], v[162:165], v[30:33]
	v_mfma_f32_16x16x32_bf16 v[26:29], v[114:117], v[162:165], v[26:29]
	v_mfma_f32_16x16x32_bf16 v[18:21], v[102:105], v[170:173], v[18:21]
	v_mfma_f32_16x16x32_bf16 v[10:13], v[114:117], v[170:173], v[10:13]
	v_mfma_f32_16x16x32_bf16 v[62:65], v[106:109], v[134:137], v[62:65]
	v_mfma_f32_16x16x32_bf16 v[58:61], v[118:121], v[134:137], v[58:61]
	v_mfma_f32_16x16x32_bf16 v[50:53], v[106:109], v[146:149], v[50:53]
	v_mfma_f32_16x16x32_bf16 v[42:45], v[118:121], v[146:149], v[42:45]
	v_mfma_f32_16x16x32_bf16 v[30:33], v[106:109], v[166:169], v[30:33]
	v_mfma_f32_16x16x32_bf16 v[26:29], v[118:121], v[166:169], v[26:29]
	v_mfma_f32_16x16x32_bf16 v[18:21], v[106:109], v[180:183], v[18:21]
	v_mfma_f32_16x16x32_bf16 v[10:13], v[118:121], v[180:183], v[10:13]
	s_setprio 0
	s_barrier
	s_add_u32 s46, s48, 0xb0000
	s_addc_u32 s47, s49, 0
	s_add_i32 s87, s88, s66
	v_lshl_add_u64 v[102:103], s[46:47], 0, v[0:1]
	s_mov_b32 m0, s87
	s_nop 0
	global_load_lds_dwordx4 v[102:103], off
	v_lshl_add_u64 v[102:103], s[46:47], 0, v[174:175]
	s_add_i32 m0, s87, 0x2000
	s_nop 0
	global_load_lds_dwordx4 v[102:103], off
	s_waitcnt vmcnt(6)
	s_barrier
	s_setprio 1
	v_mfma_f32_16x16x32_bf16 v[54:57], v[184:187], v[126:129], v[54:57]
	v_mfma_f32_16x16x32_bf16 v[46:49], v[204:207], v[126:129], v[46:49]
	v_mfma_f32_16x16x32_bf16 v[38:41], v[184:187], v[138:141], v[38:41]
	v_mfma_f32_16x16x32_bf16 v[34:37], v[204:207], v[138:141], v[34:37]
	v_mfma_f32_16x16x32_bf16 v[22:25], v[184:187], v[162:165], v[22:25]
	v_mfma_f32_16x16x32_bf16 v[14:17], v[204:207], v[162:165], v[14:17]
	v_mfma_f32_16x16x32_bf16 v[6:9], v[184:187], v[170:173], v[6:9]
	v_mfma_f32_16x16x32_bf16 v[2:5], v[204:207], v[170:173], v[2:5]
	v_mfma_f32_16x16x32_bf16 v[54:57], v[196:199], v[134:137], v[54:57]
	v_mfma_f32_16x16x32_bf16 v[46:49], v[208:211], v[134:137], v[46:49]
	v_mfma_f32_16x16x32_bf16 v[38:41], v[196:199], v[146:149], v[38:41]
	v_mfma_f32_16x16x32_bf16 v[34:37], v[208:211], v[146:149], v[34:37]
	v_mfma_f32_16x16x32_bf16 v[22:25], v[196:199], v[166:169], v[22:25]
	v_mfma_f32_16x16x32_bf16 v[14:17], v[208:211], v[166:169], v[14:17]
	v_mfma_f32_16x16x32_bf16 v[6:9], v[196:199], v[180:183], v[6:9]
	v_mfma_f32_16x16x32_bf16 v[2:5], v[208:211], v[180:183], v[2:5]
	s_setprio 0
	s_add_i32 s87, 0, 0x18000
	v_add_u32_e32 v118, s87, v191
	s_barrier
	ds_read_b128 v[102:105], v118
	ds_read_b128 v[106:109], v118 offset:1024
	ds_read_b128 v[114:117], v118 offset:2048
	ds_read_b128 v[118:121], v118 offset:3072
	s_add_u32 s46, s52, 0xb0000
	s_addc_u32 s47, s53, 0
	s_mov_b32 m0, s69
	v_lshl_add_u64 v[146:147], s[46:47], 0, v[0:1]
	ds_read_b128 v[126:129], v193 offset:32768
	ds_read_b128 v[134:137], v193 offset:33792
	ds_read_b128 v[138:141], v193 offset:34816
	ds_read_b128 v[162:165], v193 offset:35840
	ds_read_b128 v[166:169], v193 offset:36864
	ds_read_b128 v[170:173], v193 offset:37888
	ds_read_b128 v[180:183], v193 offset:38912
	ds_read_b128 v[184:187], v193 offset:39936
	global_load_lds_dwordx4 v[146:147], off
	v_lshl_add_u64 v[146:147], s[46:47], 0, v[174:175]
	s_mov_b32 m0, s70
	s_nop 0
	global_load_lds_dwordx4 v[146:147], off
	s_waitcnt lgkmcnt(8)
	s_barrier
	s_waitcnt lgkmcnt(0)
	s_setprio 1
	s_waitcnt lgkmcnt(0)
	v_mfma_f32_16x16x32_bf16 v[146:149], v[102:105], v[126:129], v[158:161]
	v_mfma_f32_16x16x32_bf16 v[158:161], v[106:109], v[134:137], v[146:149]
	v_mfma_f32_16x16x32_bf16 v[146:149], v[114:117], v[126:129], v[154:157]
	v_mfma_f32_16x16x32_bf16 v[142:145], v[102:105], v[138:141], v[142:145]
	v_mfma_f32_16x16x32_bf16 v[130:133], v[114:117], v[138:141], v[130:133]
	v_mfma_f32_16x16x32_bf16 v[94:97], v[102:105], v[166:169], v[94:97]
	v_mfma_f32_16x16x32_bf16 v[90:93], v[114:117], v[166:169], v[90:93]
	v_mfma_f32_16x16x32_bf16 v[82:85], v[102:105], v[180:183], v[82:85]
	v_mfma_f32_16x16x32_bf16 v[74:77], v[114:117], v[180:183], v[74:77]
	v_mfma_f32_16x16x32_bf16 v[154:157], v[118:121], v[134:137], v[146:149]
	v_mfma_f32_16x16x32_bf16 v[142:145], v[106:109], v[162:165], v[142:145]
	v_mfma_f32_16x16x32_bf16 v[130:133], v[118:121], v[162:165], v[130:133]
	v_mfma_f32_16x16x32_bf16 v[94:97], v[106:109], v[170:173], v[94:97]
	v_mfma_f32_16x16x32_bf16 v[90:93], v[118:121], v[170:173], v[90:93]
	v_mfma_f32_16x16x32_bf16 v[82:85], v[106:109], v[184:187], v[82:85]
	v_mfma_f32_16x16x32_bf16 v[74:77], v[118:121], v[184:187], v[74:77]
	s_setprio 0
	s_barrier
	s_add_i32 s52, 0, 0x1c000
	v_add_u32_e32 v146, s52, v191
	s_add_i32 s46, s87, s66
	ds_read_b128 v[196:199], v146
	ds_read_b128 v[204:207], v146 offset:1024
	ds_read_b128 v[208:211], v146 offset:2048
	ds_read_b128 v[212:215], v146 offset:3072
	v_lshl_add_u64 v[146:147], v[188:189], 0, s[12:13]
	s_mov_b32 m0, s46
	s_nop 0
	global_load_lds_dwordx4 v[146:147], off
	v_lshl_add_u64 v[146:147], v[200:201], 0, s[12:13]
	s_add_i32 m0, s46, 0x2000
	s_nop 0
	global_load_lds_dwordx4 v[146:147], off
	s_barrier
	s_waitcnt lgkmcnt(0)
	s_setprio 1
	s_waitcnt lgkmcnt(0)
	v_mfma_f32_16x16x32_bf16 v[146:149], v[196:199], v[126:129], v[150:153]
	v_mfma_f32_16x16x32_bf16 v[122:125], v[208:211], v[126:129], v[122:125]
	v_mfma_f32_16x16x32_bf16 v[110:113], v[196:199], v[138:141], v[110:113]
	v_mfma_f32_16x16x32_bf16 v[98:101], v[208:211], v[138:141], v[98:101]
	v_mfma_f32_16x16x32_bf16 v[86:89], v[196:199], v[166:169], v[86:89]
	v_mfma_f32_16x16x32_bf16 v[78:81], v[208:211], v[166:169], v[78:81]
	v_mfma_f32_16x16x32_bf16 v[70:73], v[196:199], v[180:183], v[70:73]
	v_mfma_f32_16x16x32_bf16 v[66:69], v[208:211], v[180:183], v[66:69]
	v_mfma_f32_16x16x32_bf16 v[150:153], v[204:207], v[134:137], v[146:149]
	v_mfma_f32_16x16x32_bf16 v[146:149], v[212:215], v[134:137], v[122:125]
	v_mfma_f32_16x16x32_bf16 v[110:113], v[204:207], v[162:165], v[110:113]
	v_mfma_f32_16x16x32_bf16 v[98:101], v[212:215], v[162:165], v[98:101]
	v_mfma_f32_16x16x32_bf16 v[86:89], v[204:207], v[170:173], v[86:89]
	v_mfma_f32_16x16x32_bf16 v[78:81], v[212:215], v[170:173], v[78:81]
	v_mfma_f32_16x16x32_bf16 v[70:73], v[204:207], v[184:187], v[70:73]
	v_mfma_f32_16x16x32_bf16 v[66:69], v[212:215], v[184:187], v[66:69]
	s_setprio 0
	s_mov_b32 m0, s10
	v_lshl_add_u64 v[184:185], v[202:203], 0, s[12:13]
	s_barrier
	ds_read_b128 v[122:125], v193 offset:49152
	ds_read_b128 v[126:129], v193 offset:50176
	ds_read_b128 v[134:137], v193 offset:51200
	ds_read_b128 v[138:141], v193 offset:52224
	ds_read_b128 v[162:165], v193 offset:53248
	ds_read_b128 v[166:169], v193 offset:54272
	ds_read_b128 v[170:173], v193 offset:55296
	ds_read_b128 v[180:183], v193 offset:56320
	global_load_lds_dwordx4 v[184:185], off
	v_lshl_add_u64 v[184:185], v[216:217], 0, s[12:13]
	s_mov_b32 m0, s71
	s_nop 0
	global_load_lds_dwordx4 v[184:185], off
	s_barrier
	s_waitcnt lgkmcnt(0)
	s_setprio 1
	s_waitcnt lgkmcnt(0)
	v_mfma_f32_16x16x32_bf16 v[62:65], v[102:105], v[122:125], v[62:65]
	v_mfma_f32_16x16x32_bf16 v[58:61], v[114:117], v[122:125], v[58:61]
	v_mfma_f32_16x16x32_bf16 v[50:53], v[102:105], v[134:137], v[50:53]
	v_mfma_f32_16x16x32_bf16 v[42:45], v[114:117], v[134:137], v[42:45]
	v_mfma_f32_16x16x32_bf16 v[30:33], v[102:105], v[162:165], v[30:33]
	v_mfma_f32_16x16x32_bf16 v[26:29], v[114:117], v[162:165], v[26:29]
	v_mfma_f32_16x16x32_bf16 v[18:21], v[102:105], v[170:173], v[18:21]
	v_mfma_f32_16x16x32_bf16 v[10:13], v[114:117], v[170:173], v[10:13]
	v_mfma_f32_16x16x32_bf16 v[62:65], v[106:109], v[126:129], v[62:65]
	v_mfma_f32_16x16x32_bf16 v[58:61], v[118:121], v[126:129], v[58:61]
	v_mfma_f32_16x16x32_bf16 v[50:53], v[106:109], v[138:141], v[50:53]
	v_mfma_f32_16x16x32_bf16 v[42:45], v[118:121], v[138:141], v[42:45]
	v_mfma_f32_16x16x32_bf16 v[30:33], v[106:109], v[166:169], v[30:33]
	v_mfma_f32_16x16x32_bf16 v[26:29], v[118:121], v[166:169], v[26:29]
	v_mfma_f32_16x16x32_bf16 v[18:21], v[106:109], v[180:183], v[18:21]
	v_mfma_f32_16x16x32_bf16 v[10:13], v[118:121], v[180:183], v[10:13]
	s_setprio 0
	s_barrier
	s_add_u32 s46, s48, 0xb0080
	s_addc_u32 s47, s49, 0
	s_add_i32 s48, s52, s66
	v_lshl_add_u64 v[102:103], s[46:47], 0, v[0:1]
	s_mov_b32 m0, s48
	s_nop 0
	global_load_lds_dwordx4 v[102:103], off
	v_lshl_add_u64 v[102:103], s[46:47], 0, v[174:175]
	s_add_i32 m0, s48, 0x2000
	s_nop 0
	global_load_lds_dwordx4 v[102:103], off
	s_waitcnt vmcnt(6)
	s_barrier
	s_setprio 1
	v_mfma_f32_16x16x32_bf16 v[54:57], v[196:199], v[122:125], v[54:57]
	v_mfma_f32_16x16x32_bf16 v[46:49], v[208:211], v[122:125], v[46:49]
	v_mfma_f32_16x16x32_bf16 v[38:41], v[196:199], v[134:137], v[38:41]
	v_mfma_f32_16x16x32_bf16 v[34:37], v[208:211], v[134:137], v[34:37]
	v_mfma_f32_16x16x32_bf16 v[22:25], v[196:199], v[162:165], v[22:25]
	v_mfma_f32_16x16x32_bf16 v[14:17], v[208:211], v[162:165], v[14:17]
	v_mfma_f32_16x16x32_bf16 v[6:9], v[196:199], v[170:173], v[6:9]
	v_mfma_f32_16x16x32_bf16 v[2:5], v[208:211], v[170:173], v[2:5]
	v_mfma_f32_16x16x32_bf16 v[54:57], v[204:207], v[126:129], v[54:57]
	v_mfma_f32_16x16x32_bf16 v[46:49], v[212:215], v[126:129], v[46:49]
	v_mfma_f32_16x16x32_bf16 v[38:41], v[204:207], v[138:141], v[38:41]
	v_mfma_f32_16x16x32_bf16 v[34:37], v[212:215], v[138:141], v[34:37]
	v_mfma_f32_16x16x32_bf16 v[22:25], v[204:207], v[166:169], v[22:25]
	v_mfma_f32_16x16x32_bf16 v[14:17], v[212:215], v[166:169], v[14:17]
	v_mfma_f32_16x16x32_bf16 v[6:9], v[204:207], v[180:183], v[6:9]
	v_mfma_f32_16x16x32_bf16 v[2:5], v[212:215], v[180:183], v[2:5]
	s_setprio 0
	s_add_i32 s86, s86, 2
	s_add_u32 s84, s84, 0x100
	s_addc_u32 s85, s85, 0
	s_cmp_gt_u32 s86, 41
	s_mov_b64 s[46:47], s[44:45]
	s_barrier
	s_cbranch_scc0 .LBB0_645
	v_lshl_or_b32 v102, s83, 8, v192
	v_ashrrev_i32_e32 v103, 31, v102
	v_lshl_add_u32 v184, s82, 8, v190
	v_lshlrev_b64 v[180:181], 2, v[102:103]
	v_ashrrev_i32_e32 v185, 31, v184
	v_lshl_add_u64 v[102:103], s[8:9], 0, v[180:181]
	v_lshl_add_u64 v[106:107], s[14:15], 0, v[180:181]
	v_lshl_add_u64 v[162:163], v[184:185], 3, s[4:5]
	global_load_dwordx4 v[134:137], v[102:103], off
	global_load_dwordx4 v[138:141], v[106:107], off
	global_load_dwordx4 v[122:125], v[102:103], off offset:64
	global_load_dwordx4 v[126:129], v[106:107], off offset:64
	global_load_dwordx4 v[114:117], v[102:103], off offset:512
	global_load_dwordx4 v[118:121], v[106:107], off offset:512
	s_nop 0
	global_load_dwordx4 v[102:105], v[102:103], off offset:576
	s_nop 0
	global_load_dwordx4 v[106:109], v[106:107], off offset:576
	v_lshl_add_u32 v194, v184, 12, v180
	v_lshlrev_b32_e32 v238, 3, v184
	v_readlane_b32 s84, v255, 48
	s_mov_b32 s83, s80
	s_mov_b32 s82, s81
	s_mov_b64 s[48:49], s[42:43]
	s_mov_b64 s[46:47], s[16:17]
	v_readlane_b32 s85, v255, 49
	v_readlane_b32 s86, v255, 50
	s_add_u32 vcc_lo, s56, 0x0
	s_addc_u32 vcc_hi, s57, 0
	global_load_dwordx2 v[188:189], v238, s[4:5] offset:0
	global_load_dwordx4 v[162:165], v194, vcc offset:0
	global_load_dwordx4 v[166:169], v194, vcc offset:64
	global_load_dwordx4 v[170:173], v194, vcc offset:512
	global_load_dwordx4 v[180:183], v194, vcc offset:576
	s_add_u32 vcc_lo, s56, 0x10000
	s_addc_u32 vcc_hi, s57, 0
	global_load_dwordx2 v[236:237], v238, s[4:5] offset:128
	global_load_dwordx4 v[184:187], v194, vcc offset:0
	global_load_dwordx4 v[196:199], v194, vcc offset:64
	global_load_dwordx4 v[200:203], v194, vcc offset:512
	global_load_dwordx4 v[204:207], v194, vcc offset:576
	s_add_u32 vcc_lo, s56, 0x20000
	s_addc_u32 vcc_hi, s57, 0
	global_load_dwordx2 v[252:253], v238, s[4:5] offset:256
	global_load_dwordx4 v[208:211], v194, vcc offset:0
	global_load_dwordx4 v[212:215], v194, vcc offset:64
	global_load_dwordx4 v[216:219], v194, vcc offset:512
	global_load_dwordx4 v[220:223], v194, vcc offset:576
	s_add_u32 vcc_lo, s56, 0x30000
	s_addc_u32 vcc_hi, s57, 0
	global_load_dwordx2 v[248:249], v238, s[4:5] offset:384
	global_load_dwordx4 v[224:227], v194, vcc offset:0
	global_load_dwordx4 v[228:231], v194, vcc offset:64
	global_load_dwordx4 v[232:235], v194, vcc offset:512
	global_load_dwordx4 v[244:247], v194, vcc offset:576
	s_waitcnt vmcnt(10)
	s_add_u32 vcc_lo, s56, 0x0
	s_addc_u32 vcc_hi, s57, 0
	v_sub_f32_e32 v163, v163, v188
	v_sub_f32_e32 v162, v162, v188
	v_sub_f32_e32 v165, v165, v188
	v_sub_f32_e32 v164, v164, v188
	v_pk_mul_f32 v[164:165], v[188:189], v[164:165] op_sel:[1,0]
	v_pk_mul_f32 v[162:163], v[188:189], v[162:163] op_sel:[1,0]
	v_pk_fma_f32 v[164:165], v[136:137], v[164:165], v[140:141]
	v_pk_fma_f32 v[162:163], v[134:135], v[162:163], v[138:139]
	v_pk_fma_f32 v[160:161], v[164:165], s[60:61], v[160:161] op_sel_hi:[1,0,1]
	v_pk_fma_f32 v[158:159], v[162:163], s[60:61], v[158:159] op_sel_hi:[1,0,1]
	global_store_dwordx4 v194, v[158:161], vcc offset:0
	v_sub_f32_e32 v167, v167, v188
	v_sub_f32_e32 v166, v166, v188
	v_sub_f32_e32 v169, v169, v188
	v_sub_f32_e32 v168, v168, v188
	v_pk_mul_f32 v[168:169], v[188:189], v[168:169] op_sel:[1,0]
	v_pk_mul_f32 v[166:167], v[188:189], v[166:167] op_sel:[1,0]
	v_pk_fma_f32 v[168:169], v[124:125], v[168:169], v[128:129]
	v_pk_fma_f32 v[166:167], v[122:123], v[166:167], v[126:127]
	v_pk_fma_f32 v[156:157], v[168:169], s[60:61], v[156:157] op_sel_hi:[1,0,1]
	v_pk_fma_f32 v[154:155], v[166:167], s[60:61], v[154:155] op_sel_hi:[1,0,1]
	global_store_dwordx4 v194, v[154:157], vcc offset:64
	v_sub_f32_e32 v171, v171, v188
	v_sub_f32_e32 v170, v170, v188
	v_sub_f32_e32 v173, v173, v188
	v_sub_f32_e32 v172, v172, v188
	v_pk_mul_f32 v[172:173], v[188:189], v[172:173] op_sel:[1,0]
	v_pk_mul_f32 v[170:171], v[188:189], v[170:171] op_sel:[1,0]
	v_pk_fma_f32 v[172:173], v[116:117], v[172:173], v[120:121]
	v_pk_fma_f32 v[170:171], v[114:115], v[170:171], v[118:119]
	v_pk_fma_f32 v[152:153], v[172:173], s[60:61], v[152:153] op_sel_hi:[1,0,1]
	v_pk_fma_f32 v[150:151], v[170:171], s[60:61], v[150:151] op_sel_hi:[1,0,1]
	global_store_dwordx4 v194, v[150:153], vcc offset:512
	v_sub_f32_e32 v181, v181, v188
	v_sub_f32_e32 v180, v180, v188
	v_sub_f32_e32 v183, v183, v188
	v_sub_f32_e32 v182, v182, v188
	v_pk_mul_f32 v[182:183], v[188:189], v[182:183] op_sel:[1,0]
	v_pk_mul_f32 v[180:181], v[188:189], v[180:181] op_sel:[1,0]
	v_pk_fma_f32 v[182:183], v[104:105], v[182:183], v[108:109]
	v_pk_fma_f32 v[180:181], v[102:103], v[180:181], v[106:107]
	v_pk_fma_f32 v[148:149], v[182:183], s[60:61], v[148:149] op_sel_hi:[1,0,1]
	v_pk_fma_f32 v[146:147], v[180:181], s[60:61], v[146:147] op_sel_hi:[1,0,1]
	global_store_dwordx4 v194, v[146:149], vcc offset:576
	s_add_u32 vcc_lo, s56, 0x10000
	s_addc_u32 vcc_hi, s57, 0
	v_sub_f32_e32 v185, v185, v236
	v_sub_f32_e32 v184, v184, v236
	v_sub_f32_e32 v187, v187, v236
	v_sub_f32_e32 v186, v186, v236
	v_pk_mul_f32 v[186:187], v[236:237], v[186:187] op_sel:[1,0]
	v_pk_mul_f32 v[184:185], v[236:237], v[184:185] op_sel:[1,0]
	v_pk_fma_f32 v[186:187], v[136:137], v[186:187], v[140:141]
	v_pk_fma_f32 v[184:185], v[134:135], v[184:185], v[138:139]
	v_pk_fma_f32 v[144:145], v[186:187], s[60:61], v[144:145] op_sel_hi:[1,0,1]
	v_pk_fma_f32 v[142:143], v[184:185], s[60:61], v[142:143] op_sel_hi:[1,0,1]
	global_store_dwordx4 v194, v[142:145], vcc offset:0
	v_sub_f32_e32 v197, v197, v236
	v_sub_f32_e32 v196, v196, v236
	v_sub_f32_e32 v199, v199, v236
	v_sub_f32_e32 v198, v198, v236
	v_pk_mul_f32 v[198:199], v[236:237], v[198:199] op_sel:[1,0]
	v_pk_mul_f32 v[196:197], v[236:237], v[196:197] op_sel:[1,0]
	v_pk_fma_f32 v[198:199], v[124:125], v[198:199], v[128:129]
	v_pk_fma_f32 v[196:197], v[122:123], v[196:197], v[126:127]
	v_pk_fma_f32 v[132:133], v[198:199], s[60:61], v[132:133] op_sel_hi:[1,0,1]
	v_pk_fma_f32 v[130:131], v[196:197], s[60:61], v[130:131] op_sel_hi:[1,0,1]
	global_store_dwordx4 v194, v[130:133], vcc offset:64
	v_sub_f32_e32 v201, v201, v236
	v_sub_f32_e32 v200, v200, v236
	v_sub_f32_e32 v203, v203, v236
	v_sub_f32_e32 v202, v202, v236
	v_pk_mul_f32 v[202:203], v[236:237], v[202:203] op_sel:[1,0]
	v_pk_mul_f32 v[200:201], v[236:237], v[200:201] op_sel:[1,0]
	v_pk_fma_f32 v[202:203], v[116:117], v[202:203], v[120:121]
	v_pk_fma_f32 v[200:201], v[114:115], v[200:201], v[118:119]
	v_pk_fma_f32 v[112:113], v[202:203], s[60:61], v[112:113] op_sel_hi:[1,0,1]
	v_pk_fma_f32 v[110:111], v[200:201], s[60:61], v[110:111] op_sel_hi:[1,0,1]
	global_store_dwordx4 v194, v[110:113], vcc offset:512
	v_sub_f32_e32 v205, v205, v236
	v_sub_f32_e32 v204, v204, v236
	v_sub_f32_e32 v207, v207, v236
	v_sub_f32_e32 v206, v206, v236
	v_pk_mul_f32 v[206:207], v[236:237], v[206:207] op_sel:[1,0]
	v_pk_mul_f32 v[204:205], v[236:237], v[204:205] op_sel:[1,0]
	v_pk_fma_f32 v[206:207], v[104:105], v[206:207], v[108:109]
	v_pk_fma_f32 v[204:205], v[102:103], v[204:205], v[106:107]
	v_pk_fma_f32 v[100:101], v[206:207], s[60:61], v[100:101] op_sel_hi:[1,0,1]
	v_pk_fma_f32 v[98:99], v[204:205], s[60:61], v[98:99] op_sel_hi:[1,0,1]
	global_store_dwordx4 v194, v[98:101], vcc offset:576
	s_add_u32 vcc_lo, s56, 0x80000
	s_addc_u32 vcc_hi, s57, 0
	global_load_dwordx2 v[188:189], v238, s[4:5] offset:1024
	global_load_dwordx4 v[158:161], v194, vcc offset:0
	global_load_dwordx4 v[154:157], v194, vcc offset:64
	global_load_dwordx4 v[150:153], v194, vcc offset:512
	global_load_dwordx4 v[146:149], v194, vcc offset:576
	s_add_u32 vcc_lo, s56, 0x90000
	s_addc_u32 vcc_hi, s57, 0
	global_load_dwordx2 v[236:237], v238, s[4:5] offset:1152
	global_load_dwordx4 v[142:145], v194, vcc offset:0
	global_load_dwordx4 v[130:133], v194, vcc offset:64
	global_load_dwordx4 v[110:113], v194, vcc offset:512
	global_load_dwordx4 v[98:101], v194, vcc offset:576
	s_waitcnt vmcnt(18)
	s_add_u32 vcc_lo, s56, 0x20000
	s_addc_u32 vcc_hi, s57, 0
	v_sub_f32_e32 v209, v209, v252
	v_sub_f32_e32 v208, v208, v252
	v_sub_f32_e32 v211, v211, v252
	v_sub_f32_e32 v210, v210, v252
	v_pk_mul_f32 v[210:211], v[252:253], v[210:211] op_sel:[1,0]
	v_pk_mul_f32 v[208:209], v[252:253], v[208:209] op_sel:[1,0]
	v_pk_fma_f32 v[210:211], v[136:137], v[210:211], v[140:141]
	v_pk_fma_f32 v[208:209], v[134:135], v[208:209], v[138:139]
	v_pk_fma_f32 v[96:97], v[210:211], s[60:61], v[96:97] op_sel_hi:[1,0,1]
	v_pk_fma_f32 v[94:95], v[208:209], s[60:61], v[94:95] op_sel_hi:[1,0,1]
	global_store_dwordx4 v194, v[94:97], vcc offset:0
	v_sub_f32_e32 v213, v213, v252
	v_sub_f32_e32 v212, v212, v252
	v_sub_f32_e32 v215, v215, v252
	v_sub_f32_e32 v214, v214, v252
	v_pk_mul_f32 v[214:215], v[252:253], v[214:215] op_sel:[1,0]
	v_pk_mul_f32 v[212:213], v[252:253], v[212:213] op_sel:[1,0]
	v_pk_fma_f32 v[214:215], v[124:125], v[214:215], v[128:129]
	v_pk_fma_f32 v[212:213], v[122:123], v[212:213], v[126:127]
	v_pk_fma_f32 v[92:93], v[214:215], s[60:61], v[92:93] op_sel_hi:[1,0,1]
	v_pk_fma_f32 v[90:91], v[212:213], s[60:61], v[90:91] op_sel_hi:[1,0,1]
	global_store_dwordx4 v194, v[90:93], vcc offset:64
	v_sub_f32_e32 v217, v217, v252
	v_sub_f32_e32 v216, v216, v252
	v_sub_f32_e32 v219, v219, v252
	v_sub_f32_e32 v218, v218, v252
	v_pk_mul_f32 v[218:219], v[252:253], v[218:219] op_sel:[1,0]
	v_pk_mul_f32 v[216:217], v[252:253], v[216:217] op_sel:[1,0]
	v_pk_fma_f32 v[218:219], v[116:117], v[218:219], v[120:121]
	v_pk_fma_f32 v[216:217], v[114:115], v[216:217], v[118:119]
	v_pk_fma_f32 v[88:89], v[218:219], s[60:61], v[88:89] op_sel_hi:[1,0,1]
	v_pk_fma_f32 v[86:87], v[216:217], s[60:61], v[86:87] op_sel_hi:[1,0,1]
	global_store_dwordx4 v194, v[86:89], vcc offset:512
	v_sub_f32_e32 v221, v221, v252
	v_sub_f32_e32 v220, v220, v252
	v_sub_f32_e32 v223, v223, v252
	v_sub_f32_e32 v222, v222, v252
	v_pk_mul_f32 v[222:223], v[252:253], v[222:223] op_sel:[1,0]
	v_pk_mul_f32 v[220:221], v[252:253], v[220:221] op_sel:[1,0]
	v_pk_fma_f32 v[222:223], v[104:105], v[222:223], v[108:109]
	v_pk_fma_f32 v[220:221], v[102:103], v[220:221], v[106:107]
	v_pk_fma_f32 v[80:81], v[222:223], s[60:61], v[80:81] op_sel_hi:[1,0,1]
	v_pk_fma_f32 v[78:79], v[220:221], s[60:61], v[78:79] op_sel_hi:[1,0,1]
	global_store_dwordx4 v194, v[78:81], vcc offset:576
	s_add_u32 vcc_lo, s56, 0x30000
	s_addc_u32 vcc_hi, s57, 0
	v_sub_f32_e32 v225, v225, v248
	v_sub_f32_e32 v224, v224, v248
	v_sub_f32_e32 v227, v227, v248
	v_sub_f32_e32 v226, v226, v248
	v_pk_mul_f32 v[226:227], v[248:249], v[226:227] op_sel:[1,0]
	v_pk_mul_f32 v[224:225], v[248:249], v[224:225] op_sel:[1,0]
	v_pk_fma_f32 v[226:227], v[136:137], v[226:227], v[140:141]
	v_pk_fma_f32 v[224:225], v[134:135], v[224:225], v[138:139]
	v_pk_fma_f32 v[84:85], v[226:227], s[60:61], v[84:85] op_sel_hi:[1,0,1]
	v_pk_fma_f32 v[82:83], v[224:225], s[60:61], v[82:83] op_sel_hi:[1,0,1]
	global_store_dwordx4 v194, v[82:85], vcc offset:0
	v_sub_f32_e32 v229, v229, v248
	v_sub_f32_e32 v228, v228, v248
	v_sub_f32_e32 v231, v231, v248
	v_sub_f32_e32 v230, v230, v248
	v_pk_mul_f32 v[230:231], v[248:249], v[230:231] op_sel:[1,0]
	v_pk_mul_f32 v[228:229], v[248:249], v[228:229] op_sel:[1,0]
	v_pk_fma_f32 v[230:231], v[124:125], v[230:231], v[128:129]
	v_pk_fma_f32 v[228:229], v[122:123], v[228:229], v[126:127]
	v_pk_fma_f32 v[76:77], v[230:231], s[60:61], v[76:77] op_sel_hi:[1,0,1]
	v_pk_fma_f32 v[74:75], v[228:229], s[60:61], v[74:75] op_sel_hi:[1,0,1]
	global_store_dwordx4 v194, v[74:77], vcc offset:64
	v_sub_f32_e32 v233, v233, v248
	v_sub_f32_e32 v232, v232, v248
	v_sub_f32_e32 v235, v235, v248
	v_sub_f32_e32 v234, v234, v248
	v_pk_mul_f32 v[234:235], v[248:249], v[234:235] op_sel:[1,0]
	v_pk_mul_f32 v[232:233], v[248:249], v[232:233] op_sel:[1,0]
	v_pk_fma_f32 v[234:235], v[116:117], v[234:235], v[120:121]
	v_pk_fma_f32 v[232:233], v[114:115], v[232:233], v[118:119]
	v_pk_fma_f32 v[72:73], v[234:235], s[60:61], v[72:73] op_sel_hi:[1,0,1]
	v_pk_fma_f32 v[70:71], v[232:233], s[60:61], v[70:71] op_sel_hi:[1,0,1]
	global_store_dwordx4 v194, v[70:73], vcc offset:512
	v_sub_f32_e32 v245, v245, v248
	v_sub_f32_e32 v244, v244, v248
	v_sub_f32_e32 v247, v247, v248
	v_sub_f32_e32 v246, v246, v248
	v_pk_mul_f32 v[246:247], v[248:249], v[246:247] op_sel:[1,0]
	v_pk_mul_f32 v[244:245], v[248:249], v[244:245] op_sel:[1,0]
	v_pk_fma_f32 v[246:247], v[104:105], v[246:247], v[108:109]
	v_pk_fma_f32 v[244:245], v[102:103], v[244:245], v[106:107]
	v_pk_fma_f32 v[68:69], v[246:247], s[60:61], v[68:69] op_sel_hi:[1,0,1]
	v_pk_fma_f32 v[66:67], v[244:245], s[60:61], v[66:67] op_sel_hi:[1,0,1]
	global_store_dwordx4 v194, v[66:69], vcc offset:576
	s_add_u32 vcc_lo, s56, 0xa0000
	s_addc_u32 vcc_hi, s57, 0
	global_load_dwordx2 v[252:253], v238, s[4:5] offset:1280
	global_load_dwordx4 v[94:97], v194, vcc offset:0
	global_load_dwordx4 v[90:93], v194, vcc offset:64
	global_load_dwordx4 v[86:89], v194, vcc offset:512
	global_load_dwordx4 v[78:81], v194, vcc offset:576
	s_add_u32 vcc_lo, s56, 0xb0000
	s_addc_u32 vcc_hi, s57, 0
	global_load_dwordx2 v[248:249], v238, s[4:5] offset:1408
	global_load_dwordx4 v[82:85], v194, vcc offset:0
	global_load_dwordx4 v[74:77], v194, vcc offset:64
	global_load_dwordx4 v[70:73], v194, vcc offset:512
	global_load_dwordx4 v[66:69], v194, vcc offset:576
	s_waitcnt vmcnt(18)
	s_add_u32 vcc_lo, s56, 0x80000
	s_addc_u32 vcc_hi, s57, 0
	v_sub_f32_e32 v159, v159, v188
	v_sub_f32_e32 v158, v158, v188
	v_sub_f32_e32 v161, v161, v188
	v_sub_f32_e32 v160, v160, v188
	v_pk_mul_f32 v[160:161], v[188:189], v[160:161] op_sel:[1,0]
	v_pk_mul_f32 v[158:159], v[188:189], v[158:159] op_sel:[1,0]
	v_pk_fma_f32 v[160:161], v[136:137], v[160:161], v[140:141]
	v_pk_fma_f32 v[158:159], v[134:135], v[158:159], v[138:139]
	v_pk_fma_f32 v[64:65], v[160:161], s[60:61], v[64:65] op_sel_hi:[1,0,1]
	v_pk_fma_f32 v[62:63], v[158:159], s[60:61], v[62:63] op_sel_hi:[1,0,1]
	global_store_dwordx4 v194, v[62:65], vcc offset:0
	v_sub_f32_e32 v155, v155, v188
	v_sub_f32_e32 v154, v154, v188
	v_sub_f32_e32 v157, v157, v188
	v_sub_f32_e32 v156, v156, v188
	v_pk_mul_f32 v[156:157], v[188:189], v[156:157] op_sel:[1,0]
	v_pk_mul_f32 v[154:155], v[188:189], v[154:155] op_sel:[1,0]
	v_pk_fma_f32 v[156:157], v[124:125], v[156:157], v[128:129]
	v_pk_fma_f32 v[154:155], v[122:123], v[154:155], v[126:127]
	v_pk_fma_f32 v[60:61], v[156:157], s[60:61], v[60:61] op_sel_hi:[1,0,1]
	v_pk_fma_f32 v[58:59], v[154:155], s[60:61], v[58:59] op_sel_hi:[1,0,1]
	global_store_dwordx4 v194, v[58:61], vcc offset:64
	v_sub_f32_e32 v151, v151, v188
	v_sub_f32_e32 v150, v150, v188
	v_sub_f32_e32 v153, v153, v188
	v_sub_f32_e32 v152, v152, v188
	v_pk_mul_f32 v[152:153], v[188:189], v[152:153] op_sel:[1,0]
	v_pk_mul_f32 v[150:151], v[188:189], v[150:151] op_sel:[1,0]
	v_pk_fma_f32 v[152:153], v[116:117], v[152:153], v[120:121]
	v_pk_fma_f32 v[150:151], v[114:115], v[150:151], v[118:119]
	v_pk_fma_f32 v[56:57], v[152:153], s[60:61], v[56:57] op_sel_hi:[1,0,1]
	v_pk_fma_f32 v[54:55], v[150:151], s[60:61], v[54:55] op_sel_hi:[1,0,1]
	global_store_dwordx4 v194, v[54:57], vcc offset:512
	v_sub_f32_e32 v147, v147, v188
	v_sub_f32_e32 v146, v146, v188
	v_sub_f32_e32 v149, v149, v188
	v_sub_f32_e32 v148, v148, v188
	v_pk_mul_f32 v[148:149], v[188:189], v[148:149] op_sel:[1,0]
	v_pk_mul_f32 v[146:147], v[188:189], v[146:147] op_sel:[1,0]
	v_pk_fma_f32 v[148:149], v[104:105], v[148:149], v[108:109]
	v_pk_fma_f32 v[146:147], v[102:103], v[146:147], v[106:107]
	v_pk_fma_f32 v[48:49], v[148:149], s[60:61], v[48:49] op_sel_hi:[1,0,1]
	v_pk_fma_f32 v[46:47], v[146:147], s[60:61], v[46:47] op_sel_hi:[1,0,1]
	global_store_dwordx4 v194, v[46:49], vcc offset:576
	s_add_u32 vcc_lo, s56, 0x90000
	s_addc_u32 vcc_hi, s57, 0
	v_sub_f32_e32 v143, v143, v236
	v_sub_f32_e32 v142, v142, v236
	v_sub_f32_e32 v145, v145, v236
	v_sub_f32_e32 v144, v144, v236
	v_pk_mul_f32 v[144:145], v[236:237], v[144:145] op_sel:[1,0]
	v_pk_mul_f32 v[142:143], v[236:237], v[142:143] op_sel:[1,0]
	v_pk_fma_f32 v[144:145], v[136:137], v[144:145], v[140:141]
	v_pk_fma_f32 v[142:143], v[134:135], v[142:143], v[138:139]
	v_pk_fma_f32 v[52:53], v[144:145], s[60:61], v[52:53] op_sel_hi:[1,0,1]
	v_pk_fma_f32 v[50:51], v[142:143], s[60:61], v[50:51] op_sel_hi:[1,0,1]
	global_store_dwordx4 v194, v[50:53], vcc offset:0
	v_sub_f32_e32 v131, v131, v236
	v_sub_f32_e32 v130, v130, v236
	v_sub_f32_e32 v133, v133, v236
	v_sub_f32_e32 v132, v132, v236
	v_pk_mul_f32 v[132:133], v[236:237], v[132:133] op_sel:[1,0]
	v_pk_mul_f32 v[130:131], v[236:237], v[130:131] op_sel:[1,0]
	v_pk_fma_f32 v[132:133], v[124:125], v[132:133], v[128:129]
	v_pk_fma_f32 v[130:131], v[122:123], v[130:131], v[126:127]
	v_pk_fma_f32 v[44:45], v[132:133], s[60:61], v[44:45] op_sel_hi:[1,0,1]
	v_pk_fma_f32 v[42:43], v[130:131], s[60:61], v[42:43] op_sel_hi:[1,0,1]
	global_store_dwordx4 v194, v[42:45], vcc offset:64
	v_sub_f32_e32 v111, v111, v236
	v_sub_f32_e32 v110, v110, v236
	v_sub_f32_e32 v113, v113, v236
	v_sub_f32_e32 v112, v112, v236
	v_pk_mul_f32 v[112:113], v[236:237], v[112:113] op_sel:[1,0]
	v_pk_mul_f32 v[110:111], v[236:237], v[110:111] op_sel:[1,0]
	v_pk_fma_f32 v[112:113], v[116:117], v[112:113], v[120:121]
	v_pk_fma_f32 v[110:111], v[114:115], v[110:111], v[118:119]
	v_pk_fma_f32 v[40:41], v[112:113], s[60:61], v[40:41] op_sel_hi:[1,0,1]
	v_pk_fma_f32 v[38:39], v[110:111], s[60:61], v[38:39] op_sel_hi:[1,0,1]
	global_store_dwordx4 v194, v[38:41], vcc offset:512
	v_sub_f32_e32 v99, v99, v236
	v_sub_f32_e32 v98, v98, v236
	v_sub_f32_e32 v101, v101, v236
	v_sub_f32_e32 v100, v100, v236
	v_pk_mul_f32 v[100:101], v[236:237], v[100:101] op_sel:[1,0]
	v_pk_mul_f32 v[98:99], v[236:237], v[98:99] op_sel:[1,0]
	v_pk_fma_f32 v[100:101], v[104:105], v[100:101], v[108:109]
	v_pk_fma_f32 v[98:99], v[102:103], v[98:99], v[106:107]
	v_pk_fma_f32 v[36:37], v[100:101], s[60:61], v[36:37] op_sel_hi:[1,0,1]
	v_pk_fma_f32 v[34:35], v[98:99], s[60:61], v[34:35] op_sel_hi:[1,0,1]
	global_store_dwordx4 v194, v[34:37], vcc offset:576
	s_waitcnt vmcnt(8)
	s_add_u32 vcc_lo, s56, 0xa0000
	s_addc_u32 vcc_hi, s57, 0
	v_sub_f32_e32 v95, v95, v252
	v_sub_f32_e32 v94, v94, v252
	v_sub_f32_e32 v97, v97, v252
	v_sub_f32_e32 v96, v96, v252
	v_pk_mul_f32 v[96:97], v[252:253], v[96:97] op_sel:[1,0]
	v_pk_mul_f32 v[94:95], v[252:253], v[94:95] op_sel:[1,0]
	v_pk_fma_f32 v[96:97], v[136:137], v[96:97], v[140:141]
	v_pk_fma_f32 v[94:95], v[134:135], v[94:95], v[138:139]
	v_pk_fma_f32 v[32:33], v[96:97], s[60:61], v[32:33] op_sel_hi:[1,0,1]
	v_pk_fma_f32 v[30:31], v[94:95], s[60:61], v[30:31] op_sel_hi:[1,0,1]
	global_store_dwordx4 v194, v[30:33], vcc offset:0
	v_sub_f32_e32 v91, v91, v252
	v_sub_f32_e32 v90, v90, v252
	v_sub_f32_e32 v93, v93, v252
	v_sub_f32_e32 v92, v92, v252
	v_pk_mul_f32 v[92:93], v[252:253], v[92:93] op_sel:[1,0]
	v_pk_mul_f32 v[90:91], v[252:253], v[90:91] op_sel:[1,0]
	v_pk_fma_f32 v[92:93], v[124:125], v[92:93], v[128:129]
	v_pk_fma_f32 v[90:91], v[122:123], v[90:91], v[126:127]
	v_pk_fma_f32 v[28:29], v[92:93], s[60:61], v[28:29] op_sel_hi:[1,0,1]
	v_pk_fma_f32 v[26:27], v[90:91], s[60:61], v[26:27] op_sel_hi:[1,0,1]
	global_store_dwordx4 v194, v[26:29], vcc offset:64
	v_sub_f32_e32 v87, v87, v252
	v_sub_f32_e32 v86, v86, v252
	v_sub_f32_e32 v89, v89, v252
	v_sub_f32_e32 v88, v88, v252
	v_pk_mul_f32 v[88:89], v[252:253], v[88:89] op_sel:[1,0]
	v_pk_mul_f32 v[86:87], v[252:253], v[86:87] op_sel:[1,0]
	v_pk_fma_f32 v[88:89], v[116:117], v[88:89], v[120:121]
	v_pk_fma_f32 v[86:87], v[114:115], v[86:87], v[118:119]
	v_pk_fma_f32 v[24:25], v[88:89], s[60:61], v[24:25] op_sel_hi:[1,0,1]
	v_pk_fma_f32 v[22:23], v[86:87], s[60:61], v[22:23] op_sel_hi:[1,0,1]
	global_store_dwordx4 v194, v[22:25], vcc offset:512
	v_sub_f32_e32 v79, v79, v252
	v_sub_f32_e32 v78, v78, v252
	v_sub_f32_e32 v81, v81, v252
	v_sub_f32_e32 v80, v80, v252
	v_pk_mul_f32 v[80:81], v[252:253], v[80:81] op_sel:[1,0]
	v_pk_mul_f32 v[78:79], v[252:253], v[78:79] op_sel:[1,0]
	v_pk_fma_f32 v[80:81], v[104:105], v[80:81], v[108:109]
	v_pk_fma_f32 v[78:79], v[102:103], v[78:79], v[106:107]
	v_pk_fma_f32 v[16:17], v[80:81], s[60:61], v[16:17] op_sel_hi:[1,0,1]
	v_pk_fma_f32 v[14:15], v[78:79], s[60:61], v[14:15] op_sel_hi:[1,0,1]
	global_store_dwordx4 v194, v[14:17], vcc offset:576
	s_add_u32 vcc_lo, s56, 0xb0000
	s_addc_u32 vcc_hi, s57, 0
	v_sub_f32_e32 v83, v83, v248
	v_sub_f32_e32 v82, v82, v248
	v_sub_f32_e32 v85, v85, v248
	v_sub_f32_e32 v84, v84, v248
	v_pk_mul_f32 v[84:85], v[248:249], v[84:85] op_sel:[1,0]
	v_pk_mul_f32 v[82:83], v[248:249], v[82:83] op_sel:[1,0]
	v_pk_fma_f32 v[84:85], v[136:137], v[84:85], v[140:141]
	v_pk_fma_f32 v[82:83], v[134:135], v[82:83], v[138:139]
	v_pk_fma_f32 v[20:21], v[84:85], s[60:61], v[20:21] op_sel_hi:[1,0,1]
	v_pk_fma_f32 v[18:19], v[82:83], s[60:61], v[18:19] op_sel_hi:[1,0,1]
	global_store_dwordx4 v194, v[18:21], vcc offset:0
	v_sub_f32_e32 v75, v75, v248
	v_sub_f32_e32 v74, v74, v248
	v_sub_f32_e32 v77, v77, v248
	v_sub_f32_e32 v76, v76, v248
	v_pk_mul_f32 v[76:77], v[248:249], v[76:77] op_sel:[1,0]
	v_pk_mul_f32 v[74:75], v[248:249], v[74:75] op_sel:[1,0]
	v_pk_fma_f32 v[76:77], v[124:125], v[76:77], v[128:129]
	v_pk_fma_f32 v[74:75], v[122:123], v[74:75], v[126:127]
	v_pk_fma_f32 v[12:13], v[76:77], s[60:61], v[12:13] op_sel_hi:[1,0,1]
	v_pk_fma_f32 v[10:11], v[74:75], s[60:61], v[10:11] op_sel_hi:[1,0,1]
	global_store_dwordx4 v194, v[10:13], vcc offset:64
	v_sub_f32_e32 v71, v71, v248
	v_sub_f32_e32 v70, v70, v248
	v_sub_f32_e32 v73, v73, v248
	v_sub_f32_e32 v72, v72, v248
	v_pk_mul_f32 v[72:73], v[248:249], v[72:73] op_sel:[1,0]
	v_pk_mul_f32 v[70:71], v[248:249], v[70:71] op_sel:[1,0]
	v_pk_fma_f32 v[72:73], v[116:117], v[72:73], v[120:121]
	v_pk_fma_f32 v[70:71], v[114:115], v[70:71], v[118:119]
	v_pk_fma_f32 v[8:9], v[72:73], s[60:61], v[8:9] op_sel_hi:[1,0,1]
	v_pk_fma_f32 v[6:7], v[70:71], s[60:61], v[6:7] op_sel_hi:[1,0,1]
	global_store_dwordx4 v194, v[6:9], vcc offset:512
	v_sub_f32_e32 v67, v67, v248
	v_sub_f32_e32 v66, v66, v248
	v_sub_f32_e32 v69, v69, v248
	v_sub_f32_e32 v68, v68, v248
	v_pk_mul_f32 v[68:69], v[248:249], v[68:69] op_sel:[1,0]
	v_pk_mul_f32 v[66:67], v[248:249], v[66:67] op_sel:[1,0]
	v_pk_fma_f32 v[68:69], v[104:105], v[68:69], v[108:109]
	v_pk_fma_f32 v[66:67], v[102:103], v[66:67], v[106:107]
	v_pk_fma_f32 v[4:5], v[68:69], s[60:61], v[4:5] op_sel_hi:[1,0,1]
	v_pk_fma_f32 v[2:3], v[66:67], s[60:61], v[2:3] op_sel_hi:[1,0,1]
	global_store_dwordx4 v194, v[2:5], vcc offset:576
	s_and_b64 vcc, exec, s[40:41]
	s_cbranch_vccz .LBB0_634
	s_waitcnt vmcnt(0)
	s_cmpk_gt_u32 s29, 0xff
	s_cbranch_scc1 .LBB0_649
	s_barrier

.LBB0_687:
	s_add_u32 s14, s58, 0x1f390000
	s_addc_u32 s15, s59, 0
	s_lshl_b32 s16, s28, 10
	s_addk_i32 s16, 0xfc00
	s_ashr_i32 s17, s16, 31
	s_lshl_b64 s[64:65], s[16:17], 2
	s_waitcnt lgkmcnt(0)
	s_add_u32 s16, s44, s64
	v_bfe_u32 v18, v242, 4, 2
	s_addc_u32 s17, s45, s65
	v_and_b32_e32 v19, 15, v242
	v_lshlrev_b32_e32 v20, 4, v18
	s_add_u32 s46, s46, s64
	v_lshl_or_b32 v196, s42, 6, v19
	v_lshl_or_b32 v19, v19, 6, v20
	v_lshlrev_b32_e32 v20, 2, v242
	s_addc_u32 s47, s47, s65
	s_lshl_b32 s42, s42, 13
	v_and_b32_e32 v20, 32, v20
	v_bitop3_b32 v21, v19, s42, v20 bitop3:0xde
	s_lshl_b32 s42, s43, 5
	s_and_b32 s44, s42, 0x60
	s_add_i32 m0, s49, 0x18000
	v_lshl_add_u64 v[8:9], v[8:9], 0, s[12:13]
	s_lshl_b32 s42, s44, 7
	s_waitcnt vmcnt(4)
	s_barrier
	global_load_lds_dwordx4 v[8:9], off
	v_lshl_add_u64 v[6:7], v[6:7], 0, s[12:13]
	s_add_i32 m0, s49, 0x1a000
	s_add_i32 s83, s49, 0x8000
	s_add_i32 s84, s49, 0xa000
	v_bitop3_b32 v197, s42, v19, v20 bitop3:0xf6
	global_load_lds_dwordx4 v[6:7], off
	v_lshl_add_u64 v[4:5], v[4:5], 0, s[12:13]
	s_mov_b32 m0, s83
	s_add_u32 s42, s96, 0x40080
	global_load_lds_dwordx4 v[4:5], off
	v_lshl_add_u64 v[2:3], v[2:3], 0, s[12:13]
	s_mov_b32 m0, s84
	s_addc_u32 s43, s97, 0
	global_load_lds_dwordx4 v[2:3], off
	s_add_i32 m0, s49, 0x1c000
	v_lshl_add_u64 v[2:3], s[42:43], 0, v[0:1]
	global_load_lds_dwordx4 v[2:3], off
	v_lshl_add_u64 v[2:3], s[42:43], 0, v[204:205]
	s_add_i32 m0, s49, 0x1e000
	s_mov_b64 s[42:43], 0x40080
	global_load_lds_dwordx4 v[2:3], off
	v_lshlrev_b32_e32 v2, 13, v14
	v_and_b32_e32 v2, 0x7fffc000, v2
	v_lshl_add_u32 v2, v15, 10, v2
	v_or_b32_e32 v2, v2, v16
	v_add_lshl_u32 v2, v2, v17, 1
	v_mov_b32_e32 v3, v1
	v_lshl_add_u64 v[206:207], v[2:3], 0, s[42:43]
	v_lshlrev_b32_e32 v2, 13, v10
	v_and_b32_e32 v2, 0x7fffc000, v2
	v_lshl_add_u32 v2, v11, 10, v2
	s_waitcnt vmcnt(6)
	v_or_b32_e32 v2, v2, v12
	v_add_lshl_u32 v2, v2, v13, 1
	s_ashr_i32 s85, s23, 31
	s_ashr_i32 s86, s10, 31
	v_lshl_or_b32 v198, v18, 2, s44
	v_lshl_add_u64 v[208:209], v[2:3], 0, s[42:43]
	s_mov_b32 s87, 0
	v_add_u32_e32 v199, 0, v21
	s_barrier
	s_branch .LBB0_689
.LBB0_689:
	s_add_i32 s87, s87, 1
	s_mul_i32 s42, s87, s85
	s_mul_hi_u32 s43, s87, s23
	s_add_i32 s43, s43, s42
	s_mul_i32 s42, s87, s23
	s_add_u32 s44, s42, s10
	s_addc_u32 s45, s43, s86
	v_mov_b64_e32 v[2:3], 0x1ff
	v_cmp_gt_i64_e64 s[42:43], s[44:45], v[2:3]
	s_and_b64 vcc, exec, s[42:43]
	s_cbranch_vccnz .LBB0_695
	s_ashr_i32 s64, s44, 31
	s_lshr_b32 s64, s64, 29
	s_add_i32 s66, s44, s64
	s_and_b32 s64, s66, -8
	s_sub_i32 s67, s44, s64
	s_cmp_gt_i32 s67, -1
	s_mov_b64 s[64:65], -1
	s_cbranch_scc0 .LBB0_692
	s_lshl_b32 s68, s67, 6
	s_mov_b64 s[64:65], 0

.LBB0_699:
	v_lshl_add_u32 v194, s54, 8, v196
	v_lshlrev_b32_e32 v238, 3, v194
	v_lshl_add_u32 v194, v194, 12, v210
	s_movk_i32 s89, 0xe3f8
	v_readlane_b32 s91, v255, 42
	s_movk_i32 s94, 0xd3f8
	s_movk_i32 s90, 0xf3f8
	s_mov_b32 s48, s66
	s_mov_b32 s54, s64
	s_mov_b64 s[96:97], s[70:71]
	s_mov_b64 s[62:63], s[68:69]
	s_and_b64 vcc, exec, s[40:41]
	s_cbranch_vccnz .Lepiout_plain
	s_add_u32 vcc_lo, s8, 0x0
	s_addc_u32 vcc_hi, s9, 0
	global_load_dwordx2 v[244:245], v238, s[14:15] offset:0
	global_load_dwordx4 v[162:165], v194, vcc offset:0
	global_load_dwordx4 v[166:169], v194, vcc offset:64
	global_load_dwordx4 v[170:173], v194, vcc offset:512
	global_load_dwordx4 v[174:177], v194, vcc offset:576
	s_add_u32 vcc_lo, s8, 0x10000
	s_addc_u32 vcc_hi, s9, 0
	global_load_dwordx2 v[246:247], v238, s[14:15] offset:128
	global_load_dwordx4 v[178:181], v194, vcc offset:0
	global_load_dwordx4 v[182:185], v194, vcc offset:64
	global_load_dwordx4 v[186:189], v194, vcc offset:512
	global_load_dwordx4 v[190:193], v194, vcc offset:576
	s_add_u32 vcc_lo, s8, 0x20000
	s_addc_u32 vcc_hi, s9, 0
	global_load_dwordx2 v[248:249], v238, s[14:15] offset:256
	global_load_dwordx4 v[200:203], v194, vcc offset:0
	global_load_dwordx4 v[210:213], v194, vcc offset:64
	global_load_dwordx4 v[214:217], v194, vcc offset:512
	global_load_dwordx4 v[218:221], v194, vcc offset:576
	s_add_u32 vcc_lo, s8, 0x30000
	s_addc_u32 vcc_hi, s9, 0
	global_load_dwordx2 v[250:251], v238, s[14:15] offset:384
	global_load_dwordx4 v[222:225], v194, vcc offset:0
	global_load_dwordx4 v[226:229], v194, vcc offset:64
	global_load_dwordx4 v[230:233], v194, vcc offset:512
	global_load_dwordx4 v[234:237], v194, vcc offset:576
	s_waitcnt vmcnt(10)
	s_add_u32 vcc_lo, s56, 0x0
	s_addc_u32 vcc_hi, s57, 0
	v_sub_f32_e32 v163, v163, v244
	v_sub_f32_e32 v162, v162, v244
	v_sub_f32_e32 v165, v165, v244
	v_sub_f32_e32 v164, v164, v244
	v_pk_mul_f32 v[164:165], v[244:245], v[164:165] op_sel:[1,0]
	v_pk_mul_f32 v[162:163], v[244:245], v[162:163] op_sel:[1,0]
	v_pk_fma_f32 v[164:165], v[80:81], v[164:165], v[84:85]
	v_pk_fma_f32 v[162:163], v[78:79], v[162:163], v[82:83]
	v_pk_fma_f32 v[160:161], v[164:165], s[60:61], v[160:161] op_sel_hi:[1,0,1]
	v_pk_fma_f32 v[158:159], v[162:163], s[60:61], v[158:159] op_sel_hi:[1,0,1]
	global_store_dwordx4 v194, v[158:161], vcc offset:0
	v_sub_f32_e32 v167, v167, v244
	v_sub_f32_e32 v166, v166, v244
	v_sub_f32_e32 v169, v169, v244
	v_sub_f32_e32 v168, v168, v244
	v_pk_mul_f32 v[168:169], v[244:245], v[168:169] op_sel:[1,0]
	v_pk_mul_f32 v[166:167], v[244:245], v[166:167] op_sel:[1,0]
	v_pk_fma_f32 v[168:169], v[64:65], v[168:169], v[68:69]
	v_pk_fma_f32 v[166:167], v[62:63], v[166:167], v[66:67]
	v_pk_fma_f32 v[156:157], v[168:169], s[60:61], v[156:157] op_sel_hi:[1,0,1]
	v_pk_fma_f32 v[154:155], v[166:167], s[60:61], v[154:155] op_sel_hi:[1,0,1]
	global_store_dwordx4 v194, v[154:157], vcc offset:64
	v_sub_f32_e32 v171, v171, v244
	v_sub_f32_e32 v170, v170, v244
	v_sub_f32_e32 v173, v173, v244
	v_sub_f32_e32 v172, v172, v244
	v_pk_mul_f32 v[172:173], v[244:245], v[172:173] op_sel:[1,0]
	v_pk_mul_f32 v[170:171], v[244:245], v[170:171] op_sel:[1,0]
	v_pk_fma_f32 v[172:173], v[52:53], v[172:173], v[60:61]
	v_pk_fma_f32 v[170:171], v[50:51], v[170:171], v[58:59]
	v_pk_fma_f32 v[152:153], v[172:173], s[60:61], v[152:153] op_sel_hi:[1,0,1]
	v_pk_fma_f32 v[150:151], v[170:171], s[60:61], v[150:151] op_sel_hi:[1,0,1]
	global_store_dwordx4 v194, v[150:153], vcc offset:512
	v_sub_f32_e32 v175, v175, v244
	v_sub_f32_e32 v174, v174, v244
	v_sub_f32_e32 v177, v177, v244
	v_sub_f32_e32 v176, v176, v244
	v_pk_mul_f32 v[176:177], v[244:245], v[176:177] op_sel:[1,0]
	v_pk_mul_f32 v[174:175], v[244:245], v[174:175] op_sel:[1,0]
	v_pk_fma_f32 v[176:177], v[44:45], v[176:177], v[48:49]
	v_pk_fma_f32 v[174:175], v[42:43], v[174:175], v[46:47]
	v_pk_fma_f32 v[148:149], v[176:177], s[60:61], v[148:149] op_sel_hi:[1,0,1]
	v_pk_fma_f32 v[146:147], v[174:175], s[60:61], v[146:147] op_sel_hi:[1,0,1]
	global_store_dwordx4 v194, v[146:149], vcc offset:576
	s_add_u32 vcc_lo, s56, 0x10000
	s_addc_u32 vcc_hi, s57, 0
	v_sub_f32_e32 v179, v179, v246
	v_sub_f32_e32 v178, v178, v246
	v_sub_f32_e32 v181, v181, v246
	v_sub_f32_e32 v180, v180, v246
	v_pk_mul_f32 v[180:181], v[246:247], v[180:181] op_sel:[1,0]
	v_pk_mul_f32 v[178:179], v[246:247], v[178:179] op_sel:[1,0]
	v_pk_fma_f32 v[180:181], v[80:81], v[180:181], v[84:85]
	v_pk_fma_f32 v[178:179], v[78:79], v[178:179], v[82:83]
	v_pk_fma_f32 v[144:145], v[180:181], s[60:61], v[144:145] op_sel_hi:[1,0,1]
	v_pk_fma_f32 v[142:143], v[178:179], s[60:61], v[142:143] op_sel_hi:[1,0,1]
	global_store_dwordx4 v194, v[142:145], vcc offset:0
	v_sub_f32_e32 v183, v183, v246
	v_sub_f32_e32 v182, v182, v246
	v_sub_f32_e32 v185, v185, v246
	v_sub_f32_e32 v184, v184, v246
	v_pk_mul_f32 v[184:185], v[246:247], v[184:185] op_sel:[1,0]
	v_pk_mul_f32 v[182:183], v[246:247], v[182:183] op_sel:[1,0]
	v_pk_fma_f32 v[184:185], v[64:65], v[184:185], v[68:69]
	v_pk_fma_f32 v[182:183], v[62:63], v[182:183], v[66:67]
	v_pk_fma_f32 v[140:141], v[184:185], s[60:61], v[140:141] op_sel_hi:[1,0,1]
	v_pk_fma_f32 v[138:139], v[182:183], s[60:61], v[138:139] op_sel_hi:[1,0,1]
	global_store_dwordx4 v194, v[138:141], vcc offset:64
	v_sub_f32_e32 v187, v187, v246
	v_sub_f32_e32 v186, v186, v246
	v_sub_f32_e32 v189, v189, v246
	v_sub_f32_e32 v188, v188, v246
	v_pk_mul_f32 v[188:189], v[246:247], v[188:189] op_sel:[1,0]
	v_pk_mul_f32 v[186:187], v[246:247], v[186:187] op_sel:[1,0]
	v_pk_fma_f32 v[188:189], v[52:53], v[188:189], v[60:61]
	v_pk_fma_f32 v[186:187], v[50:51], v[186:187], v[58:59]
	v_pk_fma_f32 v[136:137], v[188:189], s[60:61], v[136:137] op_sel_hi:[1,0,1]
	v_pk_fma_f32 v[134:135], v[186:187], s[60:61], v[134:135] op_sel_hi:[1,0,1]
	global_store_dwordx4 v194, v[134:137], vcc offset:512
	v_sub_f32_e32 v191, v191, v246
	v_sub_f32_e32 v190, v190, v246
	v_sub_f32_e32 v193, v193, v246
	v_sub_f32_e32 v192, v192, v246
	v_pk_mul_f32 v[192:193], v[246:247], v[192:193] op_sel:[1,0]
	v_pk_mul_f32 v[190:191], v[246:247], v[190:191] op_sel:[1,0]
	v_pk_fma_f32 v[192:193], v[44:45], v[192:193], v[48:49]
	v_pk_fma_f32 v[190:191], v[42:43], v[190:191], v[46:47]
	v_pk_fma_f32 v[132:133], v[192:193], s[60:61], v[132:133] op_sel_hi:[1,0,1]
	v_pk_fma_f32 v[130:131], v[190:191], s[60:61], v[130:131] op_sel_hi:[1,0,1]
	global_store_dwordx4 v194, v[130:133], vcc offset:576
	s_add_u32 vcc_lo, s8, 0x80000
	s_addc_u32 vcc_hi, s9, 0
	global_load_dwordx2 v[244:245], v238, s[14:15] offset:1024
	global_load_dwordx4 v[158:161], v194, vcc offset:0
	global_load_dwordx4 v[154:157], v194, vcc offset:64
	global_load_dwordx4 v[150:153], v194, vcc offset:512
	global_load_dwordx4 v[146:149], v194, vcc offset:576
	s_add_u32 vcc_lo, s8, 0x90000
	s_addc_u32 vcc_hi, s9, 0
	global_load_dwordx2 v[246:247], v238, s[14:15] offset:1152
	global_load_dwordx4 v[142:145], v194, vcc offset:0
	global_load_dwordx4 v[138:141], v194, vcc offset:64
	global_load_dwordx4 v[134:137], v194, vcc offset:512
	global_load_dwordx4 v[130:133], v194, vcc offset:576
	s_waitcnt vmcnt(18)
	s_add_u32 vcc_lo, s56, 0x20000
	s_addc_u32 vcc_hi, s57, 0
	v_sub_f32_e32 v201, v201, v248
	v_sub_f32_e32 v200, v200, v248
	v_sub_f32_e32 v203, v203, v248
	v_sub_f32_e32 v202, v202, v248
	v_pk_mul_f32 v[202:203], v[248:249], v[202:203] op_sel:[1,0]
	v_pk_mul_f32 v[200:201], v[248:249], v[200:201] op_sel:[1,0]
	v_pk_fma_f32 v[202:203], v[80:81], v[202:203], v[84:85]
	v_pk_fma_f32 v[200:201], v[78:79], v[200:201], v[82:83]
	v_pk_fma_f32 v[128:129], v[202:203], s[60:61], v[128:129] op_sel_hi:[1,0,1]
	v_pk_fma_f32 v[126:127], v[200:201], s[60:61], v[126:127] op_sel_hi:[1,0,1]
	global_store_dwordx4 v194, v[126:129], vcc offset:0
	v_sub_f32_e32 v211, v211, v248
	v_sub_f32_e32 v210, v210, v248
	v_sub_f32_e32 v213, v213, v248
	v_sub_f32_e32 v212, v212, v248
	v_pk_mul_f32 v[212:213], v[248:249], v[212:213] op_sel:[1,0]
	v_pk_mul_f32 v[210:211], v[248:249], v[210:211] op_sel:[1,0]
	v_pk_fma_f32 v[212:213], v[64:65], v[212:213], v[68:69]
	v_pk_fma_f32 v[210:211], v[62:63], v[210:211], v[66:67]
	v_pk_fma_f32 v[124:125], v[212:213], s[60:61], v[124:125] op_sel_hi:[1,0,1]
	v_pk_fma_f32 v[122:123], v[210:211], s[60:61], v[122:123] op_sel_hi:[1,0,1]
	global_store_dwordx4 v194, v[122:125], vcc offset:64
	v_sub_f32_e32 v215, v215, v248
	v_sub_f32_e32 v214, v214, v248
	v_sub_f32_e32 v217, v217, v248
	v_sub_f32_e32 v216, v216, v248
	v_pk_mul_f32 v[216:217], v[248:249], v[216:217] op_sel:[1,0]
	v_pk_mul_f32 v[214:215], v[248:249], v[214:215] op_sel:[1,0]
	v_pk_fma_f32 v[216:217], v[52:53], v[216:217], v[60:61]
	v_pk_fma_f32 v[214:215], v[50:51], v[214:215], v[58:59]
	v_pk_fma_f32 v[120:121], v[216:217], s[60:61], v[120:121] op_sel_hi:[1,0,1]
	v_pk_fma_f32 v[118:119], v[214:215], s[60:61], v[118:119] op_sel_hi:[1,0,1]
	global_store_dwordx4 v194, v[118:121], vcc offset:512
	v_sub_f32_e32 v219, v219, v248
	v_sub_f32_e32 v218, v218, v248
	v_sub_f32_e32 v221, v221, v248
	v_sub_f32_e32 v220, v220, v248
	v_pk_mul_f32 v[220:221], v[248:249], v[220:221] op_sel:[1,0]
	v_pk_mul_f32 v[218:219], v[248:249], v[218:219] op_sel:[1,0]
	v_pk_fma_f32 v[220:221], v[44:45], v[220:221], v[48:49]
	v_pk_fma_f32 v[218:219], v[42:43], v[218:219], v[46:47]
	v_pk_fma_f32 v[116:117], v[220:221], s[60:61], v[116:117] op_sel_hi:[1,0,1]
	v_pk_fma_f32 v[114:115], v[218:219], s[60:61], v[114:115] op_sel_hi:[1,0,1]
	global_store_dwordx4 v194, v[114:117], vcc offset:576
	s_add_u32 vcc_lo, s56, 0x30000
	s_addc_u32 vcc_hi, s57, 0
	v_sub_f32_e32 v223, v223, v250
	v_sub_f32_e32 v222, v222, v250
	v_sub_f32_e32 v225, v225, v250
	v_sub_f32_e32 v224, v224, v250
	v_pk_mul_f32 v[224:225], v[250:251], v[224:225] op_sel:[1,0]
	v_pk_mul_f32 v[222:223], v[250:251], v[222:223] op_sel:[1,0]
	v_pk_fma_f32 v[224:225], v[80:81], v[224:225], v[84:85]
	v_pk_fma_f32 v[222:223], v[78:79], v[222:223], v[82:83]
	v_pk_fma_f32 v[112:113], v[224:225], s[60:61], v[112:113] op_sel_hi:[1,0,1]
	v_pk_fma_f32 v[110:111], v[222:223], s[60:61], v[110:111] op_sel_hi:[1,0,1]
	global_store_dwordx4 v194, v[110:113], vcc offset:0
	v_sub_f32_e32 v227, v227, v250
	v_sub_f32_e32 v226, v226, v250
	v_sub_f32_e32 v229, v229, v250
	v_sub_f32_e32 v228, v228, v250
	v_pk_mul_f32 v[228:229], v[250:251], v[228:229] op_sel:[1,0]
	v_pk_mul_f32 v[226:227], v[250:251], v[226:227] op_sel:[1,0]
	v_pk_fma_f32 v[228:229], v[64:65], v[228:229], v[68:69]
	v_pk_fma_f32 v[226:227], v[62:63], v[226:227], v[66:67]
	v_pk_fma_f32 v[108:109], v[228:229], s[60:61], v[108:109] op_sel_hi:[1,0,1]
	v_pk_fma_f32 v[106:107], v[226:227], s[60:61], v[106:107] op_sel_hi:[1,0,1]
	global_store_dwordx4 v194, v[106:109], vcc offset:64
	v_sub_f32_e32 v231, v231, v250
	v_sub_f32_e32 v230, v230, v250
	v_sub_f32_e32 v233, v233, v250
	v_sub_f32_e32 v232, v232, v250
	v_pk_mul_f32 v[232:233], v[250:251], v[232:233] op_sel:[1,0]
	v_pk_mul_f32 v[230:231], v[250:251], v[230:231] op_sel:[1,0]
	v_pk_fma_f32 v[232:233], v[52:53], v[232:233], v[60:61]
	v_pk_fma_f32 v[230:231], v[50:51], v[230:231], v[58:59]
	v_pk_fma_f32 v[104:105], v[232:233], s[60:61], v[104:105] op_sel_hi:[1,0,1]
	v_pk_fma_f32 v[102:103], v[230:231], s[60:61], v[102:103] op_sel_hi:[1,0,1]
	global_store_dwordx4 v194, v[102:105], vcc offset:512
	v_sub_f32_e32 v235, v235, v250
	v_sub_f32_e32 v234, v234, v250
	v_sub_f32_e32 v237, v237, v250
	v_sub_f32_e32 v236, v236, v250
	v_pk_mul_f32 v[236:237], v[250:251], v[236:237] op_sel:[1,0]
	v_pk_mul_f32 v[234:235], v[250:251], v[234:235] op_sel:[1,0]
	v_pk_fma_f32 v[236:237], v[44:45], v[236:237], v[48:49]
	v_pk_fma_f32 v[234:235], v[42:43], v[234:235], v[46:47]
	v_pk_fma_f32 v[100:101], v[236:237], s[60:61], v[100:101] op_sel_hi:[1,0,1]
	v_pk_fma_f32 v[98:99], v[234:235], s[60:61], v[98:99] op_sel_hi:[1,0,1]
	global_store_dwordx4 v194, v[98:101], vcc offset:576
	s_add_u32 vcc_lo, s8, 0xa0000
	s_addc_u32 vcc_hi, s9, 0
	global_load_dwordx2 v[248:249], v238, s[14:15] offset:1280
	global_load_dwordx4 v[126:129], v194, vcc offset:0
	global_load_dwordx4 v[122:125], v194, vcc offset:64
	global_load_dwordx4 v[118:121], v194, vcc offset:512
	global_load_dwordx4 v[114:117], v194, vcc offset:576
	s_add_u32 vcc_lo, s8, 0xb0000
	s_addc_u32 vcc_hi, s9, 0
	global_load_dwordx2 v[250:251], v238, s[14:15] offset:1408
	global_load_dwordx4 v[110:113], v194, vcc offset:0
	global_load_dwordx4 v[106:109], v194, vcc offset:64
	global_load_dwordx4 v[102:105], v194, vcc offset:512
	global_load_dwordx4 v[98:101], v194, vcc offset:576
	s_waitcnt vmcnt(18)
	s_add_u32 vcc_lo, s56, 0x80000
	s_addc_u32 vcc_hi, s57, 0
	v_sub_f32_e32 v159, v159, v244
	v_sub_f32_e32 v158, v158, v244
	v_sub_f32_e32 v161, v161, v244
	v_sub_f32_e32 v160, v160, v244
	v_pk_mul_f32 v[160:161], v[244:245], v[160:161] op_sel:[1,0]
	v_pk_mul_f32 v[158:159], v[244:245], v[158:159] op_sel:[1,0]
	v_pk_fma_f32 v[160:161], v[80:81], v[160:161], v[84:85]
	v_pk_fma_f32 v[158:159], v[78:79], v[158:159], v[82:83]
	v_pk_fma_f32 v[96:97], v[160:161], s[60:61], v[96:97] op_sel_hi:[1,0,1]
	v_pk_fma_f32 v[94:95], v[158:159], s[60:61], v[94:95] op_sel_hi:[1,0,1]
	global_store_dwordx4 v194, v[94:97], vcc offset:0
	v_sub_f32_e32 v155, v155, v244
	v_sub_f32_e32 v154, v154, v244
	v_sub_f32_e32 v157, v157, v244
	v_sub_f32_e32 v156, v156, v244
	v_pk_mul_f32 v[156:157], v[244:245], v[156:157] op_sel:[1,0]
	v_pk_mul_f32 v[154:155], v[244:245], v[154:155] op_sel:[1,0]
	v_pk_fma_f32 v[156:157], v[64:65], v[156:157], v[68:69]
	v_pk_fma_f32 v[154:155], v[62:63], v[154:155], v[66:67]
	v_pk_fma_f32 v[92:93], v[156:157], s[60:61], v[92:93] op_sel_hi:[1,0,1]
	v_pk_fma_f32 v[90:91], v[154:155], s[60:61], v[90:91] op_sel_hi:[1,0,1]
	global_store_dwordx4 v194, v[90:93], vcc offset:64
	v_sub_f32_e32 v151, v151, v244
	v_sub_f32_e32 v150, v150, v244
	v_sub_f32_e32 v153, v153, v244
	v_sub_f32_e32 v152, v152, v244
	v_pk_mul_f32 v[152:153], v[244:245], v[152:153] op_sel:[1,0]
	v_pk_mul_f32 v[150:151], v[244:245], v[150:151] op_sel:[1,0]
	v_pk_fma_f32 v[152:153], v[52:53], v[152:153], v[60:61]
	v_pk_fma_f32 v[150:151], v[50:51], v[150:151], v[58:59]
	v_pk_fma_f32 v[88:89], v[152:153], s[60:61], v[88:89] op_sel_hi:[1,0,1]
	v_pk_fma_f32 v[86:87], v[150:151], s[60:61], v[86:87] op_sel_hi:[1,0,1]
	global_store_dwordx4 v194, v[86:89], vcc offset:512
	v_sub_f32_e32 v147, v147, v244
	v_sub_f32_e32 v146, v146, v244
	v_sub_f32_e32 v149, v149, v244
	v_sub_f32_e32 v148, v148, v244
	v_pk_mul_f32 v[148:149], v[244:245], v[148:149] op_sel:[1,0]
	v_pk_mul_f32 v[146:147], v[244:245], v[146:147] op_sel:[1,0]
	v_pk_fma_f32 v[148:149], v[44:45], v[148:149], v[48:49]
	v_pk_fma_f32 v[146:147], v[42:43], v[146:147], v[46:47]
	v_pk_fma_f32 v[76:77], v[148:149], s[60:61], v[76:77] op_sel_hi:[1,0,1]
	v_pk_fma_f32 v[74:75], v[146:147], s[60:61], v[74:75] op_sel_hi:[1,0,1]
	global_store_dwordx4 v194, v[74:77], vcc offset:576
	s_add_u32 vcc_lo, s56, 0x90000
	s_addc_u32 vcc_hi, s57, 0
	v_sub_f32_e32 v143, v143, v246
	v_sub_f32_e32 v142, v142, v246
	v_sub_f32_e32 v145, v145, v246
	v_sub_f32_e32 v144, v144, v246
	v_pk_mul_f32 v[144:145], v[246:247], v[144:145] op_sel:[1,0]
	v_pk_mul_f32 v[142:143], v[246:247], v[142:143] op_sel:[1,0]
	v_pk_fma_f32 v[144:145], v[80:81], v[144:145], v[84:85]
	v_pk_fma_f32 v[142:143], v[78:79], v[142:143], v[82:83]
	v_pk_fma_f32 v[72:73], v[144:145], s[60:61], v[72:73] op_sel_hi:[1,0,1]
	v_pk_fma_f32 v[70:71], v[142:143], s[60:61], v[70:71] op_sel_hi:[1,0,1]
	global_store_dwordx4 v194, v[70:73], vcc offset:0
	v_sub_f32_e32 v139, v139, v246
	v_sub_f32_e32 v138, v138, v246
	v_sub_f32_e32 v141, v141, v246
	v_sub_f32_e32 v140, v140, v246
	v_pk_mul_f32 v[140:141], v[246:247], v[140:141] op_sel:[1,0]
	v_pk_mul_f32 v[138:139], v[246:247], v[138:139] op_sel:[1,0]
	v_pk_fma_f32 v[140:141], v[64:65], v[140:141], v[68:69]
	v_pk_fma_f32 v[138:139], v[62:63], v[138:139], v[66:67]
	v_pk_fma_f32 v[56:57], v[140:141], s[60:61], v[56:57] op_sel_hi:[1,0,1]
	v_pk_fma_f32 v[54:55], v[138:139], s[60:61], v[54:55] op_sel_hi:[1,0,1]
	global_store_dwordx4 v194, v[54:57], vcc offset:64
	v_sub_f32_e32 v135, v135, v246
	v_sub_f32_e32 v134, v134, v246
	v_sub_f32_e32 v137, v137, v246
	v_sub_f32_e32 v136, v136, v246
	v_pk_mul_f32 v[136:137], v[246:247], v[136:137] op_sel:[1,0]
	v_pk_mul_f32 v[134:135], v[246:247], v[134:135] op_sel:[1,0]
	v_pk_fma_f32 v[136:137], v[52:53], v[136:137], v[60:61]
	v_pk_fma_f32 v[134:135], v[50:51], v[134:135], v[58:59]
	v_pk_fma_f32 v[40:41], v[136:137], s[60:61], v[40:41] op_sel_hi:[1,0,1]
	v_pk_fma_f32 v[38:39], v[134:135], s[60:61], v[38:39] op_sel_hi:[1,0,1]
	global_store_dwordx4 v194, v[38:41], vcc offset:512
	v_sub_f32_e32 v131, v131, v246
	v_sub_f32_e32 v130, v130, v246
	v_sub_f32_e32 v133, v133, v246
	v_sub_f32_e32 v132, v132, v246
	v_pk_mul_f32 v[132:133], v[246:247], v[132:133] op_sel:[1,0]
	v_pk_mul_f32 v[130:131], v[246:247], v[130:131] op_sel:[1,0]
	v_pk_fma_f32 v[132:133], v[44:45], v[132:133], v[48:49]
	v_pk_fma_f32 v[130:131], v[42:43], v[130:131], v[46:47]
	v_pk_fma_f32 v[36:37], v[132:133], s[60:61], v[36:37] op_sel_hi:[1,0,1]
	v_pk_fma_f32 v[34:35], v[130:131], s[60:61], v[34:35] op_sel_hi:[1,0,1]
	global_store_dwordx4 v194, v[34:37], vcc offset:576
	s_waitcnt vmcnt(8)
	s_add_u32 vcc_lo, s56, 0xa0000
	s_addc_u32 vcc_hi, s57, 0
	v_sub_f32_e32 v127, v127, v248
	v_sub_f32_e32 v126, v126, v248
	v_sub_f32_e32 v129, v129, v248
	v_sub_f32_e32 v128, v128, v248
	v_pk_mul_f32 v[128:129], v[248:249], v[128:129] op_sel:[1,0]
	v_pk_mul_f32 v[126:127], v[248:249], v[126:127] op_sel:[1,0]
	v_pk_fma_f32 v[128:129], v[80:81], v[128:129], v[84:85]
	v_pk_fma_f32 v[126:127], v[78:79], v[126:127], v[82:83]
	v_pk_fma_f32 v[32:33], v[128:129], s[60:61], v[32:33] op_sel_hi:[1,0,1]
	v_pk_fma_f32 v[30:31], v[126:127], s[60:61], v[30:31] op_sel_hi:[1,0,1]
	global_store_dwordx4 v194, v[30:33], vcc offset:0
	v_sub_f32_e32 v123, v123, v248
	v_sub_f32_e32 v122, v122, v248
	v_sub_f32_e32 v125, v125, v248
	v_sub_f32_e32 v124, v124, v248
	v_pk_mul_f32 v[124:125], v[248:249], v[124:125] op_sel:[1,0]
	v_pk_mul_f32 v[122:123], v[248:249], v[122:123] op_sel:[1,0]
	v_pk_fma_f32 v[124:125], v[64:65], v[124:125], v[68:69]
	v_pk_fma_f32 v[122:123], v[62:63], v[122:123], v[66:67]
	v_pk_fma_f32 v[28:29], v[124:125], s[60:61], v[28:29] op_sel_hi:[1,0,1]
	v_pk_fma_f32 v[26:27], v[122:123], s[60:61], v[26:27] op_sel_hi:[1,0,1]
	global_store_dwordx4 v194, v[26:29], vcc offset:64
	v_sub_f32_e32 v119, v119, v248
	v_sub_f32_e32 v118, v118, v248
	v_sub_f32_e32 v121, v121, v248
	v_sub_f32_e32 v120, v120, v248
	v_pk_mul_f32 v[120:121], v[248:249], v[120:121] op_sel:[1,0]
	v_pk_mul_f32 v[118:119], v[248:249], v[118:119] op_sel:[1,0]
	v_pk_fma_f32 v[120:121], v[52:53], v[120:121], v[60:61]
	v_pk_fma_f32 v[118:119], v[50:51], v[118:119], v[58:59]
	v_pk_fma_f32 v[24:25], v[120:121], s[60:61], v[24:25] op_sel_hi:[1,0,1]
	v_pk_fma_f32 v[22:23], v[118:119], s[60:61], v[22:23] op_sel_hi:[1,0,1]
	global_store_dwordx4 v194, v[22:25], vcc offset:512
	v_sub_f32_e32 v115, v115, v248
	v_sub_f32_e32 v114, v114, v248
	v_sub_f32_e32 v117, v117, v248
	v_sub_f32_e32 v116, v116, v248
	v_pk_mul_f32 v[116:117], v[248:249], v[116:117] op_sel:[1,0]
	v_pk_mul_f32 v[114:115], v[248:249], v[114:115] op_sel:[1,0]
	v_pk_fma_f32 v[116:117], v[44:45], v[116:117], v[48:49]
	v_pk_fma_f32 v[114:115], v[42:43], v[114:115], v[46:47]
	v_pk_fma_f32 v[20:21], v[116:117], s[60:61], v[20:21] op_sel_hi:[1,0,1]
	v_pk_fma_f32 v[18:19], v[114:115], s[60:61], v[18:19] op_sel_hi:[1,0,1]
	global_store_dwordx4 v194, v[18:21], vcc offset:576
	s_add_u32 vcc_lo, s56, 0xb0000
	s_addc_u32 vcc_hi, s57, 0
	v_sub_f32_e32 v111, v111, v250
	v_sub_f32_e32 v110, v110, v250
	v_sub_f32_e32 v113, v113, v250
	v_sub_f32_e32 v112, v112, v250
	v_pk_mul_f32 v[112:113], v[250:251], v[112:113] op_sel:[1,0]
	v_pk_mul_f32 v[110:111], v[250:251], v[110:111] op_sel:[1,0]
	v_pk_fma_f32 v[112:113], v[80:81], v[112:113], v[84:85]
	v_pk_fma_f32 v[110:111], v[78:79], v[110:111], v[82:83]
	v_pk_fma_f32 v[16:17], v[112:113], s[60:61], v[16:17] op_sel_hi:[1,0,1]
	v_pk_fma_f32 v[14:15], v[110:111], s[60:61], v[14:15] op_sel_hi:[1,0,1]
	global_store_dwordx4 v194, v[14:17], vcc offset:0
	v_sub_f32_e32 v107, v107, v250
	v_sub_f32_e32 v106, v106, v250
	v_sub_f32_e32 v109, v109, v250
	v_sub_f32_e32 v108, v108, v250
	v_pk_mul_f32 v[108:109], v[250:251], v[108:109] op_sel:[1,0]
	v_pk_mul_f32 v[106:107], v[250:251], v[106:107] op_sel:[1,0]
	v_pk_fma_f32 v[108:109], v[64:65], v[108:109], v[68:69]
	v_pk_fma_f32 v[106:107], v[62:63], v[106:107], v[66:67]
	v_pk_fma_f32 v[12:13], v[108:109], s[60:61], v[12:13] op_sel_hi:[1,0,1]
	v_pk_fma_f32 v[10:11], v[106:107], s[60:61], v[10:11] op_sel_hi:[1,0,1]
	global_store_dwordx4 v194, v[10:13], vcc offset:64
	v_sub_f32_e32 v103, v103, v250
	v_sub_f32_e32 v102, v102, v250
	v_sub_f32_e32 v105, v105, v250
	v_sub_f32_e32 v104, v104, v250
	v_pk_mul_f32 v[104:105], v[250:251], v[104:105] op_sel:[1,0]
	v_pk_mul_f32 v[102:103], v[250:251], v[102:103] op_sel:[1,0]
	v_pk_fma_f32 v[104:105], v[52:53], v[104:105], v[60:61]
	v_pk_fma_f32 v[102:103], v[50:51], v[102:103], v[58:59]
	v_pk_fma_f32 v[8:9], v[104:105], s[60:61], v[8:9] op_sel_hi:[1,0,1]
	v_pk_fma_f32 v[6:7], v[102:103], s[60:61], v[6:7] op_sel_hi:[1,0,1]
	global_store_dwordx4 v194, v[6:9], vcc offset:512
	v_sub_f32_e32 v99, v99, v250
	v_sub_f32_e32 v98, v98, v250
	v_sub_f32_e32 v101, v101, v250
	v_sub_f32_e32 v100, v100, v250
	v_pk_mul_f32 v[100:101], v[250:251], v[100:101] op_sel:[1,0]
	v_pk_mul_f32 v[98:99], v[250:251], v[98:99] op_sel:[1,0]
	v_pk_fma_f32 v[100:101], v[44:45], v[100:101], v[48:49]
	v_pk_fma_f32 v[98:99], v[42:43], v[98:99], v[46:47]
	v_pk_fma_f32 v[4:5], v[100:101], s[60:61], v[4:5] op_sel_hi:[1,0,1]
	v_pk_fma_f32 v[2:3], v[98:99], s[60:61], v[2:3] op_sel_hi:[1,0,1]
	global_store_dwordx4 v194, v[2:5], vcc offset:576
	s_branch .Lepiout_end
.Lepiout_plain:
	s_add_u32 vcc_lo, s8, 0x0
	s_addc_u32 vcc_hi, s9, 0
	global_load_dwordx4 v[162:165], v194, vcc offset:0
	global_load_dwordx4 v[166:169], v194, vcc offset:64
	global_load_dwordx4 v[170:173], v194, vcc offset:512
	global_load_dwordx4 v[174:177], v194, vcc offset:576
	s_add_u32 vcc_lo, s8, 0x10000
	s_addc_u32 vcc_hi, s9, 0
	global_load_dwordx4 v[178:181], v194, vcc offset:0
	global_load_dwordx4 v[182:185], v194, vcc offset:64
	global_load_dwordx4 v[186:189], v194, vcc offset:512
	global_load_dwordx4 v[190:193], v194, vcc offset:576
	s_add_u32 vcc_lo, s8, 0x20000
	s_addc_u32 vcc_hi, s9, 0
	global_load_dwordx4 v[200:203], v194, vcc offset:0
	global_load_dwordx4 v[210:213], v194, vcc offset:64
	global_load_dwordx4 v[214:217], v194, vcc offset:512
	global_load_dwordx4 v[218:221], v194, vcc offset:576
	s_add_u32 vcc_lo, s8, 0x30000
	s_addc_u32 vcc_hi, s9, 0
	global_load_dwordx4 v[222:225], v194, vcc offset:0
	global_load_dwordx4 v[226:229], v194, vcc offset:64
	global_load_dwordx4 v[230:233], v194, vcc offset:512
	global_load_dwordx4 v[234:237], v194, vcc offset:576
	s_waitcnt vmcnt(8)
	s_add_u32 vcc_lo, s56, 0x0
	s_addc_u32 vcc_hi, s57, 0
	v_pk_fma_f32 v[160:161], v[164:165], s[60:61], v[160:161] op_sel_hi:[1,0,1]
	v_pk_fma_f32 v[158:159], v[162:163], s[60:61], v[158:159] op_sel_hi:[1,0,1]
	global_store_dwordx4 v194, v[158:161], vcc offset:0
	v_pk_fma_f32 v[156:157], v[168:169], s[60:61], v[156:157] op_sel_hi:[1,0,1]
	v_pk_fma_f32 v[154:155], v[166:167], s[60:61], v[154:155] op_sel_hi:[1,0,1]
	global_store_dwordx4 v194, v[154:157], vcc offset:64
	v_pk_fma_f32 v[152:153], v[172:173], s[60:61], v[152:153] op_sel_hi:[1,0,1]
	v_pk_fma_f32 v[150:151], v[170:171], s[60:61], v[150:151] op_sel_hi:[1,0,1]
	global_store_dwordx4 v194, v[150:153], vcc offset:512
	v_pk_fma_f32 v[148:149], v[176:177], s[60:61], v[148:149] op_sel_hi:[1,0,1]
	v_pk_fma_f32 v[146:147], v[174:175], s[60:61], v[146:147] op_sel_hi:[1,0,1]
	global_store_dwordx4 v194, v[146:149], vcc offset:576
	s_add_u32 vcc_lo, s56, 0x10000
	s_addc_u32 vcc_hi, s57, 0
	v_pk_fma_f32 v[144:145], v[180:181], s[60:61], v[144:145] op_sel_hi:[1,0,1]
	v_pk_fma_f32 v[142:143], v[178:179], s[60:61], v[142:143] op_sel_hi:[1,0,1]
	global_store_dwordx4 v194, v[142:145], vcc offset:0
	v_pk_fma_f32 v[140:141], v[184:185], s[60:61], v[140:141] op_sel_hi:[1,0,1]
	v_pk_fma_f32 v[138:139], v[182:183], s[60:61], v[138:139] op_sel_hi:[1,0,1]
	global_store_dwordx4 v194, v[138:141], vcc offset:64
	v_pk_fma_f32 v[136:137], v[188:189], s[60:61], v[136:137] op_sel_hi:[1,0,1]
	v_pk_fma_f32 v[134:135], v[186:187], s[60:61], v[134:135] op_sel_hi:[1,0,1]
	global_store_dwordx4 v194, v[134:137], vcc offset:512
	v_pk_fma_f32 v[132:133], v[192:193], s[60:61], v[132:133] op_sel_hi:[1,0,1]
	v_pk_fma_f32 v[130:131], v[190:191], s[60:61], v[130:131] op_sel_hi:[1,0,1]
	global_store_dwordx4 v194, v[130:133], vcc offset:576
	s_add_u32 vcc_lo, s8, 0x80000
	s_addc_u32 vcc_hi, s9, 0
	global_load_dwordx4 v[158:161], v194, vcc offset:0
	global_load_dwordx4 v[154:157], v194, vcc offset:64
	global_load_dwordx4 v[150:153], v194, vcc offset:512
	global_load_dwordx4 v[146:149], v194, vcc offset:576
	s_add_u32 vcc_lo, s8, 0x90000
	s_addc_u32 vcc_hi, s9, 0
	global_load_dwordx4 v[142:145], v194, vcc offset:0
	global_load_dwordx4 v[138:141], v194, vcc offset:64
	global_load_dwordx4 v[134:137], v194, vcc offset:512
	global_load_dwordx4 v[130:133], v194, vcc offset:576
	s_waitcnt vmcnt(16)
	s_add_u32 vcc_lo, s56, 0x20000
	s_addc_u32 vcc_hi, s57, 0
	v_pk_fma_f32 v[128:129], v[202:203], s[60:61], v[128:129] op_sel_hi:[1,0,1]
	v_pk_fma_f32 v[126:127], v[200:201], s[60:61], v[126:127] op_sel_hi:[1,0,1]
	global_store_dwordx4 v194, v[126:129], vcc offset:0
	v_pk_fma_f32 v[124:125], v[212:213], s[60:61], v[124:125] op_sel_hi:[1,0,1]
	v_pk_fma_f32 v[122:123], v[210:211], s[60:61], v[122:123] op_sel_hi:[1,0,1]
	global_store_dwordx4 v194, v[122:125], vcc offset:64
	v_pk_fma_f32 v[120:121], v[216:217], s[60:61], v[120:121] op_sel_hi:[1,0,1]
	v_pk_fma_f32 v[118:119], v[214:215], s[60:61], v[118:119] op_sel_hi:[1,0,1]
	global_store_dwordx4 v194, v[118:121], vcc offset:512
	v_pk_fma_f32 v[116:117], v[220:221], s[60:61], v[116:117] op_sel_hi:[1,0,1]
	v_pk_fma_f32 v[114:115], v[218:219], s[60:61], v[114:115] op_sel_hi:[1,0,1]
	global_store_dwordx4 v194, v[114:117], vcc offset:576
	s_add_u32 vcc_lo, s56, 0x30000
	s_addc_u32 vcc_hi, s57, 0
	v_pk_fma_f32 v[112:113], v[224:225], s[60:61], v[112:113] op_sel_hi:[1,0,1]
	v_pk_fma_f32 v[110:111], v[222:223], s[60:61], v[110:111] op_sel_hi:[1,0,1]
	global_store_dwordx4 v194, v[110:113], vcc offset:0
	v_pk_fma_f32 v[108:109], v[228:229], s[60:61], v[108:109] op_sel_hi:[1,0,1]
	v_pk_fma_f32 v[106:107], v[226:227], s[60:61], v[106:107] op_sel_hi:[1,0,1]
	global_store_dwordx4 v194, v[106:109], vcc offset:64
	v_pk_fma_f32 v[104:105], v[232:233], s[60:61], v[104:105] op_sel_hi:[1,0,1]
	v_pk_fma_f32 v[102:103], v[230:231], s[60:61], v[102:103] op_sel_hi:[1,0,1]
	global_store_dwordx4 v194, v[102:105], vcc offset:512
	v_pk_fma_f32 v[100:101], v[236:237], s[60:61], v[100:101] op_sel_hi:[1,0,1]
	v_pk_fma_f32 v[98:99], v[234:235], s[60:61], v[98:99] op_sel_hi:[1,0,1]
	global_store_dwordx4 v194, v[98:101], vcc offset:576
	s_add_u32 vcc_lo, s8, 0xa0000
	s_addc_u32 vcc_hi, s9, 0
	global_load_dwordx4 v[126:129], v194, vcc offset:0
	global_load_dwordx4 v[122:125], v194, vcc offset:64
	global_load_dwordx4 v[118:121], v194, vcc offset:512
	global_load_dwordx4 v[114:117], v194, vcc offset:576
	s_add_u32 vcc_lo, s8, 0xb0000
	s_addc_u32 vcc_hi, s9, 0
	global_load_dwordx4 v[110:113], v194, vcc offset:0
	global_load_dwordx4 v[106:109], v194, vcc offset:64
	global_load_dwordx4 v[102:105], v194, vcc offset:512
	global_load_dwordx4 v[98:101], v194, vcc offset:576
	s_waitcnt vmcnt(16)
	s_add_u32 vcc_lo, s56, 0x80000
	s_addc_u32 vcc_hi, s57, 0
	v_pk_fma_f32 v[96:97], v[160:161], s[60:61], v[96:97] op_sel_hi:[1,0,1]
	v_pk_fma_f32 v[94:95], v[158:159], s[60:61], v[94:95] op_sel_hi:[1,0,1]
	global_store_dwordx4 v194, v[94:97], vcc offset:0
	v_pk_fma_f32 v[92:93], v[156:157], s[60:61], v[92:93] op_sel_hi:[1,0,1]
	v_pk_fma_f32 v[90:91], v[154:155], s[60:61], v[90:91] op_sel_hi:[1,0,1]
	global_store_dwordx4 v194, v[90:93], vcc offset:64
	v_pk_fma_f32 v[88:89], v[152:153], s[60:61], v[88:89] op_sel_hi:[1,0,1]
	v_pk_fma_f32 v[86:87], v[150:151], s[60:61], v[86:87] op_sel_hi:[1,0,1]
	global_store_dwordx4 v194, v[86:89], vcc offset:512
	v_pk_fma_f32 v[76:77], v[148:149], s[60:61], v[76:77] op_sel_hi:[1,0,1]
	v_pk_fma_f32 v[74:75], v[146:147], s[60:61], v[74:75] op_sel_hi:[1,0,1]
	global_store_dwordx4 v194, v[74:77], vcc offset:576
	s_add_u32 vcc_lo, s56, 0x90000
	s_addc_u32 vcc_hi, s57, 0
	v_pk_fma_f32 v[72:73], v[144:145], s[60:61], v[72:73] op_sel_hi:[1,0,1]
	v_pk_fma_f32 v[70:71], v[142:143], s[60:61], v[70:71] op_sel_hi:[1,0,1]
	global_store_dwordx4 v194, v[70:73], vcc offset:0
	v_pk_fma_f32 v[56:57], v[140:141], s[60:61], v[56:57] op_sel_hi:[1,0,1]
	v_pk_fma_f32 v[54:55], v[138:139], s[60:61], v[54:55] op_sel_hi:[1,0,1]
	global_store_dwordx4 v194, v[54:57], vcc offset:64
	v_pk_fma_f32 v[40:41], v[136:137], s[60:61], v[40:41] op_sel_hi:[1,0,1]
	v_pk_fma_f32 v[38:39], v[134:135], s[60:61], v[38:39] op_sel_hi:[1,0,1]
	global_store_dwordx4 v194, v[38:41], vcc offset:512
	v_pk_fma_f32 v[36:37], v[132:133], s[60:61], v[36:37] op_sel_hi:[1,0,1]
	v_pk_fma_f32 v[34:35], v[130:131], s[60:61], v[34:35] op_sel_hi:[1,0,1]
	global_store_dwordx4 v194, v[34:37], vcc offset:576
	s_waitcnt vmcnt(8)
	s_add_u32 vcc_lo, s56, 0xa0000
	s_addc_u32 vcc_hi, s57, 0
	v_pk_fma_f32 v[32:33], v[128:129], s[60:61], v[32:33] op_sel_hi:[1,0,1]
	v_pk_fma_f32 v[30:31], v[126:127], s[60:61], v[30:31] op_sel_hi:[1,0,1]
	global_store_dwordx4 v194, v[30:33], vcc offset:0
	v_pk_fma_f32 v[28:29], v[124:125], s[60:61], v[28:29] op_sel_hi:[1,0,1]
	v_pk_fma_f32 v[26:27], v[122:123], s[60:61], v[26:27] op_sel_hi:[1,0,1]
	global_store_dwordx4 v194, v[26:29], vcc offset:64
	v_pk_fma_f32 v[24:25], v[120:121], s[60:61], v[24:25] op_sel_hi:[1,0,1]
	v_pk_fma_f32 v[22:23], v[118:119], s[60:61], v[22:23] op_sel_hi:[1,0,1]
	global_store_dwordx4 v194, v[22:25], vcc offset:512
	v_pk_fma_f32 v[20:21], v[116:117], s[60:61], v[20:21] op_sel_hi:[1,0,1]
	v_pk_fma_f32 v[18:19], v[114:115], s[60:61], v[18:19] op_sel_hi:[1,0,1]
	global_store_dwordx4 v194, v[18:21], vcc offset:576
	s_add_u32 vcc_lo, s56, 0xb0000
	s_addc_u32 vcc_hi, s57, 0
	v_pk_fma_f32 v[16:17], v[112:113], s[60:61], v[16:17] op_sel_hi:[1,0,1]
	v_pk_fma_f32 v[14:15], v[110:111], s[60:61], v[14:15] op_sel_hi:[1,0,1]
	global_store_dwordx4 v194, v[14:17], vcc offset:0
	v_pk_fma_f32 v[12:13], v[108:109], s[60:61], v[12:13] op_sel_hi:[1,0,1]
	v_pk_fma_f32 v[10:11], v[106:107], s[60:61], v[10:11] op_sel_hi:[1,0,1]
	global_store_dwordx4 v194, v[10:13], vcc offset:64
	v_pk_fma_f32 v[8:9], v[104:105], s[60:61], v[8:9] op_sel_hi:[1,0,1]
	v_pk_fma_f32 v[6:7], v[102:103], s[60:61], v[6:7] op_sel_hi:[1,0,1]
	global_store_dwordx4 v194, v[6:9], vcc offset:512
	v_pk_fma_f32 v[4:5], v[100:101], s[60:61], v[4:5] op_sel_hi:[1,0,1]
	v_pk_fma_f32 v[2:3], v[98:99], s[60:61], v[2:3] op_sel_hi:[1,0,1]
	global_store_dwordx4 v194, v[2:5], vcc offset:576
.Lepiout_end:
	s_and_b64 vcc, exec, s[42:43]
	s_cbranch_vccnz .LBB0_715
	s_branch .LBB0_689

.LBB0_786:
	s_andn2_b64 vcc, exec, s[26:27]
	s_waitcnt lgkmcnt(0)
	s_mov_b64 s[8:9], -1
	s_cbranch_vccnz .LBB0_873
	v_lshrrev_b32_e32 v5, 5, v242
	v_lshlrev_b32_e32 v0, 4, v5
	s_not_b32 s8, s71
	v_lshl_add_u64 v[2:3], s[58:59], 0, v[0:1]
	s_mov_b64 s[14:15], 0xf390000
	s_add_i32 s10, s23, s8
	v_lshl_add_u64 v[130:131], v[2:3], 0, s[14:15]
	s_mov_b64 s[14:15], 0xf360000
	s_cmp_lg_u32 s33, 0
	v_lshl_add_u64 v[132:133], v[2:3], 0, s[14:15]
	v_lshlrev_b32_e32 v0, 6, v242
	v_mov_b32_e32 v3, 0x3c0
	s_movk_i32 s14, 0x100
	s_cselect_b64 s[8:9], -1, 0
	v_bitop3_b32 v4, v0, s14, v3 bitop3:0x6c
	s_and_b32 s14, s66, 0xc0
	v_add_u32_e32 v164, s14, v242
	v_and_b32_e32 v2, 0x3c0, v0
	v_lshlrev_b32_e32 v0, 4, v164
	v_and_b32_e32 v0, 0x1fc0, v0
	v_lshl_add_u64 v[6:7], s[58:59], 0, v[0:1]
	s_mov_b64 s[16:17], 0x15390000
	v_lshl_add_u64 v[136:137], v[6:7], 0, s[16:17]
	v_lshlrev_b32_e32 v3, 1, v242
	v_lshrrev_b32_e32 v6, 1, v242
	v_and_b32_e32 v0, 19, v242
	v_and_b32_e32 v3, 8, v3
	v_and_b32_e32 v6, 4, v6
	v_or3_b32 v0, v6, v0, v3
	v_lshlrev_b32_e32 v165, 7, v0
	v_lshrrev_b32_e32 v0, 1, v0
	s_cmp_gt_i32 s1, 3
	v_bitop3_b32 v3, v0, v5, 7 bitop3:0x6c
	s_cselect_b64 s[14:15], -1, 0
	s_add_u32 s16, s58, 0x12390000
	v_lshlrev_b32_e32 v166, 4, v3
	v_add_u32_e32 v3, 2, v5
	s_addc_u32 s17, s59, 0
	v_bitop3_b32 v6, v0, v3, 7 bitop3:0x6c
	s_lshl_b32 s18, s1, 10
	v_lshlrev_b32_e32 v167, 4, v6
	v_or_b32_e32 v6, 4, v5
	s_add_i32 s29, s18, 0
	v_bitop3_b32 v6, v0, v6, 7 bitop3:0x6c
	s_add_u32 s42, s58, 0xa500000
	v_lshlrev_b32_e32 v168, 4, v6
	v_add_u32_e32 v6, 6, v5
	s_addc_u32 s43, s59, 0
	v_bitop3_b32 v0, v0, v6, 7 bitop3:0x6c
	s_add_u32 s44, s58, 0x1c090000
	v_lshlrev_b32_e32 v169, 4, v0
	v_lshrrev_b32_e32 v0, 2, v242
	s_addc_u32 s45, s59, 0
	s_lshl_b32 s41, s1, 5
	v_and_b32_e32 v135, 31, v242
	v_lshlrev_b32_e32 v148, 3, v5
	v_lshlrev_b32_e32 v134, 2, v5
	v_bitop3_b32 v5, v0, v5, 3 bitop3:0x6c
	v_bitop3_b32 v0, v3, v0, 3 bitop3:0x78
	s_lshl_b32 s54, s1, 8
	s_lshl_b32 s55, s1, 7
	s_addk_i32 s41, 0xf00
	v_add_u32_e32 v156, 8, v134
	v_add_u32_e32 v158, 9, v134
	v_add_u32_e32 v160, 10, v134
	v_add_u32_e32 v162, 11, v134
	v_lshlrev_b32_e32 v172, 4, v0
	v_or_b32_e32 v0, s41, v135
	s_add_u32 s46, s58, 0x1c090018
	s_mov_b32 s40, 0
	v_xor_b32_e32 v149, 4, v134
	v_or_b32_e32 v150, 1, v134
	v_xor_b32_e32 v151, 5, v134
	v_or_b32_e32 v152, 2, v134
	v_xor_b32_e32 v153, 6, v134
	v_or_b32_e32 v154, 3, v134
	v_xor_b32_e32 v155, 7, v134
	v_xor_b32_e32 v157, 4, v156
	v_xor_b32_e32 v159, 4, v158
	v_xor_b32_e32 v161, 4, v160
	v_xor_b32_e32 v163, 4, v162
	v_lshrrev_b32_e32 v138, 3, v164
	v_mov_b32_e32 v139, v1
	v_lshlrev_b32_e32 v170, 6, v135
	v_lshlrev_b32_e32 v171, 4, v5
	v_lshlrev_b32_e32 v173, 2, v135
	v_sub_u32_e32 v174, v0, v148
	s_addc_u32 s47, s59, 0
	v_add_u32_e32 v175, 0xf00, v164
	v_lshlrev_b32_e32 v140, 1, v2
	v_lshlrev_b32_e32 v142, 1, v4
	s_add_i32 s56, s29, 0x2000
	s_add_i32 s57, s29, 0x4000
	s_add_i32 s61, s29, 0x6000
	s_add_i32 s62, s29, 0xa000
	s_mov_b32 s63, 0
	s_branch .LBB0_791

.LBB0_797:
	v_cmp_gt_i32_e32 vcc, s66, v134
	s_nop 4
	v_mov_b32_e32 v26, 0xff61b1e6
	s_mov_b32 s40, 0xff61b1e6
	v_cndmask_b32_e32 v12, v26, v18, vcc
	v_cmp_lt_f32_e32 vcc, s40, v12
	v_max_f32_e32 v13, v12, v12
	v_max_f32_e32 v13, 0xff61b1e6, v13
	v_cndmask_b32_e32 v12, -1, v134, vcc
	v_cmp_gt_i32_e32 vcc, s66, v149
	v_lshrrev_b32_e32 v0, 4, v0
	v_xor_b32_e32 v0, v0, v242
	v_cndmask_b32_e32 v2, v26, v2, vcc
	v_max_f32_e32 v14, v2, v2
	v_cmp_lt_f32_e32 vcc, s40, v2
	v_max_f32_e32 v14, 0xff61b1e6, v14
	v_lshlrev_b32_e32 v0, 4, v0
	v_cndmask_b32_e32 v15, -1, v149, vcc
	v_cmp_gt_f32_e32 vcc, v2, v13
	s_mov_b32 m0, s29
	s_barrier
	v_cndmask_b32_e32 v14, v14, v13, vcc
	v_cndmask_b32_e32 v16, v12, v149, vcc
	v_cndmask_b32_e32 v2, v13, v2, vcc
	v_cndmask_b32_e32 v12, v15, v12, vcc
	v_cmp_gt_i32_e32 vcc, s66, v150
	s_add_i32 s49, s67, 8
	v_lshl_add_u32 v145, s65, 8, v174
	v_cndmask_b32_e32 v13, v26, v19, vcc
	v_max_f32_e32 v15, v13, v13
	v_cmp_lt_f32_e64 s[40:41], s40, v13
	v_max_f32_e32 v15, 0xff61b1e6, v15
	v_cmp_gt_f32_e32 vcc, v13, v14
	v_cndmask_b32_e64 v17, -1, v150, s[40:41]
	v_cmp_gt_f32_e64 s[40:41], v13, v2
	v_cndmask_b32_e32 v15, v15, v14, vcc
	v_cndmask_b32_e32 v17, v17, v12, vcc
	v_cndmask_b32_e32 v14, v14, v13, vcc
	v_cndmask_b32_e32 v12, v12, v150, vcc
	v_cmp_gt_i32_e32 vcc, s66, v151
	v_cndmask_b32_e64 v14, v14, v2, s[40:41]
	v_cndmask_b32_e64 v18, v16, v150, s[40:41]
	v_cndmask_b32_e32 v3, v26, v3, vcc
	v_cmp_gt_f32_e32 vcc, v3, v15
	v_cndmask_b32_e64 v2, v2, v13, s[40:41]
	v_cndmask_b32_e64 v12, v12, v16, s[40:41]
	v_cndmask_b32_e32 v13, v15, v3, vcc
	v_cmp_gt_f32_e64 s[40:41], v3, v14
	v_cndmask_b32_e32 v15, v17, v151, vcc
	v_cmp_gt_f32_e32 vcc, v3, v2
	v_cndmask_b32_e64 v13, v13, v14, s[40:41]
	v_cndmask_b32_e64 v15, v15, v12, s[40:41]
	v_cndmask_b32_e64 v14, v14, v3, s[40:41]
	v_cndmask_b32_e64 v12, v12, v151, s[40:41]
	v_cndmask_b32_e32 v14, v14, v2, vcc
	v_cndmask_b32_e32 v16, v18, v151, vcc
	v_cndmask_b32_e32 v2, v2, v3, vcc
	v_cndmask_b32_e32 v3, v12, v18, vcc
	v_cmp_gt_i32_e32 vcc, s66, v152
	v_mov_b32_e32 v176, 0xf149f2ca
	v_mov_b32_e32 v141, 0
	v_cndmask_b32_e32 v12, v26, v20, vcc
	v_cmp_gt_f32_e32 vcc, v12, v13
	v_cmp_gt_f32_e64 s[40:41], v12, v14
	s_nop 0
	v_cndmask_b32_e32 v13, v13, v12, vcc
	v_cndmask_b32_e32 v15, v15, v152, vcc
	v_cndmask_b32_e64 v13, v13, v14, s[40:41]
	v_cndmask_b32_e64 v15, v15, v3, s[40:41]
	v_cndmask_b32_e64 v14, v14, v12, s[40:41]
	v_cmp_gt_f32_e32 vcc, v12, v2
	v_cndmask_b32_e64 v3, v3, v152, s[40:41]
	s_nop 0
	v_cndmask_b32_e32 v14, v14, v2, vcc
	v_cndmask_b32_e32 v17, v16, v152, vcc
	v_cndmask_b32_e32 v2, v2, v12, vcc
	v_cndmask_b32_e32 v3, v3, v16, vcc
	v_cmp_gt_i32_e32 vcc, s66, v153
	s_nop 1
	v_cndmask_b32_e32 v4, v26, v4, vcc
	v_cmp_gt_f32_e32 vcc, v4, v13
	v_cmp_gt_f32_e64 s[40:41], v4, v14
	s_nop 0
	v_cndmask_b32_e32 v12, v13, v4, vcc
	v_cndmask_b32_e32 v13, v15, v153, vcc
	v_cndmask_b32_e64 v12, v12, v14, s[40:41]
	v_cndmask_b32_e64 v13, v13, v3, s[40:41]
	v_cndmask_b32_e64 v14, v14, v4, s[40:41]
	v_cmp_gt_f32_e32 vcc, v4, v2
	v_cndmask_b32_e64 v3, v3, v153, s[40:41]
	s_nop 0
	v_cndmask_b32_e32 v14, v14, v2, vcc
	v_cndmask_b32_e32 v15, v17, v153, vcc
	v_cndmask_b32_e32 v2, v2, v4, vcc
	v_cndmask_b32_e32 v3, v3, v17, vcc
	v_cmp_gt_i32_e32 vcc, s66, v154
	s_nop 1
	v_cndmask_b32_e32 v4, v26, v21, vcc
	v_cmp_gt_f32_e32 vcc, v4, v12
	v_cmp_gt_f32_e64 s[40:41], v4, v14
	s_nop 0
	v_cndmask_b32_e32 v12, v12, v4, vcc
	v_cndmask_b32_e32 v13, v13, v154, vcc
	v_cndmask_b32_e64 v12, v12, v14, s[40:41]
	v_cndmask_b32_e64 v13, v13, v3, s[40:41]
	v_cndmask_b32_e64 v14, v14, v4, s[40:41]
	v_cmp_gt_f32_e32 vcc, v4, v2
	v_cndmask_b32_e64 v3, v3, v154, s[40:41]
	s_nop 0
	v_cndmask_b32_e32 v14, v14, v2, vcc
	v_cndmask_b32_e32 v16, v15, v154, vcc
	v_cndmask_b32_e32 v2, v2, v4, vcc
	v_cndmask_b32_e32 v3, v3, v15, vcc
	v_cmp_gt_i32_e32 vcc, s66, v155
	s_nop 1
	v_cndmask_b32_e32 v4, v26, v5, vcc
	v_cmp_gt_f32_e32 vcc, v4, v12
	v_cmp_gt_f32_e64 s[40:41], v4, v14
	s_nop 0
	v_cndmask_b32_e32 v5, v12, v4, vcc
	v_cndmask_b32_e32 v12, v13, v155, vcc
	v_cndmask_b32_e64 v12, v12, v3, s[40:41]
	v_cndmask_b32_e64 v13, v14, v4, s[40:41]
	v_cmp_gt_f32_e32 vcc, v4, v2
	v_cndmask_b32_e64 v3, v3, v155, s[40:41]
	v_cndmask_b32_e64 v5, v5, v14, s[40:41]
	v_cndmask_b32_e32 v13, v13, v2, vcc
	v_cndmask_b32_e32 v14, v16, v155, vcc
	v_cndmask_b32_e32 v2, v2, v4, vcc
	v_cndmask_b32_e32 v3, v3, v16, vcc
	v_cmp_gt_i32_e32 vcc, s66, v156
	s_nop 1
	v_cndmask_b32_e32 v4, v26, v22, vcc
	v_cmp_gt_f32_e32 vcc, v4, v5
	v_cmp_gt_f32_e64 s[40:41], v4, v13
	s_nop 0
	v_cndmask_b32_e32 v5, v5, v4, vcc
	v_cndmask_b32_e32 v12, v12, v156, vcc
	v_cndmask_b32_e64 v5, v5, v13, s[40:41]
	v_cndmask_b32_e64 v12, v12, v3, s[40:41]
	v_cndmask_b32_e64 v13, v13, v4, s[40:41]
	v_cmp_gt_f32_e32 vcc, v4, v2
	v_cndmask_b32_e64 v3, v3, v156, s[40:41]
	s_nop 0
	v_cndmask_b32_e32 v13, v13, v2, vcc
	v_cndmask_b32_e32 v15, v14, v156, vcc
	v_cndmask_b32_e32 v2, v2, v4, vcc
	v_cndmask_b32_e32 v3, v3, v14, vcc
	v_cmp_gt_i32_e32 vcc, s66, v157
	s_nop 1
	v_cndmask_b32_e32 v4, v26, v6, vcc
	v_cmp_gt_f32_e32 vcc, v4, v5
	v_cmp_gt_f32_e64 s[40:41], v4, v13
	s_nop 0
	v_cndmask_b32_e32 v6, v12, v157, vcc
	v_cndmask_b32_e32 v5, v5, v4, vcc
	v_cndmask_b32_e64 v6, v6, v3, s[40:41]
	v_cndmask_b32_e64 v12, v13, v4, s[40:41]
	v_cmp_gt_f32_e32 vcc, v4, v2
	v_cndmask_b32_e64 v3, v3, v157, s[40:41]
	v_cndmask_b32_e64 v5, v5, v13, s[40:41]
	v_cndmask_b32_e32 v12, v12, v2, vcc
	v_cndmask_b32_e32 v13, v15, v157, vcc
	v_cndmask_b32_e32 v2, v2, v4, vcc
	v_cndmask_b32_e32 v3, v3, v15, vcc
	v_cmp_gt_i32_e32 vcc, s66, v158
	s_nop 1
	v_cndmask_b32_e32 v4, v26, v23, vcc
	v_cmp_gt_f32_e32 vcc, v4, v5
	v_cmp_gt_f32_e64 s[40:41], v4, v12
	s_nop 0
	v_cndmask_b32_e32 v5, v5, v4, vcc
	v_cndmask_b32_e32 v6, v6, v158, vcc
	v_cndmask_b32_e64 v5, v5, v12, s[40:41]
	v_cndmask_b32_e64 v6, v6, v3, s[40:41]
	v_cndmask_b32_e64 v12, v12, v4, s[40:41]
	v_cmp_gt_f32_e32 vcc, v4, v2
	v_cndmask_b32_e64 v3, v3, v158, s[40:41]
	s_nop 0
	v_cndmask_b32_e32 v12, v12, v2, vcc
	v_cndmask_b32_e32 v14, v13, v158, vcc
	v_cndmask_b32_e32 v2, v2, v4, vcc
	v_cndmask_b32_e32 v3, v3, v13, vcc
	v_cmp_gt_i32_e32 vcc, s66, v159
	s_nop 1
	v_cndmask_b32_e32 v4, v26, v7, vcc
	v_cmp_gt_f32_e32 vcc, v4, v5
	v_cmp_gt_f32_e64 s[40:41], v4, v12
	s_nop 0
	v_cndmask_b32_e32 v6, v6, v159, vcc
	v_cndmask_b32_e32 v5, v5, v4, vcc
	v_cndmask_b32_e64 v6, v6, v3, s[40:41]
	v_cndmask_b32_e64 v7, v12, v4, s[40:41]
	v_cmp_gt_f32_e32 vcc, v4, v2
	v_cndmask_b32_e64 v3, v3, v159, s[40:41]
	v_cndmask_b32_e64 v5, v5, v12, s[40:41]
	v_cndmask_b32_e32 v7, v7, v2, vcc
	v_cndmask_b32_e32 v12, v14, v159, vcc
	v_cndmask_b32_e32 v2, v2, v4, vcc
	v_cndmask_b32_e32 v3, v3, v14, vcc
	v_cmp_gt_i32_e32 vcc, s66, v160
	s_nop 1
	v_cndmask_b32_e32 v4, v26, v24, vcc
	v_cmp_gt_f32_e32 vcc, v4, v5
	v_cmp_gt_f32_e64 s[40:41], v4, v7
	s_nop 0
	v_cndmask_b32_e32 v5, v5, v4, vcc
	v_cndmask_b32_e64 v13, v5, v7, s[40:41]
	v_cndmask_b32_e32 v5, v6, v160, vcc
	v_cndmask_b32_e64 v6, v5, v3, s[40:41]
	v_cndmask_b32_e64 v5, v7, v4, s[40:41]
	v_cndmask_b32_e64 v3, v3, v160, s[40:41]
	s_lshl_b32 s40, s69, 1
	v_cmp_gt_f32_e32 vcc, v4, v2
	v_and_b32_e32 v0, s40, v0
	s_mov_b64 s[40:41], 0x2000
	v_cndmask_b32_e32 v7, v5, v2, vcc
	v_cndmask_b32_e32 v14, v12, v160, vcc
	v_cndmask_b32_e32 v15, v2, v4, vcc
	v_cndmask_b32_e32 v12, v3, v12, vcc
	v_lshl_add_u64 v[2:3], v[10:11], 0, v[0:1]
	global_load_lds_dwordx4 v[2:3], off
	v_lshl_add_u64 v[4:5], v[2:3], 0, s[20:21]
	s_mov_b32 m0, s56
	v_cmp_gt_i32_e32 vcc, s66, v161
	global_load_lds_dwordx4 v[4:5], off
	v_lshl_add_u64 v[4:5], v[2:3], 0, s[40:41]
	s_mov_b32 m0, s57
	s_mov_b64 s[40:41], 0x4000
	global_load_lds_dwordx4 v[4:5], off
	v_lshl_add_u64 v[4:5], v[2:3], 0, s[24:25]
	s_mov_b32 m0, s61
	v_cndmask_b32_e32 v0, v26, v8, vcc
	global_load_lds_dwordx4 v[4:5], off
	v_lshl_add_u64 v[4:5], v[2:3], 0, s[40:41]
	s_add_i32 m0, s29, 0x8000
	s_mov_b64 s[40:41], 0x5000
	global_load_lds_dwordx4 v[4:5], off
	v_lshl_add_u64 v[4:5], v[2:3], 0, s[40:41]
	s_mov_b32 m0, s62
	v_cmp_gt_f32_e32 vcc, v0, v13
	global_load_lds_dwordx4 v[4:5], off
	s_nop 0
	v_cndmask_b32_e32 v4, v13, v0, vcc
	v_cmp_gt_f32_e64 s[40:41], v0, v7
	v_cndmask_b32_e32 v5, v6, v161, vcc
	v_cmp_gt_f32_e32 vcc, v0, v15
	v_cndmask_b32_e64 v4, v4, v7, s[40:41]
	v_cndmask_b32_e64 v6, v7, v0, s[40:41]
	v_cndmask_b32_e64 v7, v12, v161, s[40:41]
	v_cndmask_b32_e32 v6, v6, v15, vcc
	v_cndmask_b32_e32 v8, v14, v161, vcc
	v_cndmask_b32_e32 v0, v15, v0, vcc
	v_cndmask_b32_e32 v7, v7, v14, vcc
	v_cmp_gt_i32_e32 vcc, s66, v162
	v_cndmask_b32_e64 v5, v5, v12, s[40:41]
	v_mov_b32_e32 v14, v1
	v_cndmask_b32_e32 v10, v26, v25, vcc
	v_cmp_gt_f32_e32 vcc, v10, v4
	v_cmp_gt_f32_e64 s[40:41], v10, v6
	v_mov_b32_e32 v15, v1
	v_cndmask_b32_e32 v4, v4, v10, vcc
	v_cndmask_b32_e32 v5, v5, v162, vcc
	v_cndmask_b32_e64 v4, v4, v6, s[40:41]
	v_cndmask_b32_e64 v5, v5, v7, s[40:41]
	v_cndmask_b32_e64 v6, v6, v10, s[40:41]
	v_cmp_gt_f32_e32 vcc, v10, v0
	v_cndmask_b32_e64 v7, v7, v162, s[40:41]
	v_mov_b32_e32 v12, v1
	v_cndmask_b32_e32 v6, v6, v0, vcc
	v_cndmask_b32_e32 v11, v8, v162, vcc
	v_cndmask_b32_e32 v0, v0, v10, vcc
	v_cndmask_b32_e32 v7, v7, v8, vcc
	v_cmp_gt_i32_e32 vcc, s66, v163
	v_mov_b32_e32 v10, v1
	v_mov_b32_e32 v13, v1
	v_cndmask_b32_e32 v8, v26, v9, vcc
	v_cmp_gt_f32_e32 vcc, v8, v4
	v_cmp_gt_f32_e64 s[40:41], v8, v6
	s_mov_b32 s69, 0
	v_cndmask_b32_e32 v4, v4, v8, vcc
	v_cndmask_b32_e64 v4, v4, v6, s[40:41]
	v_cndmask_b32_e32 v5, v5, v163, vcc
	v_cndmask_b32_e64 v6, v6, v8, s[40:41]
	v_cmp_gt_f32_e32 vcc, v8, v0
	v_cndmask_b32_e64 v5, v5, v7, s[40:41]
	v_cndmask_b32_e64 v7, v7, v163, s[40:41]
	v_cndmask_b32_e32 v6, v6, v0, vcc
	v_cndmask_b32_e32 v9, v11, v163, vcc
	v_cndmask_b32_e32 v0, v0, v8, vcc
	s_mov_b32 s40, 0xfe967699
	v_cndmask_b32_e32 v7, v7, v11, vcc
	v_lshlrev_b32_e64 v8, v9, 1
	v_cmp_lt_f32_e32 vcc, s40, v0
	v_lshlrev_b32_e64 v7, v7, 1
	v_lshlrev_b32_e64 v5, v5, 1
	v_cndmask_b32_e32 v0, 0, v8, vcc
	v_cmp_lt_f32_e32 vcc, s40, v6
	v_mov_b32_e32 v8, v1
	v_mov_b32_e32 v9, v1
	v_cndmask_b32_e32 v6, 0, v7, vcc
	v_cmp_lt_f32_e32 vcc, s40, v4
	s_lshl_b32 s40, s65, 3
	s_add_i32 s70, s40, 0x7f
	v_cndmask_b32_e32 v4, 0, v5, vcc
	s_mov_b64 s[40:41], 0x6000
	v_or3_b32 v143, v4, v0, v6
	v_lshl_add_u64 v[146:147], v[2:3], 0, s[40:41]
	v_mov_b32_e32 v0, v1
	v_mov_b32_e32 v2, v1
	v_mov_b32_e32 v3, v1
	v_mov_b32_e32 v4, v1
	v_mov_b32_e32 v5, v1
	v_mov_b32_e32 v6, v1
	v_mov_b32_e32 v7, v1
	v_mov_b32_e32 v11, v1
	v_mov_b64_e32 v[32:33], v[14:15]
	v_mov_b64_e32 v[30:31], v[12:13]
	v_mov_b64_e32 v[28:29], v[10:11]
	v_mov_b64_e32 v[26:27], v[8:9]
	v_mov_b64_e32 v[24:25], v[6:7]
	v_mov_b64_e32 v[22:23], v[4:5]
	v_mov_b64_e32 v[20:21], v[2:3]
	v_mov_b64_e32 v[18:19], v[0:1]
	v_mov_b64_e32 v[16:17], v[14:15]
	v_mov_b64_e32 v[14:15], v[12:13]
	v_mov_b64_e32 v[12:13], v[10:11]
	v_mov_b64_e32 v[10:11], v[8:9]
	v_mov_b64_e32 v[8:9], v[6:7]
	v_mov_b64_e32 v[6:7], v[4:5]
	v_mov_b64_e32 v[4:5], v[2:3]
	v_mov_b64_e32 v[2:3], v[0:1]
	s_branch .LBB0_801
.LBB0_801:
	s_add_i32 m0, s18, 0xc000
	s_nop 0
	global_load_lds_dwordx4 v[146:147], off
	v_lshl_add_u64 v[146:147], v[146:147], 0, s[20:21]
	s_add_i32 m0, s18, 0xe000
	s_nop 0
	global_load_lds_dwordx4 v[146:147], off
	v_lshl_add_u64 v[146:147], v[146:147], 0, s[20:21]
	s_cmp_eq_u32 s49, 8
	s_cbranch_scc1 .Lmob_pk8
	s_add_i32 m0, s18, 0x10000
	s_nop 0
	global_load_lds_dwordx4 v[146:147], off
	v_lshl_add_u64 v[146:147], v[146:147], 0, s[20:21]
	s_add_i32 m0, s18, 0x12000
	s_nop 0
	global_load_lds_dwordx4 v[146:147], off
	v_lshl_add_u64 v[146:147], v[146:147], 0, s[20:21]
	s_add_i32 m0, s18, 0x14000
	s_nop 0
	global_load_lds_dwordx4 v[146:147], off
	v_lshl_add_u64 v[146:147], v[146:147], 0, s[20:21]
	s_add_i32 m0, s18, 0x16000
	s_nop 0
	global_load_lds_dwordx4 v[146:147], off
	v_lshl_add_u64 v[146:147], v[146:147], 0, s[20:21]
	s_add_i32 m0, s18, 0x18000
	s_nop 0
	global_load_lds_dwordx4 v[146:147], off
	v_lshl_add_u64 v[146:147], v[146:147], 0, s[20:21]
	s_add_i32 m0, s18, 0x1a000
	s_nop 0
	global_load_lds_dwordx4 v[146:147], off
	v_lshl_add_u64 v[146:147], v[146:147], 0, s[20:21]
	s_branch .Lmob_pk14
.Lmob_pk8:
.Lmob_pk14:
	v_add_u32_e32 v216, v166, v165
	v_add_u32_e32 v217, v167, v165
	v_add_u32_e32 v218, v168, v165
	v_add_u32_e32 v219, v169, v165
	v_add_u32_e32 v220, v170, v171
	v_add_u32_e32 v221, v170, v172
	v_mov_b32_e32 v123, 0xff800000
	s_cmp_eq_u32 s49, 8
	s_cbranch_scc1 .Lmob_pw7
	s_waitcnt vmcnt(13)
	s_branch .Lmob_pbar
.Lmob_pw7:
	s_waitcnt vmcnt(7)
.Lmob_pbar:
	s_barrier
	ds_read_b128 v[66:69], v216
	ds_read_b128 v[70:73], v217
	ds_read_b128 v[74:77], v218
	ds_read_b128 v[78:81], v219
	s_waitcnt lgkmcnt(0)
	v_mfma_f32_32x32x16_bf16 v[34:49], v[66:69], v[82:85], 0
	v_mfma_f32_32x32x16_bf16 v[34:49], v[70:73], v[86:89], v[34:49]
	v_mfma_f32_32x32x16_bf16 v[34:49], v[74:77], v[90:93], v[34:49]
	v_mfma_f32_32x32x16_bf16 v[34:49], v[78:81], v[94:97], v[34:49]
.Lmob_top_e:
	s_add_i32 s40, s69, 14
	s_cmp_ge_u32 s40, s49
	s_cbranch_scc1 .Lmob_noissue_e
	s_and_b32 s40, s40, 15
	s_lshl_b32 s40, s40, 13
	s_add_i32 m0, s40, s18
	s_nop 0
	global_load_lds_dwordx4 v[146:147], off
.Lmob_noissue_e:
	s_cmp_gt_i32 s70, 13
	s_cbranch_scc1 .Lmob_w13_e
	s_cmp_gt_i32 s70, 7
	s_cbranch_scc1 .Lmob_w6_e
	s_cmp_gt_i32 s70, 4
	s_cbranch_scc1 .Lmob_w3_e
	s_cmp_gt_i32 s70, 2
	s_cbranch_scc1 .Lmob_w1_e
	s_waitcnt vmcnt(0)
	s_branch .Lmob_bar_e
.Lmob_w1_e:
	s_waitcnt vmcnt(1)
	s_branch .Lmob_bar_e
.Lmob_w3_e:
	s_waitcnt vmcnt(3)
	s_branch .Lmob_bar_e
.Lmob_w6_e:
	s_waitcnt vmcnt(6)
	s_branch .Lmob_bar_e
.Lmob_w13_e:
	s_waitcnt vmcnt(13)
.Lmob_bar_e:
	s_barrier
	s_cmp_gt_i32 s69, s68
	s_cbranch_scc1 .Lmob_next_e
	s_and_b32 s40, s69, 15
	s_lshl_b32 s40, s40, 13
	s_cmp_eq_u32 s69, s68
	s_cbranch_scc1 .Lmob_last_e
	s_add_i32 s41, s69, 1
	s_and_b32 s41, s41, 15
	s_lshl_b32 s41, s41, 13
	s_cmp_lt_u32 s69, s67
	s_cbranch_scc1 .Lmob_lane_e
	v_add_u32_e32 v103, s41, v216
	ds_read_b128 v[66:69], v103
	v_add_u32_e32 v103, s41, v217
	ds_read_b128 v[70:73], v103
	v_add_u32_e32 v103, s41, v218
	ds_read_b128 v[74:77], v103
	v_add_u32_e32 v103, s41, v219
	ds_read_b128 v[78:81], v103
	v_add_u32_e32 v103, s40, v220
	ds_read_b128 v[104:107], v103 offset:4096
	ds_read_b128 v[108:111], v103 offset:6144
	v_add_u32_e32 v103, s40, v221
	ds_read_b128 v[112:115], v103 offset:4096
	ds_read_b128 v[116:119], v103 offset:6144
	v_max_f32_e32 v99, v35, v35
	v_max_f32_e32 v100, v34, v34
	v_max_f32_e32 v99, v100, v99
	v_max3_f32 v99, v99, v36, v37
	v_max3_f32 v99, v99, v38, v39
	v_max3_f32 v99, v99, v40, v41
	v_max3_f32 v99, v99, v42, v43
	v_max3_f32 v99, v99, v44, v45
	v_max3_f32 v99, v99, v46, v47
	v_max3_f32 v99, v99, v48, v49
	s_waitcnt lgkmcnt(4)
	v_mfma_f32_32x32x16_bf16 v[200:215], v[66:69], v[82:85], 0
	v_mov_b32_e32 v100, v99
	s_nop 1
	v_permlane32_swap_b32_e32 v99, v100
	v_max_f32_e32 v100, v100, v100
	v_max_f32_e32 v99, v99, v99
	v_max_f32_e32 v99, v99, v100
	v_mfma_f32_32x32x16_bf16 v[200:215], v[70:73], v[86:89], v[200:215]
	v_add_f32_e32 v100, 0x42317218, v176
	v_cmp_gt_f32_e32 vcc, v99, v100
	s_cbranch_vccnz .Lmob_rare_fbe
.Lmob_back_fbe:
	v_mul_f32_e32 v98, 0xbe38aa3b, v176
	s_waitcnt lgkmcnt(0)
	v_add_u32_e32 v102, 1, v145
	v_med3_i32 v102, v102, 0, 24
	v_bfm_b32 v102, v102, 0
	v_fmamk_f32 v34, v34, 0x3e38aa3b, v98
	v_fmamk_f32 v35, v35, 0x3e38aa3b, v98
	v_fmamk_f32 v36, v36, 0x3e38aa3b, v98
	v_fmamk_f32 v37, v37, 0x3e38aa3b, v98
	v_fmamk_f32 v38, v38, 0x3e38aa3b, v98
	v_fmamk_f32 v39, v39, 0x3e38aa3b, v98
	v_fmamk_f32 v40, v40, 0x3e38aa3b, v98
	v_fmamk_f32 v41, v41, 0x3e38aa3b, v98
	v_mfma_f32_32x32x16_bf16 v[200:215], v[74:77], v[90:93], v[200:215]
	v_exp_f32_e32 v34, v34
	v_exp_f32_e32 v35, v35
	v_exp_f32_e32 v36, v36
	v_exp_f32_e32 v37, v37
	v_exp_f32_e32 v38, v38
	v_exp_f32_e32 v39, v39
	v_exp_f32_e32 v40, v40
	v_exp_f32_e32 v41, v41
	v_bfe_i32 v244, v102, 0, 1
	v_bfe_i32 v245, v102, 1, 1
	v_bfe_i32 v246, v102, 2, 1
	v_bfe_i32 v247, v102, 3, 1
	v_mfma_f32_32x32x16_bf16 v[200:215], v[78:81], v[94:97], v[200:215]
	v_bfe_i32 v248, v102, 4, 1
	v_bfe_i32 v249, v102, 5, 1
	v_bfe_i32 v250, v102, 6, 1
	v_bfe_i32 v251, v102, 7, 1
	v_and_b32_e32 v34, v244, v34
	v_and_b32_e32 v35, v245, v35
	v_and_b32_e32 v36, v246, v36
	v_and_b32_e32 v37, v247, v37
	v_and_b32_e32 v38, v248, v38
	v_and_b32_e32 v39, v249, v39
	v_and_b32_e32 v40, v250, v40
	v_and_b32_e32 v41, v251, v41
	v_add_f32_e32 v101, v34, v35
	v_add_f32_e32 v101, v101, v36
	v_add_f32_e32 v101, v101, v37
	v_add_f32_e32 v101, v101, v38
	v_add_f32_e32 v101, v101, v39
	v_add_f32_e32 v101, v101, v40
	v_add_f32_e32 v101, v101, v41
	v_cvt_pk_bf16_f32 v224, v34, v35
	v_cvt_pk_bf16_f32 v225, v36, v37
	v_cvt_pk_bf16_f32 v226, v38, v39
	v_cvt_pk_bf16_f32 v227, v40, v41
	v_fmamk_f32 v42, v42, 0x3e38aa3b, v98
	v_fmamk_f32 v43, v43, 0x3e38aa3b, v98
	v_mfma_f32_32x32x16_bf16 v[18:33], v[104:107], v[224:227], v[18:33]
	v_fmamk_f32 v44, v44, 0x3e38aa3b, v98
	v_fmamk_f32 v45, v45, 0x3e38aa3b, v98
	v_fmamk_f32 v46, v46, 0x3e38aa3b, v98
	v_fmamk_f32 v47, v47, 0x3e38aa3b, v98
	v_fmamk_f32 v48, v48, 0x3e38aa3b, v98
	v_fmamk_f32 v49, v49, 0x3e38aa3b, v98
	v_exp_f32_e32 v42, v42
	v_exp_f32_e32 v43, v43
	v_exp_f32_e32 v44, v44
	v_exp_f32_e32 v45, v45
	v_exp_f32_e32 v46, v46
	v_exp_f32_e32 v47, v47
	v_mfma_f32_32x32x16_bf16 v[2:17], v[108:111], v[224:227], v[2:17]
	v_exp_f32_e32 v48, v48
	v_exp_f32_e32 v49, v49
	v_bfe_i32 v244, v102, 16, 1
	v_bfe_i32 v245, v102, 17, 1
	v_bfe_i32 v246, v102, 18, 1
	v_bfe_i32 v247, v102, 19, 1
	v_bfe_i32 v248, v102, 20, 1
	v_bfe_i32 v249, v102, 21, 1
	v_bfe_i32 v250, v102, 22, 1
	v_bfe_i32 v251, v102, 23, 1
	v_and_b32_e32 v42, v244, v42
	v_and_b32_e32 v43, v245, v43
	v_and_b32_e32 v44, v246, v44
	v_and_b32_e32 v45, v247, v45
	v_and_b32_e32 v46, v248, v46
	v_and_b32_e32 v47, v249, v47
	v_and_b32_e32 v48, v250, v48
	v_and_b32_e32 v49, v251, v49
	v_add_f32_e32 v101, v101, v42
	v_add_f32_e32 v101, v101, v43
	v_add_f32_e32 v101, v101, v44
	v_add_f32_e32 v101, v101, v45
	v_add_f32_e32 v101, v101, v46
	v_add_f32_e32 v101, v101, v47
	v_add_f32_e32 v101, v101, v48
	v_add_f32_e32 v101, v101, v49
	v_cvt_pk_bf16_f32 v228, v42, v43
	v_cvt_pk_bf16_f32 v229, v44, v45
	v_cvt_pk_bf16_f32 v230, v46, v47
	v_cvt_pk_bf16_f32 v231, v48, v49
	v_add_f32_e32 v141, v141, v101
	s_nop 0
	v_mfma_f32_32x32x16_bf16 v[18:33], v[112:115], v[228:231], v[18:33]
	v_mfma_f32_32x32x16_bf16 v[2:17], v[116:119], v[228:231], v[2:17]
	s_branch .Lmob_next_e
.Lmob_lane_e:
	v_add_u32_e32 v103, s41, v216
	ds_read_b128 v[66:69], v103
	v_add_u32_e32 v103, s41, v217
	ds_read_b128 v[70:73], v103
	v_add_u32_e32 v103, s41, v218
	ds_read_b128 v[74:77], v103
	v_add_u32_e32 v103, s41, v219
	ds_read_b128 v[78:81], v103
	v_add_u32_e32 v103, s40, v220
	ds_read_b128 v[104:107], v103 offset:4096
	ds_read_b128 v[108:111], v103 offset:6144
	v_add_u32_e32 v103, s40, v221
	ds_read_b128 v[112:115], v103 offset:4096
	ds_read_b128 v[116:119], v103 offset:6144
	v_max_f32_e32 v99, v35, v35
	v_max_f32_e32 v100, v34, v34
	v_max_f32_e32 v99, v100, v99
	v_max3_f32 v99, v99, v36, v37
	v_max3_f32 v99, v99, v38, v39
	v_max3_f32 v99, v99, v40, v41
	v_max3_f32 v99, v99, v42, v43
	v_max3_f32 v99, v99, v44, v45
	v_max3_f32 v99, v99, v46, v47
	v_max3_f32 v99, v99, v48, v49
	s_waitcnt lgkmcnt(4)
	v_mfma_f32_32x32x16_bf16 v[200:215], v[66:69], v[82:85], 0
	v_mov_b32_e32 v100, v99
	s_nop 1
	v_permlane32_swap_b32_e32 v99, v100
	v_max_f32_e32 v100, v100, v100
	v_max_f32_e32 v99, v99, v99
	v_max_f32_e32 v99, v99, v100
	v_mfma_f32_32x32x16_bf16 v[200:215], v[70:73], v[86:89], v[200:215]
	v_add_f32_e32 v100, 0x42317218, v176
	v_cmp_gt_f32_e32 vcc, v99, v100
	s_cbranch_vccnz .Lmob_rare_fle
.Lmob_back_fle:
	v_mul_f32_e32 v98, 0xbe38aa3b, v176
	s_waitcnt lgkmcnt(0)
	s_lshr_b32 s41, s69, 3
	v_bfe_u32 v100, v143, s41, 1
	v_cmp_ne_u32_e32 vcc, 0, v100
	s_nop 1
	v_cndmask_b32_e32 v98, v123, v98, vcc
	v_fmamk_f32 v34, v34, 0x3e38aa3b, v98
	v_fmamk_f32 v35, v35, 0x3e38aa3b, v98
	v_fmamk_f32 v36, v36, 0x3e38aa3b, v98
	v_fmamk_f32 v37, v37, 0x3e38aa3b, v98
	v_fmamk_f32 v38, v38, 0x3e38aa3b, v98
	v_fmamk_f32 v39, v39, 0x3e38aa3b, v98
	v_fmamk_f32 v40, v40, 0x3e38aa3b, v98
	v_fmamk_f32 v41, v41, 0x3e38aa3b, v98
	v_mfma_f32_32x32x16_bf16 v[200:215], v[74:77], v[90:93], v[200:215]
	v_exp_f32_e32 v34, v34
	v_exp_f32_e32 v35, v35
	v_exp_f32_e32 v36, v36
	v_exp_f32_e32 v37, v37
	v_exp_f32_e32 v38, v38
	v_exp_f32_e32 v39, v39
	v_exp_f32_e32 v40, v40
	v_exp_f32_e32 v41, v41
	v_add_f32_e32 v101, v34, v35
	v_add_f32_e32 v101, v101, v36
	v_add_f32_e32 v101, v101, v37
	v_mfma_f32_32x32x16_bf16 v[200:215], v[78:81], v[94:97], v[200:215]
	v_add_f32_e32 v101, v101, v38
	v_add_f32_e32 v101, v101, v39
	v_add_f32_e32 v101, v101, v40
	v_add_f32_e32 v101, v101, v41
	v_cvt_pk_bf16_f32 v224, v34, v35
	v_cvt_pk_bf16_f32 v225, v36, v37
	v_cvt_pk_bf16_f32 v226, v38, v39
	v_cvt_pk_bf16_f32 v227, v40, v41
	v_fmamk_f32 v42, v42, 0x3e38aa3b, v98
	v_fmamk_f32 v43, v43, 0x3e38aa3b, v98
	v_mfma_f32_32x32x16_bf16 v[18:33], v[104:107], v[224:227], v[18:33]
	v_fmamk_f32 v44, v44, 0x3e38aa3b, v98
	v_fmamk_f32 v45, v45, 0x3e38aa3b, v98
	v_fmamk_f32 v46, v46, 0x3e38aa3b, v98
	v_fmamk_f32 v47, v47, 0x3e38aa3b, v98
	v_fmamk_f32 v48, v48, 0x3e38aa3b, v98
	v_fmamk_f32 v49, v49, 0x3e38aa3b, v98
	v_exp_f32_e32 v42, v42
	v_exp_f32_e32 v43, v43
	v_exp_f32_e32 v44, v44
	v_exp_f32_e32 v45, v45
	v_exp_f32_e32 v46, v46
	v_exp_f32_e32 v47, v47
	v_mfma_f32_32x32x16_bf16 v[2:17], v[108:111], v[224:227], v[2:17]
	v_exp_f32_e32 v48, v48
	v_exp_f32_e32 v49, v49
	v_add_f32_e32 v101, v101, v42
	v_add_f32_e32 v101, v101, v43
	v_add_f32_e32 v101, v101, v44
	v_add_f32_e32 v101, v101, v45
	v_add_f32_e32 v101, v101, v46
	v_add_f32_e32 v101, v101, v47
	v_add_f32_e32 v101, v101, v48
	v_add_f32_e32 v101, v101, v49
	v_cvt_pk_bf16_f32 v228, v42, v43
	v_cvt_pk_bf16_f32 v229, v44, v45
	v_cvt_pk_bf16_f32 v230, v46, v47
	v_cvt_pk_bf16_f32 v231, v48, v49
	v_add_f32_e32 v141, v141, v101
	s_nop 0
	v_mfma_f32_32x32x16_bf16 v[18:33], v[112:115], v[228:231], v[18:33]
	v_mfma_f32_32x32x16_bf16 v[2:17], v[116:119], v[228:231], v[2:17]
	s_branch .Lmob_next_e
.Lmob_last_e:
	v_add_u32_e32 v103, s40, v220
	ds_read_b128 v[104:107], v103 offset:4096
	ds_read_b128 v[108:111], v103 offset:6144
	v_add_u32_e32 v103, s40, v221
	ds_read_b128 v[112:115], v103 offset:4096
	ds_read_b128 v[116:119], v103 offset:6144
	v_max_f32_e32 v99, v35, v35
	v_max_f32_e32 v100, v34, v34
	v_max_f32_e32 v99, v100, v99
	v_max3_f32 v99, v99, v36, v37
	v_max3_f32 v99, v99, v38, v39
	v_max3_f32 v99, v99, v40, v41
	v_max3_f32 v99, v99, v42, v43
	v_max3_f32 v99, v99, v44, v45
	v_max3_f32 v99, v99, v46, v47
	v_max3_f32 v99, v99, v48, v49
	v_mov_b32_e32 v100, v99
	s_nop 1
	v_permlane32_swap_b32_e32 v99, v100
	v_max_f32_e32 v100, v100, v100
	v_max_f32_e32 v99, v99, v99
	v_max_f32_e32 v99, v99, v100
	v_add_f32_e32 v100, 0x42317218, v176
	v_cmp_gt_f32_e32 vcc, v99, v100
	s_cbranch_vccnz .Lmob_rare_lbe
.Lmob_back_lbe:
	v_mul_f32_e32 v98, 0xbe38aa3b, v176
	s_waitcnt lgkmcnt(0)
	v_add_u32_e32 v102, 1, v145
	v_med3_i32 v102, v102, 0, 24
	v_bfm_b32 v102, v102, 0
	v_fmamk_f32 v34, v34, 0x3e38aa3b, v98
	v_fmamk_f32 v35, v35, 0x3e38aa3b, v98
	v_fmamk_f32 v36, v36, 0x3e38aa3b, v98
	v_fmamk_f32 v37, v37, 0x3e38aa3b, v98
	v_fmamk_f32 v38, v38, 0x3e38aa3b, v98
	v_fmamk_f32 v39, v39, 0x3e38aa3b, v98
	v_fmamk_f32 v40, v40, 0x3e38aa3b, v98
	v_fmamk_f32 v41, v41, 0x3e38aa3b, v98
	v_exp_f32_e32 v34, v34
	v_exp_f32_e32 v35, v35
	v_exp_f32_e32 v36, v36
	v_exp_f32_e32 v37, v37
	v_exp_f32_e32 v38, v38
	v_exp_f32_e32 v39, v39
	v_exp_f32_e32 v40, v40
	v_exp_f32_e32 v41, v41
	v_bfe_i32 v244, v102, 0, 1
	v_bfe_i32 v245, v102, 1, 1
	v_bfe_i32 v246, v102, 2, 1
	v_bfe_i32 v247, v102, 3, 1
	v_bfe_i32 v248, v102, 4, 1
	v_bfe_i32 v249, v102, 5, 1
	v_bfe_i32 v250, v102, 6, 1
	v_bfe_i32 v251, v102, 7, 1
	v_and_b32_e32 v34, v244, v34
	v_and_b32_e32 v35, v245, v35
	v_and_b32_e32 v36, v246, v36
	v_and_b32_e32 v37, v247, v37
	v_and_b32_e32 v38, v248, v38
	v_and_b32_e32 v39, v249, v39
	v_and_b32_e32 v40, v250, v40
	v_and_b32_e32 v41, v251, v41
	v_add_f32_e32 v101, v34, v35
	v_add_f32_e32 v101, v101, v36
	v_add_f32_e32 v101, v101, v37
	v_add_f32_e32 v101, v101, v38
	v_add_f32_e32 v101, v101, v39
	v_add_f32_e32 v101, v101, v40
	v_add_f32_e32 v101, v101, v41
	v_cvt_pk_bf16_f32 v224, v34, v35
	v_cvt_pk_bf16_f32 v225, v36, v37
	v_cvt_pk_bf16_f32 v226, v38, v39
	v_cvt_pk_bf16_f32 v227, v40, v41
	v_fmamk_f32 v42, v42, 0x3e38aa3b, v98
	v_fmamk_f32 v43, v43, 0x3e38aa3b, v98
	v_mfma_f32_32x32x16_bf16 v[18:33], v[104:107], v[224:227], v[18:33]
	v_fmamk_f32 v44, v44, 0x3e38aa3b, v98
	v_fmamk_f32 v45, v45, 0x3e38aa3b, v98
	v_fmamk_f32 v46, v46, 0x3e38aa3b, v98
	v_fmamk_f32 v47, v47, 0x3e38aa3b, v98
	v_fmamk_f32 v48, v48, 0x3e38aa3b, v98
	v_fmamk_f32 v49, v49, 0x3e38aa3b, v98
	v_exp_f32_e32 v42, v42
	v_exp_f32_e32 v43, v43
	v_exp_f32_e32 v44, v44
	v_exp_f32_e32 v45, v45
	v_exp_f32_e32 v46, v46
	v_exp_f32_e32 v47, v47
	v_mfma_f32_32x32x16_bf16 v[2:17], v[108:111], v[224:227], v[2:17]
	v_exp_f32_e32 v48, v48
	v_exp_f32_e32 v49, v49
	v_bfe_i32 v244, v102, 16, 1
	v_bfe_i32 v245, v102, 17, 1
	v_bfe_i32 v246, v102, 18, 1
	v_bfe_i32 v247, v102, 19, 1
	v_bfe_i32 v248, v102, 20, 1
	v_bfe_i32 v249, v102, 21, 1
	v_bfe_i32 v250, v102, 22, 1
	v_bfe_i32 v251, v102, 23, 1
	v_and_b32_e32 v42, v244, v42
	v_and_b32_e32 v43, v245, v43
	v_and_b32_e32 v44, v246, v44
	v_and_b32_e32 v45, v247, v45
	v_and_b32_e32 v46, v248, v46
	v_and_b32_e32 v47, v249, v47
	v_and_b32_e32 v48, v250, v48
	v_and_b32_e32 v49, v251, v49
	v_add_f32_e32 v101, v101, v42
	v_add_f32_e32 v101, v101, v43
	v_add_f32_e32 v101, v101, v44
	v_add_f32_e32 v101, v101, v45
	v_add_f32_e32 v101, v101, v46
	v_add_f32_e32 v101, v101, v47
	v_add_f32_e32 v101, v101, v48
	v_add_f32_e32 v101, v101, v49
	v_cvt_pk_bf16_f32 v228, v42, v43
	v_cvt_pk_bf16_f32 v229, v44, v45
	v_cvt_pk_bf16_f32 v230, v46, v47
	v_cvt_pk_bf16_f32 v231, v48, v49
	v_add_f32_e32 v141, v141, v101
	s_nop 0
	v_mfma_f32_32x32x16_bf16 v[18:33], v[112:115], v[228:231], v[18:33]
	v_mfma_f32_32x32x16_bf16 v[2:17], v[116:119], v[228:231], v[2:17]

.Lmob_bar_o:
	s_barrier
	s_cmp_gt_i32 s69, s68
	s_cbranch_scc1 .Lmob_next_o
	s_and_b32 s40, s69, 15
	s_lshl_b32 s40, s40, 13
	s_cmp_eq_u32 s69, s68
	s_cbranch_scc1 .Lmob_last_o
	s_add_i32 s41, s69, 1
	s_and_b32 s41, s41, 15
	s_lshl_b32 s41, s41, 13
	s_cmp_lt_u32 s69, s67
	s_cbranch_scc1 .Lmob_lane_o
	v_add_u32_e32 v103, s41, v216
	ds_read_b128 v[66:69], v103
	v_add_u32_e32 v103, s41, v217
	ds_read_b128 v[70:73], v103
	v_add_u32_e32 v103, s41, v218
	ds_read_b128 v[74:77], v103
	v_add_u32_e32 v103, s41, v219
	ds_read_b128 v[78:81], v103
	v_add_u32_e32 v103, s40, v220
	ds_read_b128 v[104:107], v103 offset:4096
	ds_read_b128 v[108:111], v103 offset:6144
	v_add_u32_e32 v103, s40, v221
	ds_read_b128 v[112:115], v103 offset:4096
	ds_read_b128 v[116:119], v103 offset:6144
	v_max_f32_e32 v99, v201, v201
	v_max_f32_e32 v100, v200, v200
	v_max_f32_e32 v99, v100, v99
	v_max3_f32 v99, v99, v202, v203
	v_max3_f32 v99, v99, v204, v205
	v_max3_f32 v99, v99, v206, v207
	v_max3_f32 v99, v99, v208, v209
	v_max3_f32 v99, v99, v210, v211
	v_max3_f32 v99, v99, v212, v213
	v_max3_f32 v99, v99, v214, v215
	s_waitcnt lgkmcnt(4)
	v_mfma_f32_32x32x16_bf16 v[34:49], v[66:69], v[82:85], 0
	v_mov_b32_e32 v100, v99
	s_nop 1
	v_permlane32_swap_b32_e32 v99, v100
	v_max_f32_e32 v100, v100, v100
	v_max_f32_e32 v99, v99, v99
	v_max_f32_e32 v99, v99, v100
	v_mfma_f32_32x32x16_bf16 v[34:49], v[70:73], v[86:89], v[34:49]
	v_add_f32_e32 v100, 0x42317218, v176
	v_cmp_gt_f32_e32 vcc, v99, v100
	s_cbranch_vccnz .Lmob_rare_fbo
.Lmob_back_fbo:
	v_mul_f32_e32 v98, 0xbe38aa3b, v176
	s_waitcnt lgkmcnt(0)
	v_add_u32_e32 v102, 1, v145
	v_med3_i32 v102, v102, 0, 24
	v_bfm_b32 v102, v102, 0
	v_fmamk_f32 v200, v200, 0x3e38aa3b, v98
	v_fmamk_f32 v201, v201, 0x3e38aa3b, v98
	v_fmamk_f32 v202, v202, 0x3e38aa3b, v98
	v_fmamk_f32 v203, v203, 0x3e38aa3b, v98
	v_fmamk_f32 v204, v204, 0x3e38aa3b, v98
	v_fmamk_f32 v205, v205, 0x3e38aa3b, v98
	v_fmamk_f32 v206, v206, 0x3e38aa3b, v98
	v_fmamk_f32 v207, v207, 0x3e38aa3b, v98
	v_mfma_f32_32x32x16_bf16 v[34:49], v[74:77], v[90:93], v[34:49]
	v_exp_f32_e32 v200, v200
	v_exp_f32_e32 v201, v201
	v_exp_f32_e32 v202, v202
	v_exp_f32_e32 v203, v203
	v_exp_f32_e32 v204, v204
	v_exp_f32_e32 v205, v205
	v_exp_f32_e32 v206, v206
	v_exp_f32_e32 v207, v207
	v_bfe_i32 v244, v102, 0, 1
	v_bfe_i32 v245, v102, 1, 1
	v_bfe_i32 v246, v102, 2, 1
	v_bfe_i32 v247, v102, 3, 1
	v_mfma_f32_32x32x16_bf16 v[34:49], v[78:81], v[94:97], v[34:49]
	v_bfe_i32 v248, v102, 4, 1
	v_bfe_i32 v249, v102, 5, 1
	v_bfe_i32 v250, v102, 6, 1
	v_bfe_i32 v251, v102, 7, 1
	v_and_b32_e32 v200, v244, v200
	v_and_b32_e32 v201, v245, v201
	v_and_b32_e32 v202, v246, v202
	v_and_b32_e32 v203, v247, v203
	v_and_b32_e32 v204, v248, v204
	v_and_b32_e32 v205, v249, v205
	v_and_b32_e32 v206, v250, v206
	v_and_b32_e32 v207, v251, v207
	v_add_f32_e32 v101, v200, v201
	v_add_f32_e32 v101, v101, v202
	v_add_f32_e32 v101, v101, v203
	v_add_f32_e32 v101, v101, v204
	v_add_f32_e32 v101, v101, v205
	v_add_f32_e32 v101, v101, v206
	v_add_f32_e32 v101, v101, v207
	v_cvt_pk_bf16_f32 v224, v200, v201
	v_cvt_pk_bf16_f32 v225, v202, v203
	v_cvt_pk_bf16_f32 v226, v204, v205
	v_cvt_pk_bf16_f32 v227, v206, v207
	v_fmamk_f32 v208, v208, 0x3e38aa3b, v98
	v_fmamk_f32 v209, v209, 0x3e38aa3b, v98
	v_mfma_f32_32x32x16_bf16 v[18:33], v[104:107], v[224:227], v[18:33]
	v_fmamk_f32 v210, v210, 0x3e38aa3b, v98
	v_fmamk_f32 v211, v211, 0x3e38aa3b, v98
	v_fmamk_f32 v212, v212, 0x3e38aa3b, v98
	v_fmamk_f32 v213, v213, 0x3e38aa3b, v98
	v_fmamk_f32 v214, v214, 0x3e38aa3b, v98
	v_fmamk_f32 v215, v215, 0x3e38aa3b, v98
	v_exp_f32_e32 v208, v208
	v_exp_f32_e32 v209, v209
	v_exp_f32_e32 v210, v210
	v_exp_f32_e32 v211, v211
	v_exp_f32_e32 v212, v212
	v_exp_f32_e32 v213, v213
	v_mfma_f32_32x32x16_bf16 v[2:17], v[108:111], v[224:227], v[2:17]
	v_exp_f32_e32 v214, v214
	v_exp_f32_e32 v215, v215
	v_bfe_i32 v244, v102, 16, 1
	v_bfe_i32 v245, v102, 17, 1
	v_bfe_i32 v246, v102, 18, 1
	v_bfe_i32 v247, v102, 19, 1
	v_bfe_i32 v248, v102, 20, 1
	v_bfe_i32 v249, v102, 21, 1
	v_bfe_i32 v250, v102, 22, 1
	v_bfe_i32 v251, v102, 23, 1
	v_and_b32_e32 v208, v244, v208
	v_and_b32_e32 v209, v245, v209
	v_and_b32_e32 v210, v246, v210
	v_and_b32_e32 v211, v247, v211
	v_and_b32_e32 v212, v248, v212
	v_and_b32_e32 v213, v249, v213
	v_and_b32_e32 v214, v250, v214
	v_and_b32_e32 v215, v251, v215
	v_add_f32_e32 v101, v101, v208
	v_add_f32_e32 v101, v101, v209
	v_add_f32_e32 v101, v101, v210
	v_add_f32_e32 v101, v101, v211
	v_add_f32_e32 v101, v101, v212
	v_add_f32_e32 v101, v101, v213
	v_add_f32_e32 v101, v101, v214
	v_add_f32_e32 v101, v101, v215
	v_cvt_pk_bf16_f32 v228, v208, v209
	v_cvt_pk_bf16_f32 v229, v210, v211
	v_cvt_pk_bf16_f32 v230, v212, v213
	v_cvt_pk_bf16_f32 v231, v214, v215
	v_add_f32_e32 v141, v141, v101
	s_nop 0
	v_mfma_f32_32x32x16_bf16 v[18:33], v[112:115], v[228:231], v[18:33]
	v_mfma_f32_32x32x16_bf16 v[2:17], v[116:119], v[228:231], v[2:17]
	s_branch .Lmob_next_o
.Lmob_lane_o:
	v_add_u32_e32 v103, s41, v216
	ds_read_b128 v[66:69], v103
	v_add_u32_e32 v103, s41, v217
	ds_read_b128 v[70:73], v103
	v_add_u32_e32 v103, s41, v218
	ds_read_b128 v[74:77], v103
	v_add_u32_e32 v103, s41, v219
	ds_read_b128 v[78:81], v103
	v_add_u32_e32 v103, s40, v220
	ds_read_b128 v[104:107], v103 offset:4096
	ds_read_b128 v[108:111], v103 offset:6144
	v_add_u32_e32 v103, s40, v221
	ds_read_b128 v[112:115], v103 offset:4096
	ds_read_b128 v[116:119], v103 offset:6144
	v_max_f32_e32 v99, v201, v201
	v_max_f32_e32 v100, v200, v200
	v_max_f32_e32 v99, v100, v99
	v_max3_f32 v99, v99, v202, v203
	v_max3_f32 v99, v99, v204, v205
	v_max3_f32 v99, v99, v206, v207
	v_max3_f32 v99, v99, v208, v209
	v_max3_f32 v99, v99, v210, v211
	v_max3_f32 v99, v99, v212, v213
	v_max3_f32 v99, v99, v214, v215
	s_waitcnt lgkmcnt(4)
	v_mfma_f32_32x32x16_bf16 v[34:49], v[66:69], v[82:85], 0
	v_mov_b32_e32 v100, v99
	s_nop 1
	v_permlane32_swap_b32_e32 v99, v100
	v_max_f32_e32 v100, v100, v100
	v_max_f32_e32 v99, v99, v99
	v_max_f32_e32 v99, v99, v100
	v_mfma_f32_32x32x16_bf16 v[34:49], v[70:73], v[86:89], v[34:49]
	v_add_f32_e32 v100, 0x42317218, v176
	v_cmp_gt_f32_e32 vcc, v99, v100
	s_cbranch_vccnz .Lmob_rare_flo
.Lmob_back_flo:
	v_mul_f32_e32 v98, 0xbe38aa3b, v176
	s_waitcnt lgkmcnt(0)
	s_lshr_b32 s41, s69, 3
	v_bfe_u32 v100, v143, s41, 1
	v_cmp_ne_u32_e32 vcc, 0, v100
	s_nop 1
	v_cndmask_b32_e32 v98, v123, v98, vcc
	v_fmamk_f32 v200, v200, 0x3e38aa3b, v98
	v_fmamk_f32 v201, v201, 0x3e38aa3b, v98
	v_fmamk_f32 v202, v202, 0x3e38aa3b, v98
	v_fmamk_f32 v203, v203, 0x3e38aa3b, v98
	v_fmamk_f32 v204, v204, 0x3e38aa3b, v98
	v_fmamk_f32 v205, v205, 0x3e38aa3b, v98
	v_fmamk_f32 v206, v206, 0x3e38aa3b, v98
	v_fmamk_f32 v207, v207, 0x3e38aa3b, v98
	v_mfma_f32_32x32x16_bf16 v[34:49], v[74:77], v[90:93], v[34:49]
	v_exp_f32_e32 v200, v200
	v_exp_f32_e32 v201, v201
	v_exp_f32_e32 v202, v202
	v_exp_f32_e32 v203, v203
	v_exp_f32_e32 v204, v204
	v_exp_f32_e32 v205, v205
	v_exp_f32_e32 v206, v206
	v_exp_f32_e32 v207, v207
	v_add_f32_e32 v101, v200, v201
	v_add_f32_e32 v101, v101, v202
	v_add_f32_e32 v101, v101, v203
	v_mfma_f32_32x32x16_bf16 v[34:49], v[78:81], v[94:97], v[34:49]
	v_add_f32_e32 v101, v101, v204
	v_add_f32_e32 v101, v101, v205
	v_add_f32_e32 v101, v101, v206
	v_add_f32_e32 v101, v101, v207
	v_cvt_pk_bf16_f32 v224, v200, v201
	v_cvt_pk_bf16_f32 v225, v202, v203
	v_cvt_pk_bf16_f32 v226, v204, v205
	v_cvt_pk_bf16_f32 v227, v206, v207
	v_fmamk_f32 v208, v208, 0x3e38aa3b, v98
	v_fmamk_f32 v209, v209, 0x3e38aa3b, v98
	v_mfma_f32_32x32x16_bf16 v[18:33], v[104:107], v[224:227], v[18:33]
	v_fmamk_f32 v210, v210, 0x3e38aa3b, v98
	v_fmamk_f32 v211, v211, 0x3e38aa3b, v98
	v_fmamk_f32 v212, v212, 0x3e38aa3b, v98
	v_fmamk_f32 v213, v213, 0x3e38aa3b, v98
	v_fmamk_f32 v214, v214, 0x3e38aa3b, v98
	v_fmamk_f32 v215, v215, 0x3e38aa3b, v98
	v_exp_f32_e32 v208, v208
	v_exp_f32_e32 v209, v209
	v_exp_f32_e32 v210, v210
	v_exp_f32_e32 v211, v211
	v_exp_f32_e32 v212, v212
	v_exp_f32_e32 v213, v213
	v_mfma_f32_32x32x16_bf16 v[2:17], v[108:111], v[224:227], v[2:17]
	v_exp_f32_e32 v214, v214
	v_exp_f32_e32 v215, v215
	v_add_f32_e32 v101, v101, v208
	v_add_f32_e32 v101, v101, v209
	v_add_f32_e32 v101, v101, v210
	v_add_f32_e32 v101, v101, v211
	v_add_f32_e32 v101, v101, v212
	v_add_f32_e32 v101, v101, v213
	v_add_f32_e32 v101, v101, v214
	v_add_f32_e32 v101, v101, v215
	v_cvt_pk_bf16_f32 v228, v208, v209
	v_cvt_pk_bf16_f32 v229, v210, v211
	v_cvt_pk_bf16_f32 v230, v212, v213
	v_cvt_pk_bf16_f32 v231, v214, v215
	v_add_f32_e32 v141, v141, v101
	s_nop 0
	v_mfma_f32_32x32x16_bf16 v[18:33], v[112:115], v[228:231], v[18:33]
	v_mfma_f32_32x32x16_bf16 v[2:17], v[116:119], v[228:231], v[2:17]
	s_branch .Lmob_next_o
.Lmob_last_o:
	v_add_u32_e32 v103, s40, v220
	ds_read_b128 v[104:107], v103 offset:4096
	ds_read_b128 v[108:111], v103 offset:6144
	v_add_u32_e32 v103, s40, v221
	ds_read_b128 v[112:115], v103 offset:4096
	ds_read_b128 v[116:119], v103 offset:6144
	v_max_f32_e32 v99, v201, v201
	v_max_f32_e32 v100, v200, v200
	v_max_f32_e32 v99, v100, v99
	v_max3_f32 v99, v99, v202, v203
	v_max3_f32 v99, v99, v204, v205
	v_max3_f32 v99, v99, v206, v207
	v_max3_f32 v99, v99, v208, v209
	v_max3_f32 v99, v99, v210, v211
	v_max3_f32 v99, v99, v212, v213
	v_max3_f32 v99, v99, v214, v215
	v_mov_b32_e32 v100, v99
	s_nop 1
	v_permlane32_swap_b32_e32 v99, v100
	v_max_f32_e32 v100, v100, v100
	v_max_f32_e32 v99, v99, v99
	v_max_f32_e32 v99, v99, v100
	v_add_f32_e32 v100, 0x42317218, v176
	v_cmp_gt_f32_e32 vcc, v99, v100
	s_cbranch_vccnz .Lmob_rare_lbo
.Lmob_back_lbo:
	v_mul_f32_e32 v98, 0xbe38aa3b, v176
	s_waitcnt lgkmcnt(0)
	v_add_u32_e32 v102, 1, v145
	v_med3_i32 v102, v102, 0, 24
	v_bfm_b32 v102, v102, 0
	v_fmamk_f32 v200, v200, 0x3e38aa3b, v98
	v_fmamk_f32 v201, v201, 0x3e38aa3b, v98
	v_fmamk_f32 v202, v202, 0x3e38aa3b, v98
	v_fmamk_f32 v203, v203, 0x3e38aa3b, v98
	v_fmamk_f32 v204, v204, 0x3e38aa3b, v98
	v_fmamk_f32 v205, v205, 0x3e38aa3b, v98
	v_fmamk_f32 v206, v206, 0x3e38aa3b, v98
	v_fmamk_f32 v207, v207, 0x3e38aa3b, v98
	v_exp_f32_e32 v200, v200
	v_exp_f32_e32 v201, v201
	v_exp_f32_e32 v202, v202
	v_exp_f32_e32 v203, v203
	v_exp_f32_e32 v204, v204
	v_exp_f32_e32 v205, v205
	v_exp_f32_e32 v206, v206
	v_exp_f32_e32 v207, v207
	v_bfe_i32 v244, v102, 0, 1
	v_bfe_i32 v245, v102, 1, 1
	v_bfe_i32 v246, v102, 2, 1
	v_bfe_i32 v247, v102, 3, 1
	v_bfe_i32 v248, v102, 4, 1
	v_bfe_i32 v249, v102, 5, 1
	v_bfe_i32 v250, v102, 6, 1
	v_bfe_i32 v251, v102, 7, 1
	v_and_b32_e32 v200, v244, v200
	v_and_b32_e32 v201, v245, v201
	v_and_b32_e32 v202, v246, v202
	v_and_b32_e32 v203, v247, v203
	v_and_b32_e32 v204, v248, v204
	v_and_b32_e32 v205, v249, v205
	v_and_b32_e32 v206, v250, v206
	v_and_b32_e32 v207, v251, v207
	v_add_f32_e32 v101, v200, v201
	v_add_f32_e32 v101, v101, v202
	v_add_f32_e32 v101, v101, v203
	v_add_f32_e32 v101, v101, v204
	v_add_f32_e32 v101, v101, v205
	v_add_f32_e32 v101, v101, v206
	v_add_f32_e32 v101, v101, v207
	v_cvt_pk_bf16_f32 v224, v200, v201
	v_cvt_pk_bf16_f32 v225, v202, v203
	v_cvt_pk_bf16_f32 v226, v204, v205
	v_cvt_pk_bf16_f32 v227, v206, v207
	v_fmamk_f32 v208, v208, 0x3e38aa3b, v98
	v_fmamk_f32 v209, v209, 0x3e38aa3b, v98
	v_mfma_f32_32x32x16_bf16 v[18:33], v[104:107], v[224:227], v[18:33]
	v_fmamk_f32 v210, v210, 0x3e38aa3b, v98
	v_fmamk_f32 v211, v211, 0x3e38aa3b, v98
	v_fmamk_f32 v212, v212, 0x3e38aa3b, v98
	v_fmamk_f32 v213, v213, 0x3e38aa3b, v98
	v_fmamk_f32 v214, v214, 0x3e38aa3b, v98
	v_fmamk_f32 v215, v215, 0x3e38aa3b, v98
	v_exp_f32_e32 v208, v208
	v_exp_f32_e32 v209, v209
	v_exp_f32_e32 v210, v210
	v_exp_f32_e32 v211, v211
	v_exp_f32_e32 v212, v212
	v_exp_f32_e32 v213, v213
	v_mfma_f32_32x32x16_bf16 v[2:17], v[108:111], v[224:227], v[2:17]
	v_exp_f32_e32 v214, v214
	v_exp_f32_e32 v215, v215
	v_bfe_i32 v244, v102, 16, 1
	v_bfe_i32 v245, v102, 17, 1
	v_bfe_i32 v246, v102, 18, 1
	v_bfe_i32 v247, v102, 19, 1
	v_bfe_i32 v248, v102, 20, 1
	v_bfe_i32 v249, v102, 21, 1
	v_bfe_i32 v250, v102, 22, 1
	v_bfe_i32 v251, v102, 23, 1
	v_and_b32_e32 v208, v244, v208
	v_and_b32_e32 v209, v245, v209
	v_and_b32_e32 v210, v246, v210
	v_and_b32_e32 v211, v247, v211
	v_and_b32_e32 v212, v248, v212
	v_and_b32_e32 v213, v249, v213
	v_and_b32_e32 v214, v250, v214
	v_and_b32_e32 v215, v251, v215
	v_add_f32_e32 v101, v101, v208
	v_add_f32_e32 v101, v101, v209
	v_add_f32_e32 v101, v101, v210
	v_add_f32_e32 v101, v101, v211
	v_add_f32_e32 v101, v101, v212
	v_add_f32_e32 v101, v101, v213
	v_add_f32_e32 v101, v101, v214
	v_add_f32_e32 v101, v101, v215
	v_cvt_pk_bf16_f32 v228, v208, v209
	v_cvt_pk_bf16_f32 v229, v210, v211
	v_cvt_pk_bf16_f32 v230, v212, v213
	v_cvt_pk_bf16_f32 v231, v214, v215
	v_add_f32_e32 v141, v141, v101
	s_nop 0
	v_mfma_f32_32x32x16_bf16 v[18:33], v[112:115], v[228:231], v[18:33]
	v_mfma_f32_32x32x16_bf16 v[2:17], v[116:119], v[228:231], v[2:17]
.Lmob_next_o:
	s_add_i32 s69, s69, 1
	s_add_i32 s70, s70, -1
	v_subrev_u32_e32 v145, 32, v145
	s_cmp_lg_u32 s70, -1
	v_lshl_add_u64 v[146:147], v[146:147], 0, s[20:21]
	s_cbranch_scc0 .LBB0_836
	s_branch .Lmob_top_e
.Lmob_rare_fbe:
	s_nop 15
	s_nop 15
	v_cndmask_b32_e32 v100, v176, v99, vcc
	v_sub_f32_e32 v120, v176, v100
	v_mul_f32_e32 v120, 0x3e38aa3b, v120
	v_exp_f32_e32 v120, v120
	v_mov_b32_e32 v176, v100
	v_mul_f32_e32 v141, v141, v120
	v_pk_mul_f32 v[32:33], v[32:33], v[120:121] op_sel_hi:[1,0]
	v_pk_mul_f32 v[30:31], v[30:31], v[120:121] op_sel_hi:[1,0]
	v_pk_mul_f32 v[28:29], v[28:29], v[120:121] op_sel_hi:[1,0]
	v_pk_mul_f32 v[26:27], v[26:27], v[120:121] op_sel_hi:[1,0]
	v_pk_mul_f32 v[24:25], v[24:25], v[120:121] op_sel_hi:[1,0]
	v_pk_mul_f32 v[22:23], v[22:23], v[120:121] op_sel_hi:[1,0]
	v_pk_mul_f32 v[20:21], v[20:21], v[120:121] op_sel_hi:[1,0]
	v_pk_mul_f32 v[18:19], v[18:19], v[120:121] op_sel_hi:[1,0]
	v_pk_mul_f32 v[16:17], v[16:17], v[120:121] op_sel_hi:[1,0]
	v_pk_mul_f32 v[14:15], v[14:15], v[120:121] op_sel_hi:[1,0]
	v_pk_mul_f32 v[12:13], v[12:13], v[120:121] op_sel_hi:[1,0]
	v_pk_mul_f32 v[10:11], v[10:11], v[120:121] op_sel_hi:[1,0]
	v_pk_mul_f32 v[8:9], v[8:9], v[120:121] op_sel_hi:[1,0]
	v_pk_mul_f32 v[6:7], v[6:7], v[120:121] op_sel_hi:[1,0]
	v_pk_mul_f32 v[4:5], v[4:5], v[120:121] op_sel_hi:[1,0]
	v_pk_mul_f32 v[2:3], v[2:3], v[120:121] op_sel_hi:[1,0]
	s_branch .Lmob_back_fbe

.LBB0_842:
	s_mul_i32 s40, s48, 43
	s_sext_i32_i16 s41, s40
	s_ashr_i32 s41, s41, 9
	s_bfe_u32 s40, s40, 0x1000f
	s_add_i32 s41, s41, s40
	s_sext_i32_i16 s40, s41
	v_lshrrev_b32_e32 v0, 4, v0
	s_lshl_b32 s41, s49, 1
	s_lshl_b32 s49, s40, 12
	s_lshl_b32 s40, s66, 8
	v_xor_b32_e32 v0, v0, v242
	s_add_i32 s40, s49, s40
	v_lshlrev_b32_e32 v0, 4, v0
	v_add_u32_e32 v4, s40, v164
	v_and_b32_e32 v0, s41, v0
	v_ashrrev_i32_e32 v5, 31, v4
	s_mov_b32 m0, s29
	v_lshl_add_u64 v[2:3], v[2:3], 0, v[0:1]
	v_lshlrev_b64 v[4:5], 9, v[4:5]
	s_add_i32 s40, s54, 0
	v_lshl_add_u64 v[4:5], s[44:45], 0, v[4:5]
	s_waitcnt vmcnt(0)
	s_barrier
	s_add_i32 s52, s68, 8
	s_cmp_gt_u32 s1, 3
	s_cbranch_scc1 .Ldsa_pm0
	s_add_i32 m0, s18, 0x20020
	s_nop 0
	global_load_lds_dwordx4 v[4:5], off
.Ldsa_pm0:
	s_mov_b32 m0, s18
	s_nop 0
	global_load_lds_dwordx4 v[2:3], off
	s_cmp_gt_u32 s1, 3
	s_cbranch_scc1 .Ldsa_pm1
	v_lshl_add_u64 v[6:7], v[4:5], 0, 16
	s_add_i32 m0, s18, 0x21020
	s_nop 0
	global_load_lds_dwordx4 v[6:7], off
	v_lshl_add_u64 v[6:7], v[4:5], 0, 32
	s_add_i32 m0, s18, 0x22020
	s_nop 0
	global_load_lds_dwordx4 v[6:7], off
.Ldsa_pm1:
	v_lshl_add_u64 v[84:85], v[4:5], 0, 48
	v_mov_b64_e32 v[6:7], v[2:3]
	v_lshl_add_u64 v[6:7], v[6:7], 0, s[20:21]
	s_add_i32 m0, s18, 0x2000
	s_nop 0
	global_load_lds_dwordx4 v[6:7], off
	v_lshl_add_u64 v[6:7], v[6:7], 0, s[20:21]
	s_add_i32 m0, s18, 0x4000
	s_nop 0
	global_load_lds_dwordx4 v[6:7], off
	v_lshl_add_u64 v[6:7], v[6:7], 0, s[20:21]
	s_add_i32 m0, s18, 0x6000
	s_nop 0
	global_load_lds_dwordx4 v[6:7], off
	v_lshl_add_u64 v[6:7], v[6:7], 0, s[20:21]
	s_add_i32 m0, s18, 0x8000
	s_nop 0
	global_load_lds_dwordx4 v[6:7], off
	v_lshl_add_u64 v[6:7], v[6:7], 0, s[20:21]
	s_add_i32 m0, s18, 0xa000
	s_nop 0
	global_load_lds_dwordx4 v[6:7], off
	v_lshl_add_u64 v[6:7], v[6:7], 0, s[20:21]
	s_add_i32 m0, s18, 0xc000
	s_nop 0
	global_load_lds_dwordx4 v[6:7], off
	v_lshl_add_u64 v[6:7], v[6:7], 0, s[20:21]
	s_add_i32 m0, s18, 0xe000
	s_nop 0
	global_load_lds_dwordx4 v[6:7], off
	s_cmp_eq_u32 s68, 0
	s_cbranch_scc1 .Ldsa_pk8
	v_lshl_add_u64 v[6:7], v[6:7], 0, s[20:21]
	s_add_i32 m0, s18, 0x10000
	s_nop 0
	global_load_lds_dwordx4 v[6:7], off
	v_lshl_add_u64 v[6:7], v[6:7], 0, s[20:21]
	s_add_i32 m0, s18, 0x12000
	s_nop 0
	global_load_lds_dwordx4 v[6:7], off
	v_lshl_add_u64 v[6:7], v[6:7], 0, s[20:21]
	s_add_i32 m0, s18, 0x14000
	s_nop 0
	global_load_lds_dwordx4 v[6:7], off
	v_lshl_add_u64 v[6:7], v[6:7], 0, s[20:21]
	s_add_i32 m0, s18, 0x16000
	s_nop 0
	global_load_lds_dwordx4 v[6:7], off
	v_lshl_add_u64 v[6:7], v[6:7], 0, s[20:21]
	s_add_i32 m0, s18, 0x18000
	s_nop 0
	global_load_lds_dwordx4 v[6:7], off
	v_lshl_add_u64 v[6:7], v[6:7], 0, s[20:21]
	s_add_i32 m0, s18, 0x1a000
	s_nop 0
	global_load_lds_dwordx4 v[6:7], off
.Ldsa_pk8:
	s_mov_b64 s[40:41], 0xe000
	v_lshl_add_u64 v[86:87], v[2:3], 0, s[40:41]
	s_add_i32 s53, s68, 7
	s_mov_b32 s65, 0
	v_mov_b32_e32 v0, 0
	v_mov_b64_e32 v[2:3], v[0:1]
	v_mov_b64_e32 v[4:5], v[0:1]
	v_mov_b64_e32 v[6:7], v[0:1]
	v_mov_b64_e32 v[8:9], v[0:1]
	v_mov_b64_e32 v[10:11], v[0:1]
	v_mov_b64_e32 v[12:13], v[0:1]
	v_mov_b64_e32 v[14:15], v[0:1]
	v_mov_b64_e32 v[16:17], v[0:1]
	v_mov_b64_e32 v[18:19], v[0:1]
	v_mov_b64_e32 v[20:21], v[0:1]
	v_mov_b64_e32 v[22:23], v[0:1]
	v_mov_b64_e32 v[24:25], v[0:1]
	v_mov_b64_e32 v[26:27], v[0:1]
	v_mov_b64_e32 v[28:29], v[0:1]
	v_mov_b64_e32 v[30:31], v[0:1]
	v_mov_b64_e32 v[32:33], v[0:1]
	v_mov_b32_e32 v83, 0xf149f2ca
	v_mov_b32_e32 v141, 0
	v_add_u32_e32 v216, v166, v165
	v_add_u32_e32 v217, v167, v165
	v_add_u32_e32 v218, v168, v165
	v_add_u32_e32 v219, v169, v165
	v_add_u32_e32 v220, v170, v171
	v_add_u32_e32 v221, v170, v172
	v_lshl_add_u32 v222, s1, 5, v135
	v_lshlrev_b32_e32 v222, 4, v222
	s_cmp_eq_u32 s52, 8
	s_cbranch_scc1 .Ldsa_pw7
	s_waitcnt vmcnt(13)
	s_branch .Ldsa_pbar

.Ldsa_pbar:
	s_barrier
	ds_read_b128 v[66:69], v216
	ds_read_b128 v[70:73], v217
	ds_read_b128 v[74:77], v218
	ds_read_b128 v[78:81], v219
	s_waitcnt lgkmcnt(0)
	v_mfma_f32_32x32x16_bf16 v[34:49], v[66:69], v[50:53], 0
	v_mfma_f32_32x32x16_bf16 v[34:49], v[70:73], v[54:57], v[34:49]
	v_mfma_f32_32x32x16_bf16 v[34:49], v[74:77], v[58:61], v[34:49]
	v_mfma_f32_32x32x16_bf16 v[34:49], v[78:81], v[62:65], v[34:49]
.Ldsa_top_e:
	s_add_i32 s40, s65, 14
	s_cmp_ge_u32 s40, s52
	s_cbranch_scc1 .Ldsa_noissue_e
	s_and_b32 s40, s40, 15
	s_lshl_b32 s40, s40, 13
	s_add_i32 m0, s40, s18
	s_nop 0
	global_load_lds_dwordx4 v[86:87], off
.Ldsa_noissue_e:
	s_cmp_gt_i32 s53, 13
	s_cbranch_scc1 .Ldsa_w13_e
	s_cmp_gt_i32 s53, 7
	s_cbranch_scc1 .Ldsa_w6_e
	s_cmp_gt_i32 s53, 4
	s_cbranch_scc1 .Ldsa_w3_e
	s_cmp_gt_i32 s53, 2
	s_cbranch_scc1 .Ldsa_w1_e
	s_waitcnt vmcnt(0)
	s_branch .Ldsa_bar_e

.Ldsa_bar_e:
	s_barrier
	s_and_b32 s41, s65, 3
	s_cmp_eq_u32 s41, 0
	s_cbranch_scc0 .Ldsa_nomask
	s_cmp_gt_u32 s1, 3
	s_cbranch_scc1 .Ldsa_nomask
	s_add_i32 s41, s65, 12
	s_cmp_ge_u32 s41, s52
	s_cbranch_scc1 .Ldsa_nomask
	s_lshl_b32 s41, s41, 10
	s_and_b32 s41, s41, 0x3000
	s_add_i32 s41, s41, 0x20020
	s_add_i32 m0, s41, s18
	s_nop 0
	global_load_lds_dwordx4 v[84:85], off
	v_lshl_add_u64 v[84:85], v[84:85], 0, 16
.Ldsa_nomask:
	s_cmp_gt_i32 s65, s67
	s_cbranch_scc1 .Ldsa_next_e
	s_and_b32 s40, s65, 15
	s_lshl_b32 s40, s40, 13
	s_lshl_b32 s66, s65, 10
	s_and_b32 s66, s66, 0x3000
	s_and_b32 s41, s65, 3
	s_lshl_b32 s41, s41, 2
	s_add_i32 s66, s66, s41
	s_add_i32 s66, s66, 0x20020
	s_cmp_eq_u32 s65, s67
	s_cbranch_scc1 .Ldsa_last_e
	s_add_i32 s41, s65, 1
	s_and_b32 s41, s41, 15
	s_lshl_b32 s41, s41, 13
	v_add_u32_e32 v125, s41, v216
	ds_read_b128 v[66:69], v125
	v_add_u32_e32 v125, s41, v217
	ds_read_b128 v[70:73], v125
	v_add_u32_e32 v125, s41, v218
	ds_read_b128 v[74:77], v125
	v_add_u32_e32 v125, s41, v219
	ds_read_b128 v[78:81], v125
	v_add_u32_e32 v125, s40, v220
	ds_read_b128 v[104:107], v125 offset:4096
	ds_read_b128 v[108:111], v125 offset:6144
	v_add_u32_e32 v125, s40, v221
	ds_read_b128 v[112:115], v125 offset:4096
	ds_read_b128 v[116:119], v125 offset:6144
	v_add_u32_e32 v125, s66, v222
	ds_read_b32 v124, v125
	v_max_f32_e32 v121, v35, v35
	v_max_f32_e32 v122, v34, v34
	v_max_f32_e32 v121, v122, v121
	v_max3_f32 v121, v121, v36, v37
	v_max3_f32 v121, v121, v38, v39
	v_max3_f32 v121, v121, v40, v41
	v_max3_f32 v121, v121, v42, v43
	v_max3_f32 v121, v121, v44, v45
	v_max3_f32 v121, v121, v46, v47
	v_max3_f32 v121, v121, v48, v49
	s_waitcnt lgkmcnt(5)
	v_mfma_f32_32x32x16_bf16 v[200:215], v[66:69], v[50:53], 0
	v_mov_b32_e32 v122, v121
	s_nop 1
	v_permlane32_swap_b32_e32 v121, v122
	v_max_f32_e32 v122, v122, v122
	v_max_f32_e32 v121, v121, v121
	v_max_f32_e32 v121, v121, v122
	v_mfma_f32_32x32x16_bf16 v[200:215], v[70:73], v[54:57], v[200:215]
	v_add_f32_e32 v122, 0x42317218, v83
	v_cmp_gt_f32_e32 vcc, v121, v122
	s_cbranch_vccnz .Ldsa_rare_fbe
.Ldsa_back_fbe:
	v_mul_f32_e32 v120, 0xbe38aa3b, v83
	s_waitcnt lgkmcnt(0)
	v_lshrrev_b32_e32 v124, v148, v124
	v_fmamk_f32 v34, v34, 0x3e38aa3b, v120
	v_fmamk_f32 v35, v35, 0x3e38aa3b, v120
	v_fmamk_f32 v36, v36, 0x3e38aa3b, v120
	v_fmamk_f32 v37, v37, 0x3e38aa3b, v120
	v_fmamk_f32 v38, v38, 0x3e38aa3b, v120
	v_fmamk_f32 v39, v39, 0x3e38aa3b, v120
	v_fmamk_f32 v40, v40, 0x3e38aa3b, v120
	v_fmamk_f32 v41, v41, 0x3e38aa3b, v120
	v_mfma_f32_32x32x16_bf16 v[200:215], v[74:77], v[58:61], v[200:215]
	v_exp_f32_e32 v34, v34
	v_exp_f32_e32 v35, v35
	v_exp_f32_e32 v36, v36
	v_exp_f32_e32 v37, v37
	v_exp_f32_e32 v38, v38
	v_exp_f32_e32 v39, v39
	v_exp_f32_e32 v40, v40
	v_exp_f32_e32 v41, v41
	v_bfe_i32 v96, v124, 0, 1
	v_bfe_i32 v97, v124, 1, 1
	v_bfe_i32 v98, v124, 2, 1
	v_bfe_i32 v99, v124, 3, 1
	v_mfma_f32_32x32x16_bf16 v[200:215], v[78:81], v[62:65], v[200:215]
	v_bfe_i32 v100, v124, 4, 1
	v_bfe_i32 v101, v124, 5, 1
	v_bfe_i32 v102, v124, 6, 1
	v_bfe_i32 v103, v124, 7, 1
	v_and_b32_e32 v34, v96, v34
	v_and_b32_e32 v35, v97, v35
	v_and_b32_e32 v36, v98, v36
	v_and_b32_e32 v37, v99, v37
	v_and_b32_e32 v38, v100, v38
	v_and_b32_e32 v39, v101, v39
	v_and_b32_e32 v40, v102, v40
	v_and_b32_e32 v41, v103, v41
	v_add_f32_e32 v123, v34, v35
	v_add_f32_e32 v123, v123, v36
	v_add_f32_e32 v123, v123, v37
	v_add_f32_e32 v123, v123, v38
	v_add_f32_e32 v123, v123, v39
	v_add_f32_e32 v123, v123, v40
	v_add_f32_e32 v123, v123, v41
	v_cvt_pk_bf16_f32 v88, v34, v35
	v_cvt_pk_bf16_f32 v89, v36, v37
	v_cvt_pk_bf16_f32 v90, v38, v39
	v_cvt_pk_bf16_f32 v91, v40, v41
	v_fmamk_f32 v42, v42, 0x3e38aa3b, v120
	v_fmamk_f32 v43, v43, 0x3e38aa3b, v120
	v_mfma_f32_32x32x16_bf16 v[18:33], v[104:107], v[88:91], v[18:33]
	v_fmamk_f32 v44, v44, 0x3e38aa3b, v120
	v_fmamk_f32 v45, v45, 0x3e38aa3b, v120
	v_fmamk_f32 v46, v46, 0x3e38aa3b, v120
	v_fmamk_f32 v47, v47, 0x3e38aa3b, v120
	v_fmamk_f32 v48, v48, 0x3e38aa3b, v120
	v_fmamk_f32 v49, v49, 0x3e38aa3b, v120
	v_exp_f32_e32 v42, v42
	v_exp_f32_e32 v43, v43
	v_exp_f32_e32 v44, v44
	v_exp_f32_e32 v45, v45
	v_exp_f32_e32 v46, v46
	v_exp_f32_e32 v47, v47
	v_mfma_f32_32x32x16_bf16 v[2:17], v[108:111], v[88:91], v[2:17]
	v_exp_f32_e32 v48, v48
	v_exp_f32_e32 v49, v49
	v_bfe_i32 v96, v124, 16, 1
	v_bfe_i32 v97, v124, 17, 1
	v_bfe_i32 v98, v124, 18, 1
	v_bfe_i32 v99, v124, 19, 1
	v_bfe_i32 v100, v124, 20, 1
	v_bfe_i32 v101, v124, 21, 1
	v_bfe_i32 v102, v124, 22, 1
	v_bfe_i32 v103, v124, 23, 1
	v_and_b32_e32 v42, v96, v42
	v_and_b32_e32 v43, v97, v43
	v_and_b32_e32 v44, v98, v44
	v_and_b32_e32 v45, v99, v45
	v_and_b32_e32 v46, v100, v46
	v_and_b32_e32 v47, v101, v47
	v_and_b32_e32 v48, v102, v48
	v_and_b32_e32 v49, v103, v49
	v_add_f32_e32 v123, v123, v42
	v_add_f32_e32 v123, v123, v43
	v_add_f32_e32 v123, v123, v44
	v_add_f32_e32 v123, v123, v45
	v_add_f32_e32 v123, v123, v46
	v_add_f32_e32 v123, v123, v47
	v_add_f32_e32 v123, v123, v48
	v_add_f32_e32 v123, v123, v49
	v_cvt_pk_bf16_f32 v92, v42, v43
	v_cvt_pk_bf16_f32 v93, v44, v45
	v_cvt_pk_bf16_f32 v94, v46, v47
	v_cvt_pk_bf16_f32 v95, v48, v49
	v_add_f32_e32 v141, v141, v123
	s_nop 0
	v_mfma_f32_32x32x16_bf16 v[18:33], v[112:115], v[92:95], v[18:33]
	v_mfma_f32_32x32x16_bf16 v[2:17], v[116:119], v[92:95], v[2:17]
	s_branch .Ldsa_next_e
.Ldsa_last_e:
	v_add_u32_e32 v125, s40, v220
	ds_read_b128 v[104:107], v125 offset:4096
	ds_read_b128 v[108:111], v125 offset:6144
	v_add_u32_e32 v125, s40, v221
	ds_read_b128 v[112:115], v125 offset:4096
	ds_read_b128 v[116:119], v125 offset:6144
	v_add_u32_e32 v125, s66, v222
	ds_read_b32 v124, v125
	v_max_f32_e32 v121, v35, v35
	v_max_f32_e32 v122, v34, v34
	v_max_f32_e32 v121, v122, v121
	v_max3_f32 v121, v121, v36, v37
	v_max3_f32 v121, v121, v38, v39
	v_max3_f32 v121, v121, v40, v41
	v_max3_f32 v121, v121, v42, v43
	v_max3_f32 v121, v121, v44, v45
	v_max3_f32 v121, v121, v46, v47
	v_max3_f32 v121, v121, v48, v49
	v_mov_b32_e32 v122, v121
	s_nop 1
	v_permlane32_swap_b32_e32 v121, v122
	v_max_f32_e32 v122, v122, v122
	v_max_f32_e32 v121, v121, v121
	v_max_f32_e32 v121, v121, v122
	v_add_f32_e32 v122, 0x42317218, v83
	v_cmp_gt_f32_e32 vcc, v121, v122
	s_cbranch_vccnz .Ldsa_rare_lbe
.Ldsa_back_lbe:
	v_mul_f32_e32 v120, 0xbe38aa3b, v83
	s_waitcnt lgkmcnt(0)
	v_lshrrev_b32_e32 v124, v148, v124
	v_fmamk_f32 v34, v34, 0x3e38aa3b, v120
	v_fmamk_f32 v35, v35, 0x3e38aa3b, v120
	v_fmamk_f32 v36, v36, 0x3e38aa3b, v120
	v_fmamk_f32 v37, v37, 0x3e38aa3b, v120
	v_fmamk_f32 v38, v38, 0x3e38aa3b, v120
	v_fmamk_f32 v39, v39, 0x3e38aa3b, v120
	v_fmamk_f32 v40, v40, 0x3e38aa3b, v120
	v_fmamk_f32 v41, v41, 0x3e38aa3b, v120
	v_exp_f32_e32 v34, v34
	v_exp_f32_e32 v35, v35
	v_exp_f32_e32 v36, v36
	v_exp_f32_e32 v37, v37
	v_exp_f32_e32 v38, v38
	v_exp_f32_e32 v39, v39
	v_exp_f32_e32 v40, v40
	v_exp_f32_e32 v41, v41
	v_bfe_i32 v96, v124, 0, 1
	v_bfe_i32 v97, v124, 1, 1
	v_bfe_i32 v98, v124, 2, 1
	v_bfe_i32 v99, v124, 3, 1
	v_bfe_i32 v100, v124, 4, 1
	v_bfe_i32 v101, v124, 5, 1
	v_bfe_i32 v102, v124, 6, 1
	v_bfe_i32 v103, v124, 7, 1
	v_and_b32_e32 v34, v96, v34
	v_and_b32_e32 v35, v97, v35
	v_and_b32_e32 v36, v98, v36
	v_and_b32_e32 v37, v99, v37
	v_and_b32_e32 v38, v100, v38
	v_and_b32_e32 v39, v101, v39
	v_and_b32_e32 v40, v102, v40
	v_and_b32_e32 v41, v103, v41
	v_add_f32_e32 v123, v34, v35
	v_add_f32_e32 v123, v123, v36
	v_add_f32_e32 v123, v123, v37
	v_add_f32_e32 v123, v123, v38
	v_add_f32_e32 v123, v123, v39
	v_add_f32_e32 v123, v123, v40
	v_add_f32_e32 v123, v123, v41
	v_cvt_pk_bf16_f32 v88, v34, v35
	v_cvt_pk_bf16_f32 v89, v36, v37
	v_cvt_pk_bf16_f32 v90, v38, v39
	v_cvt_pk_bf16_f32 v91, v40, v41
	v_fmamk_f32 v42, v42, 0x3e38aa3b, v120
	v_fmamk_f32 v43, v43, 0x3e38aa3b, v120
	v_mfma_f32_32x32x16_bf16 v[18:33], v[104:107], v[88:91], v[18:33]
	v_fmamk_f32 v44, v44, 0x3e38aa3b, v120
	v_fmamk_f32 v45, v45, 0x3e38aa3b, v120
	v_fmamk_f32 v46, v46, 0x3e38aa3b, v120
	v_fmamk_f32 v47, v47, 0x3e38aa3b, v120
	v_fmamk_f32 v48, v48, 0x3e38aa3b, v120
	v_fmamk_f32 v49, v49, 0x3e38aa3b, v120
	v_exp_f32_e32 v42, v42
	v_exp_f32_e32 v43, v43
	v_exp_f32_e32 v44, v44
	v_exp_f32_e32 v45, v45
	v_exp_f32_e32 v46, v46
	v_exp_f32_e32 v47, v47
	v_mfma_f32_32x32x16_bf16 v[2:17], v[108:111], v[88:91], v[2:17]
	v_exp_f32_e32 v48, v48
	v_exp_f32_e32 v49, v49
	v_bfe_i32 v96, v124, 16, 1
	v_bfe_i32 v97, v124, 17, 1
	v_bfe_i32 v98, v124, 18, 1
	v_bfe_i32 v99, v124, 19, 1
	v_bfe_i32 v100, v124, 20, 1
	v_bfe_i32 v101, v124, 21, 1
	v_bfe_i32 v102, v124, 22, 1
	v_bfe_i32 v103, v124, 23, 1
	v_and_b32_e32 v42, v96, v42
	v_and_b32_e32 v43, v97, v43
	v_and_b32_e32 v44, v98, v44
	v_and_b32_e32 v45, v99, v45
	v_and_b32_e32 v46, v100, v46
	v_and_b32_e32 v47, v101, v47
	v_and_b32_e32 v48, v102, v48
	v_and_b32_e32 v49, v103, v49
	v_add_f32_e32 v123, v123, v42
	v_add_f32_e32 v123, v123, v43
	v_add_f32_e32 v123, v123, v44
	v_add_f32_e32 v123, v123, v45
	v_add_f32_e32 v123, v123, v46
	v_add_f32_e32 v123, v123, v47
	v_add_f32_e32 v123, v123, v48
	v_add_f32_e32 v123, v123, v49
	v_cvt_pk_bf16_f32 v92, v42, v43
	v_cvt_pk_bf16_f32 v93, v44, v45
	v_cvt_pk_bf16_f32 v94, v46, v47
	v_cvt_pk_bf16_f32 v95, v48, v49
	v_add_f32_e32 v141, v141, v123
	s_nop 0
	v_mfma_f32_32x32x16_bf16 v[18:33], v[112:115], v[92:95], v[18:33]
	v_mfma_f32_32x32x16_bf16 v[2:17], v[116:119], v[92:95], v[2:17]
.Ldsa_next_e:
	s_add_i32 s65, s65, 1
	s_add_i32 s53, s53, -1
	s_cmp_lg_u32 s53, -1
	v_lshl_add_u64 v[86:87], v[86:87], 0, s[20:21]
	s_cbranch_scc0 .LBB0_788

.Ldsa_bar_o:
	s_barrier
	s_cmp_gt_i32 s65, s67
	s_cbranch_scc1 .Ldsa_next_o
	s_and_b32 s40, s65, 15
	s_lshl_b32 s40, s40, 13
	s_lshl_b32 s66, s65, 10
	s_and_b32 s66, s66, 0x3000
	s_and_b32 s41, s65, 3
	s_lshl_b32 s41, s41, 2
	s_add_i32 s66, s66, s41
	s_add_i32 s66, s66, 0x20020
	s_cmp_eq_u32 s65, s67
	s_cbranch_scc1 .Ldsa_last_o
	s_add_i32 s41, s65, 1
	s_and_b32 s41, s41, 15
	s_lshl_b32 s41, s41, 13
	v_add_u32_e32 v125, s41, v216
	ds_read_b128 v[66:69], v125
	v_add_u32_e32 v125, s41, v217
	ds_read_b128 v[70:73], v125
	v_add_u32_e32 v125, s41, v218
	ds_read_b128 v[74:77], v125
	v_add_u32_e32 v125, s41, v219
	ds_read_b128 v[78:81], v125
	v_add_u32_e32 v125, s40, v220
	ds_read_b128 v[104:107], v125 offset:4096
	ds_read_b128 v[108:111], v125 offset:6144
	v_add_u32_e32 v125, s40, v221
	ds_read_b128 v[112:115], v125 offset:4096
	ds_read_b128 v[116:119], v125 offset:6144
	v_add_u32_e32 v125, s66, v222
	ds_read_b32 v124, v125
	v_max_f32_e32 v121, v201, v201
	v_max_f32_e32 v122, v200, v200
	v_max_f32_e32 v121, v122, v121
	v_max3_f32 v121, v121, v202, v203
	v_max3_f32 v121, v121, v204, v205
	v_max3_f32 v121, v121, v206, v207
	v_max3_f32 v121, v121, v208, v209
	v_max3_f32 v121, v121, v210, v211
	v_max3_f32 v121, v121, v212, v213
	v_max3_f32 v121, v121, v214, v215
	s_waitcnt lgkmcnt(5)
	v_mfma_f32_32x32x16_bf16 v[34:49], v[66:69], v[50:53], 0
	v_mov_b32_e32 v122, v121
	s_nop 1
	v_permlane32_swap_b32_e32 v121, v122
	v_max_f32_e32 v122, v122, v122
	v_max_f32_e32 v121, v121, v121
	v_max_f32_e32 v121, v121, v122
	v_mfma_f32_32x32x16_bf16 v[34:49], v[70:73], v[54:57], v[34:49]
	v_add_f32_e32 v122, 0x42317218, v83
	v_cmp_gt_f32_e32 vcc, v121, v122
	s_cbranch_vccnz .Ldsa_rare_fbo
.Ldsa_back_fbo:
	v_mul_f32_e32 v120, 0xbe38aa3b, v83
	s_waitcnt lgkmcnt(0)
	v_lshrrev_b32_e32 v124, v148, v124
	v_fmamk_f32 v200, v200, 0x3e38aa3b, v120
	v_fmamk_f32 v201, v201, 0x3e38aa3b, v120
	v_fmamk_f32 v202, v202, 0x3e38aa3b, v120
	v_fmamk_f32 v203, v203, 0x3e38aa3b, v120
	v_fmamk_f32 v204, v204, 0x3e38aa3b, v120
	v_fmamk_f32 v205, v205, 0x3e38aa3b, v120
	v_fmamk_f32 v206, v206, 0x3e38aa3b, v120
	v_fmamk_f32 v207, v207, 0x3e38aa3b, v120
	v_mfma_f32_32x32x16_bf16 v[34:49], v[74:77], v[58:61], v[34:49]
	v_exp_f32_e32 v200, v200
	v_exp_f32_e32 v201, v201
	v_exp_f32_e32 v202, v202
	v_exp_f32_e32 v203, v203
	v_exp_f32_e32 v204, v204
	v_exp_f32_e32 v205, v205
	v_exp_f32_e32 v206, v206
	v_exp_f32_e32 v207, v207
	v_bfe_i32 v96, v124, 0, 1
	v_bfe_i32 v97, v124, 1, 1
	v_bfe_i32 v98, v124, 2, 1
	v_bfe_i32 v99, v124, 3, 1
	v_mfma_f32_32x32x16_bf16 v[34:49], v[78:81], v[62:65], v[34:49]
	v_bfe_i32 v100, v124, 4, 1
	v_bfe_i32 v101, v124, 5, 1
	v_bfe_i32 v102, v124, 6, 1
	v_bfe_i32 v103, v124, 7, 1
	v_and_b32_e32 v200, v96, v200
	v_and_b32_e32 v201, v97, v201
	v_and_b32_e32 v202, v98, v202
	v_and_b32_e32 v203, v99, v203
	v_and_b32_e32 v204, v100, v204
	v_and_b32_e32 v205, v101, v205
	v_and_b32_e32 v206, v102, v206
	v_and_b32_e32 v207, v103, v207
	v_add_f32_e32 v123, v200, v201
	v_add_f32_e32 v123, v123, v202
	v_add_f32_e32 v123, v123, v203
	v_add_f32_e32 v123, v123, v204
	v_add_f32_e32 v123, v123, v205
	v_add_f32_e32 v123, v123, v206
	v_add_f32_e32 v123, v123, v207
	v_cvt_pk_bf16_f32 v88, v200, v201
	v_cvt_pk_bf16_f32 v89, v202, v203
	v_cvt_pk_bf16_f32 v90, v204, v205
	v_cvt_pk_bf16_f32 v91, v206, v207
	v_fmamk_f32 v208, v208, 0x3e38aa3b, v120
	v_fmamk_f32 v209, v209, 0x3e38aa3b, v120
	v_mfma_f32_32x32x16_bf16 v[18:33], v[104:107], v[88:91], v[18:33]
	v_fmamk_f32 v210, v210, 0x3e38aa3b, v120
	v_fmamk_f32 v211, v211, 0x3e38aa3b, v120
	v_fmamk_f32 v212, v212, 0x3e38aa3b, v120
	v_fmamk_f32 v213, v213, 0x3e38aa3b, v120
	v_fmamk_f32 v214, v214, 0x3e38aa3b, v120
	v_fmamk_f32 v215, v215, 0x3e38aa3b, v120
	v_exp_f32_e32 v208, v208
	v_exp_f32_e32 v209, v209
	v_exp_f32_e32 v210, v210
	v_exp_f32_e32 v211, v211
	v_exp_f32_e32 v212, v212
	v_exp_f32_e32 v213, v213
	v_mfma_f32_32x32x16_bf16 v[2:17], v[108:111], v[88:91], v[2:17]
	v_exp_f32_e32 v214, v214
	v_exp_f32_e32 v215, v215
	v_bfe_i32 v96, v124, 16, 1
	v_bfe_i32 v97, v124, 17, 1
	v_bfe_i32 v98, v124, 18, 1
	v_bfe_i32 v99, v124, 19, 1
	v_bfe_i32 v100, v124, 20, 1
	v_bfe_i32 v101, v124, 21, 1
	v_bfe_i32 v102, v124, 22, 1
	v_bfe_i32 v103, v124, 23, 1
	v_and_b32_e32 v208, v96, v208
	v_and_b32_e32 v209, v97, v209
	v_and_b32_e32 v210, v98, v210
	v_and_b32_e32 v211, v99, v211
	v_and_b32_e32 v212, v100, v212
	v_and_b32_e32 v213, v101, v213
	v_and_b32_e32 v214, v102, v214
	v_and_b32_e32 v215, v103, v215
	v_add_f32_e32 v123, v123, v208
	v_add_f32_e32 v123, v123, v209
	v_add_f32_e32 v123, v123, v210
	v_add_f32_e32 v123, v123, v211
	v_add_f32_e32 v123, v123, v212
	v_add_f32_e32 v123, v123, v213
	v_add_f32_e32 v123, v123, v214
	v_add_f32_e32 v123, v123, v215
	v_cvt_pk_bf16_f32 v92, v208, v209
	v_cvt_pk_bf16_f32 v93, v210, v211
	v_cvt_pk_bf16_f32 v94, v212, v213
	v_cvt_pk_bf16_f32 v95, v214, v215
	v_add_f32_e32 v141, v141, v123
	s_nop 0
	v_mfma_f32_32x32x16_bf16 v[18:33], v[112:115], v[92:95], v[18:33]
	v_mfma_f32_32x32x16_bf16 v[2:17], v[116:119], v[92:95], v[2:17]
	s_branch .Ldsa_next_o
.Ldsa_last_o:
	v_add_u32_e32 v125, s40, v220
	ds_read_b128 v[104:107], v125 offset:4096
	ds_read_b128 v[108:111], v125 offset:6144
	v_add_u32_e32 v125, s40, v221
	ds_read_b128 v[112:115], v125 offset:4096
	ds_read_b128 v[116:119], v125 offset:6144
	v_add_u32_e32 v125, s66, v222
	ds_read_b32 v124, v125
	v_max_f32_e32 v121, v201, v201
	v_max_f32_e32 v122, v200, v200
	v_max_f32_e32 v121, v122, v121
	v_max3_f32 v121, v121, v202, v203
	v_max3_f32 v121, v121, v204, v205
	v_max3_f32 v121, v121, v206, v207
	v_max3_f32 v121, v121, v208, v209
	v_max3_f32 v121, v121, v210, v211
	v_max3_f32 v121, v121, v212, v213
	v_max3_f32 v121, v121, v214, v215
	v_mov_b32_e32 v122, v121
	s_nop 1
	v_permlane32_swap_b32_e32 v121, v122
	v_max_f32_e32 v122, v122, v122
	v_max_f32_e32 v121, v121, v121
	v_max_f32_e32 v121, v121, v122
	v_add_f32_e32 v122, 0x42317218, v83
	v_cmp_gt_f32_e32 vcc, v121, v122
	s_cbranch_vccnz .Ldsa_rare_lbo
.Ldsa_back_lbo:
	v_mul_f32_e32 v120, 0xbe38aa3b, v83
	s_waitcnt lgkmcnt(0)
	v_lshrrev_b32_e32 v124, v148, v124
	v_fmamk_f32 v200, v200, 0x3e38aa3b, v120
	v_fmamk_f32 v201, v201, 0x3e38aa3b, v120
	v_fmamk_f32 v202, v202, 0x3e38aa3b, v120
	v_fmamk_f32 v203, v203, 0x3e38aa3b, v120
	v_fmamk_f32 v204, v204, 0x3e38aa3b, v120
	v_fmamk_f32 v205, v205, 0x3e38aa3b, v120
	v_fmamk_f32 v206, v206, 0x3e38aa3b, v120
	v_fmamk_f32 v207, v207, 0x3e38aa3b, v120
	v_exp_f32_e32 v200, v200
	v_exp_f32_e32 v201, v201
	v_exp_f32_e32 v202, v202
	v_exp_f32_e32 v203, v203
	v_exp_f32_e32 v204, v204
	v_exp_f32_e32 v205, v205
	v_exp_f32_e32 v206, v206
	v_exp_f32_e32 v207, v207
	v_bfe_i32 v96, v124, 0, 1
	v_bfe_i32 v97, v124, 1, 1
	v_bfe_i32 v98, v124, 2, 1
	v_bfe_i32 v99, v124, 3, 1
	v_bfe_i32 v100, v124, 4, 1
	v_bfe_i32 v101, v124, 5, 1
	v_bfe_i32 v102, v124, 6, 1
	v_bfe_i32 v103, v124, 7, 1
	v_and_b32_e32 v200, v96, v200
	v_and_b32_e32 v201, v97, v201
	v_and_b32_e32 v202, v98, v202
	v_and_b32_e32 v203, v99, v203
	v_and_b32_e32 v204, v100, v204
	v_and_b32_e32 v205, v101, v205
	v_and_b32_e32 v206, v102, v206
	v_and_b32_e32 v207, v103, v207
	v_add_f32_e32 v123, v200, v201
	v_add_f32_e32 v123, v123, v202
	v_add_f32_e32 v123, v123, v203
	v_add_f32_e32 v123, v123, v204
	v_add_f32_e32 v123, v123, v205
	v_add_f32_e32 v123, v123, v206
	v_add_f32_e32 v123, v123, v207
	v_cvt_pk_bf16_f32 v88, v200, v201
	v_cvt_pk_bf16_f32 v89, v202, v203
	v_cvt_pk_bf16_f32 v90, v204, v205
	v_cvt_pk_bf16_f32 v91, v206, v207
	v_fmamk_f32 v208, v208, 0x3e38aa3b, v120
	v_fmamk_f32 v209, v209, 0x3e38aa3b, v120
	v_mfma_f32_32x32x16_bf16 v[18:33], v[104:107], v[88:91], v[18:33]
	v_fmamk_f32 v210, v210, 0x3e38aa3b, v120
	v_fmamk_f32 v211, v211, 0x3e38aa3b, v120
	v_fmamk_f32 v212, v212, 0x3e38aa3b, v120
	v_fmamk_f32 v213, v213, 0x3e38aa3b, v120
	v_fmamk_f32 v214, v214, 0x3e38aa3b, v120
	v_fmamk_f32 v215, v215, 0x3e38aa3b, v120
	v_exp_f32_e32 v208, v208
	v_exp_f32_e32 v209, v209
	v_exp_f32_e32 v210, v210
	v_exp_f32_e32 v211, v211
	v_exp_f32_e32 v212, v212
	v_exp_f32_e32 v213, v213
	v_mfma_f32_32x32x16_bf16 v[2:17], v[108:111], v[88:91], v[2:17]
	v_exp_f32_e32 v214, v214
	v_exp_f32_e32 v215, v215
	v_bfe_i32 v96, v124, 16, 1
	v_bfe_i32 v97, v124, 17, 1
	v_bfe_i32 v98, v124, 18, 1
	v_bfe_i32 v99, v124, 19, 1
	v_bfe_i32 v100, v124, 20, 1
	v_bfe_i32 v101, v124, 21, 1
	v_bfe_i32 v102, v124, 22, 1
	v_bfe_i32 v103, v124, 23, 1
	v_and_b32_e32 v208, v96, v208
	v_and_b32_e32 v209, v97, v209
	v_and_b32_e32 v210, v98, v210
	v_and_b32_e32 v211, v99, v211
	v_and_b32_e32 v212, v100, v212
	v_and_b32_e32 v213, v101, v213
	v_and_b32_e32 v214, v102, v214
	v_and_b32_e32 v215, v103, v215
	v_add_f32_e32 v123, v123, v208
	v_add_f32_e32 v123, v123, v209
	v_add_f32_e32 v123, v123, v210
	v_add_f32_e32 v123, v123, v211
	v_add_f32_e32 v123, v123, v212
	v_add_f32_e32 v123, v123, v213
	v_add_f32_e32 v123, v123, v214
	v_add_f32_e32 v123, v123, v215
	v_cvt_pk_bf16_f32 v92, v208, v209
	v_cvt_pk_bf16_f32 v93, v210, v211
	v_cvt_pk_bf16_f32 v94, v212, v213
	v_cvt_pk_bf16_f32 v95, v214, v215
	v_add_f32_e32 v141, v141, v123
	s_nop 0
	v_mfma_f32_32x32x16_bf16 v[18:33], v[112:115], v[92:95], v[18:33]
	v_mfma_f32_32x32x16_bf16 v[2:17], v[116:119], v[92:95], v[2:17]
.Ldsa_next_o:
	s_add_i32 s65, s65, 1
	s_add_i32 s53, s53, -1
	s_cmp_lg_u32 s53, -1
	v_lshl_add_u64 v[86:87], v[86:87], 0, s[20:21]
	s_cbranch_scc0 .LBB0_788
	s_branch .Ldsa_top_e
.Ldsa_rare_fbe:
	s_nop 15
	s_nop 15
	v_cndmask_b32_e32 v122, v83, v121, vcc
	v_sub_f32_e32 v126, v83, v122
	v_mul_f32_e32 v126, 0x3e38aa3b, v126
	v_exp_f32_e32 v126, v126
	v_mov_b32_e32 v83, v122
	v_mul_f32_e32 v141, v141, v126
	v_pk_mul_f32 v[32:33], v[32:33], v[126:127] op_sel_hi:[1,0]
	v_pk_mul_f32 v[30:31], v[30:31], v[126:127] op_sel_hi:[1,0]
	v_pk_mul_f32 v[28:29], v[28:29], v[126:127] op_sel_hi:[1,0]
	v_pk_mul_f32 v[26:27], v[26:27], v[126:127] op_sel_hi:[1,0]
	v_pk_mul_f32 v[24:25], v[24:25], v[126:127] op_sel_hi:[1,0]
	v_pk_mul_f32 v[22:23], v[22:23], v[126:127] op_sel_hi:[1,0]
	v_pk_mul_f32 v[20:21], v[20:21], v[126:127] op_sel_hi:[1,0]
	v_pk_mul_f32 v[18:19], v[18:19], v[126:127] op_sel_hi:[1,0]
	v_pk_mul_f32 v[16:17], v[16:17], v[126:127] op_sel_hi:[1,0]
	v_pk_mul_f32 v[14:15], v[14:15], v[126:127] op_sel_hi:[1,0]
	v_pk_mul_f32 v[12:13], v[12:13], v[126:127] op_sel_hi:[1,0]
	v_pk_mul_f32 v[10:11], v[10:11], v[126:127] op_sel_hi:[1,0]
	v_pk_mul_f32 v[8:9], v[8:9], v[126:127] op_sel_hi:[1,0]
	v_pk_mul_f32 v[6:7], v[6:7], v[126:127] op_sel_hi:[1,0]
	v_pk_mul_f32 v[4:5], v[4:5], v[126:127] op_sel_hi:[1,0]
	v_pk_mul_f32 v[2:3], v[2:3], v[126:127] op_sel_hi:[1,0]
	s_branch .Ldsa_back_fbe

	.amdhsa_kernel _Z10fwd_kernel6Params
		.amdhsa_group_segment_fixed_size 16448
		.amdhsa_private_segment_fixed_size 0
		.amdhsa_kernarg_size 456
		.amdhsa_user_sgpr_count 2
		.amdhsa_user_sgpr_dispatch_ptr 0
		.amdhsa_user_sgpr_queue_ptr 0
		.amdhsa_user_sgpr_kernarg_segment_ptr 1
		.amdhsa_user_sgpr_dispatch_id 0
		.amdhsa_user_sgpr_kernarg_preload_length 0
		.amdhsa_user_sgpr_kernarg_preload_offset 0
		.amdhsa_user_sgpr_private_segment_size 0
		.amdhsa_uses_dynamic_stack 0
		.amdhsa_enable_private_segment 0
		.amdhsa_system_sgpr_workgroup_id_x 1
		.amdhsa_system_sgpr_workgroup_id_y 0
		.amdhsa_system_sgpr_workgroup_id_z 0
		.amdhsa_system_sgpr_workgroup_info 0
		.amdhsa_system_vgpr_workitem_id 2
		.amdhsa_next_free_vgpr 256
		.amdhsa_next_free_sgpr 102
		.amdhsa_accum_offset 256
		.amdhsa_reserve_vcc 1
		.amdhsa_float_round_mode_32 0
		.amdhsa_float_round_mode_16_64 0
		.amdhsa_float_denorm_mode_32 3
		.amdhsa_float_denorm_mode_16_64 3
		.amdhsa_dx10_clamp 1
		.amdhsa_ieee_mode 1
		.amdhsa_fp16_overflow 0
		.amdhsa_tg_split 0
		.amdhsa_exception_fp_ieee_invalid_op 0
		.amdhsa_exception_fp_denorm_src 0
		.amdhsa_exception_fp_ieee_div_zero 0
		.amdhsa_exception_fp_ieee_overflow 0
		.amdhsa_exception_fp_ieee_underflow 0
		.amdhsa_exception_fp_ieee_inexact 0
		.amdhsa_exception_int_div_zero 0
	.end_amdhsa_kernel

amdhsa.kernels:
  - .agpr_count:     0
    .args:
      - .offset:         0
        .size:           200
        .value_kind:     by_value
      - .offset:         200
        .size:           4
        .value_kind:     hidden_block_count_x
      - .offset:         204
        .size:           4
        .value_kind:     hidden_block_count_y
      - .offset:         208
        .size:           4
        .value_kind:     hidden_block_count_z
      - .offset:         212
        .size:           2
        .value_kind:     hidden_group_size_x
      - .offset:         214
        .size:           2
        .value_kind:     hidden_group_size_y
      - .offset:         216
        .size:           2
        .value_kind:     hidden_group_size_z
      - .offset:         218
        .size:           2
        .value_kind:     hidden_remainder_x
      - .offset:         220
        .size:           2
        .value_kind:     hidden_remainder_y
      - .offset:         222
        .size:           2
        .value_kind:     hidden_remainder_z
      - .offset:         240
        .size:           8
        .value_kind:     hidden_global_offset_x
      - .offset:         248
        .size:           8
        .value_kind:     hidden_global_offset_y
      - .offset:         256
        .size:           8
        .value_kind:     hidden_global_offset_z
      - .offset:         264
        .size:           2
        .value_kind:     hidden_grid_dims
      - .offset:         288
        .size:           8
        .value_kind:     hidden_multigrid_sync_arg
      - .offset:         320
        .size:           4
        .value_kind:     hidden_dynamic_lds_size
    .group_segment_fixed_size: 16448
    .kernarg_segment_align: 8
    .kernarg_segment_size: 456
    .language:       OpenCL C
    .language_version:
      - 2
      - 0
    .max_flat_workgroup_size: 512
    .name:           _Z10fwd_kernel6Params
    .private_segment_fixed_size: 0
    .sgpr_count:     108
    .sgpr_spill_count: 118
    .symbol:         _Z10fwd_kernel6Params.kd
    .uniform_work_group_size: 1
    .uses_dynamic_stack: false
    .vgpr_count:     256
    .vgpr_spill_count: 0
    .wavefront_size: 64
